# gate GEMM epilogue: second column group's loads issued mid-way through the first group; unit-end barrier moved below the first group's loads
# speedup vs baseline: 1.0057x; 1.0057x over previous
; #define PG8_STAGE(bufoff, gbase, voff) do { _Pragma("unroll") for (int _i = 0; _i < 2; ++_i) \
;         __builtin_amdgcn_global_load_lds((const unsigned*)((const char*)(gbase) + (voff)[_i]), (LAS unsigned*)(lds + (bufoff) + ldsw + _i * 8192), 16, 0, 0); } while (0)
; #define PG8_LDA(dst, b, h) do { _Pragma("unroll") for (int m = 0; m < 4; ++m) _Pragma("unroll") for (int k = 0; k < 2; ++k) dst[m][k] = *(const LAS bf16x8*)(lds + PG8_SA(b, h) + aoff + m * 2048 + k * 1024); } while (0)
; #define PG8_LDB(dst, b, h) do { _Pragma("unroll") for (int n = 0; n < 2; ++n) _Pragma("unroll") for (int k = 0; k < 2; ++k) dst[n][k] = *(const LAS bf16x8*)(lds + PG8_SB(b, h) + boff + n * 2048 + k * 1024); } while (0)
; #define PG8_WAIT_L(n) asm volatile("s_waitcnt lgkmcnt(" #n ")" ::: "memory")
; #define PG8_BAR __builtin_amdgcn_s_barrier()
; #define PG8_SCHED __builtin_amdgcn_sched_barrier(0)
; template <class Epi>
; __device__ __forceinline__ void gemm_phase(LAS unsigned char* lds, const bf16_t* A, int lda, const bf16_t* Bt, int ldb, int M, int N, int K, int asel, const Epi& E, const int fixed_round = -1) {
;     ...
;         const bool has_next = (fixed_round < 0) && S.next(ui + 1, nxt);
;         const char* nA = has_next ? PG8_ABASE(nxt) : cA; const char* nB = has_next ? (const char*)Bt + (size_t)nxt.pn * tstepB : cB;
;         for (int t = 0; t < nt; t += 2) {
;             const bool last = (t == nt - 2);
;             const char* a1 = cA + (size_t)(t + 1) * kstep;
;             const char* a2 = last ? nA : cA + (size_t)(t + 2) * kstep; const char* b2 = last ? nB : cB + (size_t)(t + 2) * kstep;
;             const char* a3 = a2 + kstep; const char* b3 = b2 + kstep;
;             PG8_LDB(B0, 0, 0); PG8_SCHED; PG8_LDA(At, 0, 0); PG8_STAGE(PG8_SA(1, 1), a1 + hstepA, voffA);
;             PG8_WAIT_L(8); PG8_BAR; PG8_WAIT_L(0); PG8_MMA(0, 0, At, B0); PG8_BAR; PG8_SCHED;
;             PG8_LDB(B1, 0, 1); PG8_STAGE(PG8_SB(0, 0), b2, voffB);
;             PG8_BAR; PG8_WAIT_L(0); PG8_MMA(0, 1, At, B1); PG8_BAR;
;             PG8_LDA(At, 0, 1); PG8_STAGE(PG8_SA(0, 0), a2, voffA);
;             PG8_BAR; PG8_WAIT_L(0); PG8_MMA(1, 0, At, B0); PG8_BAR; PG8_SCHED;
.LBB0_938:
	s_ashr_i32 s57, s56, 31
	s_lshl_b64 s[2:3], s[56:57], 20
	s_add_u32 s28, s6, s2
	s_addc_u32 s29, s7, s3
	s_ashr_i32 s2, s54, 1
	s_ashr_i32 s3, s2, 31
	s_lshl_b64 s[2:3], s[2:3], 9
	s_add_u32 s58, s28, s2
	s_addc_u32 s59, s29, s3
	ds_read_b128 v[0:3], v215
	ds_read_b128 v[4:7], v215 offset:1024
	ds_read_b128 v[8:11], v215 offset:2048
	ds_read_b128 v[12:15], v215 offset:3072
	s_and_b64 s[2:3], exec, s[0:1]
	s_cselect_b32 s3, s59, s65
	s_cselect_b32 s2, s58, s64
	s_ashr_i32 s55, s54, 31
	s_lshl_b64 s[28:29], s[54:55], 17
	s_add_u32 s60, s68, s28
	s_addc_u32 s61, s69, s29
	s_and_b64 s[0:1], exec, s[0:1]
	s_cselect_b32 s1, s61, s67
	s_cselect_b32 s0, s60, s66
	s_add_u32 s28, s64, 0x80080
	s_addc_u32 s29, s65, 0
	s_add_i32 vcc_hi, s63, 0xc000
	v_lshl_add_u64 v[48:49], s[28:29], 0, v[140:141]
	s_mov_b32 m0, vcc_hi
	s_add_i32 s55, s63, 0xe000
	ds_read_b128 v[16:19], v216
	ds_read_b128 v[20:23], v216 offset:1024
	ds_read_b128 v[24:27], v216 offset:2048
	ds_read_b128 v[28:31], v216 offset:3072
	ds_read_b128 v[32:35], v216 offset:4096
	ds_read_b128 v[36:39], v216 offset:5120
	ds_read_b128 v[40:43], v216 offset:6144
	ds_read_b128 v[44:47], v216 offset:7168
	global_load_lds_dwordx4 v[48:49], off
	v_lshl_add_u64 v[48:49], s[28:29], 0, v[144:145]
	s_mov_b32 m0, s55
	s_nop 0
	global_load_lds_dwordx4 v[48:49], off
	s_waitcnt lgkmcnt(8)
	s_barrier
	s_waitcnt lgkmcnt(0)
	s_setprio 1
	s_waitcnt lgkmcnt(0)
	v_mfma_f32_16x16x32_bf16 v[48:51], v[0:3], v[16:19], 0
	v_mfma_f32_16x16x32_bf16 v[52:55], v[8:11], v[16:19], 0
	v_mfma_f32_16x16x32_bf16 v[56:59], v[0:3], v[24:27], 0
	v_mfma_f32_16x16x32_bf16 v[60:63], v[8:11], v[24:27], 0
	v_mfma_f32_16x16x32_bf16 v[64:67], v[0:3], v[32:35], 0
	v_mfma_f32_16x16x32_bf16 v[68:71], v[8:11], v[32:35], 0
	v_mfma_f32_16x16x32_bf16 v[72:75], v[0:3], v[40:43], 0
	v_mfma_f32_16x16x32_bf16 v[76:79], v[8:11], v[40:43], 0
	v_mfma_f32_16x16x32_bf16 v[48:51], v[4:7], v[20:23], v[48:51]
	v_mfma_f32_16x16x32_bf16 v[52:55], v[12:15], v[20:23], v[52:55]
	v_mfma_f32_16x16x32_bf16 v[56:59], v[4:7], v[28:31], v[56:59]
	v_mfma_f32_16x16x32_bf16 v[60:63], v[12:15], v[28:31], v[60:63]
	v_mfma_f32_16x16x32_bf16 v[64:67], v[4:7], v[36:39], v[64:67]
	v_mfma_f32_16x16x32_bf16 v[68:71], v[12:15], v[36:39], v[68:71]
	v_mfma_f32_16x16x32_bf16 v[72:75], v[4:7], v[44:47], v[72:75]
	v_mfma_f32_16x16x32_bf16 v[76:79], v[12:15], v[44:47], v[76:79]
	s_setprio 0
	s_barrier
	v_lshl_add_u64 v[198:199], s[66:67], 0, v[142:143]
	s_add_i32 s96, s81, s70
	v_lshl_add_u64 v[96:97], v[198:199], 0, s[46:47]
	s_mov_b32 m0, s96
	v_lshl_add_u64 v[210:211], s[66:67], 0, v[146:147]
	s_add_i32 s57, s96, 0x2000
	ds_read_b128 v[80:83], v217
	ds_read_b128 v[84:87], v217 offset:1024
	ds_read_b128 v[88:91], v217 offset:2048
	ds_read_b128 v[92:95], v217 offset:3072
	global_load_lds_dwordx4 v[96:97], off
	v_lshl_add_u64 v[96:97], v[210:211], 0, s[46:47]
	s_mov_b32 m0, s57
	s_nop 0
	global_load_lds_dwordx4 v[96:97], off
	s_barrier
	s_waitcnt lgkmcnt(0)
	s_setprio 1
	s_waitcnt lgkmcnt(0)
	v_mfma_f32_16x16x32_bf16 v[96:99], v[80:83], v[16:19], 0
	v_mfma_f32_16x16x32_bf16 v[16:19], v[88:91], v[16:19], 0
	v_mfma_f32_16x16x32_bf16 v[96:99], v[84:87], v[20:23], v[96:99]
	v_mfma_f32_16x16x32_bf16 v[16:19], v[92:95], v[20:23], v[16:19]
	v_mfma_f32_16x16x32_bf16 v[20:23], v[80:83], v[24:27], 0
	v_mfma_f32_16x16x32_bf16 v[24:27], v[88:91], v[24:27], 0
	v_mfma_f32_16x16x32_bf16 v[20:23], v[84:87], v[28:31], v[20:23]
	v_mfma_f32_16x16x32_bf16 v[24:27], v[92:95], v[28:31], v[24:27]
	v_mfma_f32_16x16x32_bf16 v[28:31], v[80:83], v[32:35], 0
	v_mfma_f32_16x16x32_bf16 v[32:35], v[88:91], v[32:35], 0
	v_mfma_f32_16x16x32_bf16 v[28:31], v[84:87], v[36:39], v[28:31]
	v_mfma_f32_16x16x32_bf16 v[32:35], v[92:95], v[36:39], v[32:35]
	v_mfma_f32_16x16x32_bf16 v[36:39], v[80:83], v[40:43], 0
	v_mfma_f32_16x16x32_bf16 v[40:43], v[88:91], v[40:43], 0
	v_mfma_f32_16x16x32_bf16 v[36:39], v[84:87], v[44:47], v[36:39]
	v_mfma_f32_16x16x32_bf16 v[40:43], v[92:95], v[44:47], v[40:43]
	s_setprio 0
	v_lshl_add_u64 v[224:225], s[64:65], 0, v[140:141]
	s_mov_b32 m0, s63
	v_lshl_add_u64 v[128:129], v[224:225], 0, s[46:47]
	v_lshl_add_u64 v[226:227], s[64:65], 0, v[144:145]
	s_barrier
	ds_read_b128 v[44:47], v216 offset:16384
	ds_read_b128 v[100:103], v216 offset:17408
	ds_read_b128 v[104:107], v216 offset:18432
	ds_read_b128 v[108:111], v216 offset:19456
	ds_read_b128 v[112:115], v216 offset:20480
	ds_read_b128 v[116:119], v216 offset:21504
	ds_read_b128 v[120:123], v216 offset:22528
	ds_read_b128 v[124:127], v216 offset:23552
	global_load_lds_dwordx4 v[128:129], off
	v_lshl_add_u64 v[128:129], v[226:227], 0, s[46:47]
	s_mov_b32 m0, s71
	s_nop 0
	global_load_lds_dwordx4 v[128:129], off
	s_barrier
	s_waitcnt lgkmcnt(0)
	s_setprio 1
	s_waitcnt lgkmcnt(0)
	v_mfma_f32_16x16x32_bf16 v[128:131], v[0:3], v[44:47], 0
	v_mfma_f32_16x16x32_bf16 v[136:139], v[0:3], v[104:107], 0
	v_mfma_f32_16x16x32_bf16 v[158:161], v[0:3], v[112:115], 0
	v_mfma_f32_16x16x32_bf16 v[0:3], v[0:3], v[120:123], 0
	v_mfma_f32_16x16x32_bf16 v[128:131], v[4:7], v[100:103], v[128:131]
	v_mfma_f32_16x16x32_bf16 v[132:135], v[8:11], v[44:47], 0
	v_mfma_f32_16x16x32_bf16 v[136:139], v[4:7], v[108:111], v[136:139]
	v_mfma_f32_16x16x32_bf16 v[154:157], v[8:11], v[104:107], 0
	v_mfma_f32_16x16x32_bf16 v[158:161], v[4:7], v[116:119], v[158:161]
	v_mfma_f32_16x16x32_bf16 v[162:165], v[8:11], v[112:115], 0
	v_mfma_f32_16x16x32_bf16 v[0:3], v[4:7], v[124:127], v[0:3]
	v_mfma_f32_16x16x32_bf16 v[4:7], v[8:11], v[120:123], 0
	v_mfma_f32_16x16x32_bf16 v[132:135], v[12:15], v[100:103], v[132:135]
	v_mfma_f32_16x16x32_bf16 v[154:157], v[12:15], v[108:111], v[154:157]
	v_mfma_f32_16x16x32_bf16 v[162:165], v[12:15], v[116:119], v[162:165]
	v_mfma_f32_16x16x32_bf16 v[4:7], v[12:15], v[124:127], v[4:7]
	s_setprio 0
	s_barrier
; #define PG8_STAGE(bufoff, gbase, voff) do { _Pragma("unroll") for (int _i = 0; _i < 2; ++_i) \
;         __builtin_amdgcn_global_load_lds((const unsigned*)((const char*)(gbase) + (voff)[_i]), (LAS unsigned*)(lds + (bufoff) + ldsw + _i * 8192), 16, 0, 0); } while (0)
; #define PG8_LDA(dst, b, h) do { _Pragma("unroll") for (int m = 0; m < 4; ++m) _Pragma("unroll") for (int k = 0; k < 2; ++k) dst[m][k] = *(const LAS bf16x8*)(lds + PG8_SA(b, h) + aoff + m * 2048 + k * 1024); } while (0)
; #define PG8_LDB(dst, b, h) do { _Pragma("unroll") for (int n = 0; n < 2; ++n) _Pragma("unroll") for (int k = 0; k < 2; ++k) dst[n][k] = *(const LAS bf16x8*)(lds + PG8_SB(b, h) + boff + n * 2048 + k * 1024); } while (0)
; #define PG8_WAIT_V(n) asm volatile("s_waitcnt vmcnt(" #n ")" ::: "memory")
; #define PG8_WAIT_L(n) asm volatile("s_waitcnt lgkmcnt(" #n ")" ::: "memory")
; #define PG8_BAR __builtin_amdgcn_s_barrier()
; #define PG8_SCHED __builtin_amdgcn_sched_barrier(0)
; template <class Epi>
; __device__ __forceinline__ void gemm_phase(LAS unsigned char* lds, const bf16_t* A, int lda, const bf16_t* Bt, int ldb, int M, int N, int K, int asel, const Epi& E, const int fixed_round = -1) {
;     ...
;             PG8_STAGE(PG8_SB(0, 1), b2 + hstepB, voffB);
;             PG8_WAIT_V(6); PG8_BAR; PG8_MMA(1, 1, At, B1); PG8_BAR;
;             PG8_LDB(B0, 1, 0); PG8_SCHED; PG8_LDA(At, 1, 0); PG8_STAGE(PG8_SA(0, 1), a2 + hstepA, voffA);
;             PG8_WAIT_L(8); PG8_BAR; PG8_WAIT_L(0); PG8_MMA(0, 0, At, B0); PG8_BAR; PG8_SCHED;
;             PG8_LDB(B1, 1, 1); PG8_STAGE(PG8_SB(1, 0), b3, voffB);
;             PG8_BAR; PG8_WAIT_L(0); PG8_MMA(0, 1, At, B1); PG8_BAR;
;             PG8_LDA(At, 1, 1); PG8_STAGE(PG8_SA(1, 0), a3, voffA);
	s_add_u32 s28, s66, 0x10100
	s_addc_u32 s29, s67, 0
	s_add_i32 vcc_lo, s82, s70
	v_lshl_add_u64 v[8:9], s[28:29], 0, v[142:143]
	s_mov_b32 m0, vcc_lo
	s_add_i32 s95, vcc_lo, 0x2000
	global_load_lds_dwordx4 v[8:9], off
	v_lshl_add_u64 v[8:9], s[28:29], 0, v[146:147]
	s_mov_b32 m0, s95
	s_nop 0
	global_load_lds_dwordx4 v[8:9], off
	s_waitcnt vmcnt(6)
	s_barrier
	s_setprio 1
	v_mfma_f32_16x16x32_bf16 v[8:11], v[80:83], v[44:47], 0
	v_mfma_f32_16x16x32_bf16 v[12:15], v[88:91], v[44:47], 0
	v_mfma_f32_16x16x32_bf16 v[8:11], v[84:87], v[100:103], v[8:11]
	v_mfma_f32_16x16x32_bf16 v[12:15], v[92:95], v[100:103], v[12:15]
	v_mfma_f32_16x16x32_bf16 v[44:47], v[80:83], v[104:107], 0
	v_mfma_f32_16x16x32_bf16 v[100:103], v[88:91], v[104:107], 0
	v_mfma_f32_16x16x32_bf16 v[104:107], v[80:83], v[112:115], 0
	v_mfma_f32_16x16x32_bf16 v[80:83], v[80:83], v[120:123], 0
	v_mfma_f32_16x16x32_bf16 v[44:47], v[84:87], v[108:111], v[44:47]
	v_mfma_f32_16x16x32_bf16 v[100:103], v[92:95], v[108:111], v[100:103]
	v_mfma_f32_16x16x32_bf16 v[104:107], v[84:87], v[116:119], v[104:107]
	v_mfma_f32_16x16x32_bf16 v[108:111], v[88:91], v[112:115], 0
	v_mfma_f32_16x16x32_bf16 v[80:83], v[84:87], v[124:127], v[80:83]
	v_mfma_f32_16x16x32_bf16 v[84:87], v[88:91], v[120:123], 0
	v_mfma_f32_16x16x32_bf16 v[108:111], v[92:95], v[116:119], v[108:111]
	v_mfma_f32_16x16x32_bf16 v[84:87], v[92:95], v[124:127], v[84:87]
	s_setprio 0
	v_add_u32_e32 v153, s83, v213
	s_barrier
	ds_read_b128 v[88:91], v153
	ds_read_b128 v[92:95], v153 offset:1024
	ds_read_b128 v[112:115], v153 offset:2048
	ds_read_b128 v[116:119], v153 offset:3072
	s_add_u32 s28, s64, 0x80100
	s_addc_u32 s29, s65, 0
	s_mov_b32 m0, s72
	v_lshl_add_u64 v[190:191], s[28:29], 0, v[140:141]
	ds_read_b128 v[120:123], v216 offset:32768
	ds_read_b128 v[124:127], v216 offset:33792
	ds_read_b128 v[166:169], v216 offset:34816
	ds_read_b128 v[170:173], v216 offset:35840
	ds_read_b128 v[174:177], v216 offset:36864
	ds_read_b128 v[178:181], v216 offset:37888
	ds_read_b128 v[182:185], v216 offset:38912
	ds_read_b128 v[186:189], v216 offset:39936
	global_load_lds_dwordx4 v[190:191], off
	v_lshl_add_u64 v[190:191], s[28:29], 0, v[144:145]
	s_mov_b32 m0, s73
	s_nop 0
	global_load_lds_dwordx4 v[190:191], off
	s_waitcnt lgkmcnt(8)
	s_barrier
	s_waitcnt lgkmcnt(0)
	s_setprio 1
	s_waitcnt lgkmcnt(0)
	v_mfma_f32_16x16x32_bf16 v[48:51], v[88:91], v[120:123], v[48:51]
	v_mfma_f32_16x16x32_bf16 v[52:55], v[112:115], v[120:123], v[52:55]
	v_mfma_f32_16x16x32_bf16 v[56:59], v[88:91], v[166:169], v[56:59]
	v_mfma_f32_16x16x32_bf16 v[60:63], v[112:115], v[166:169], v[60:63]
	v_mfma_f32_16x16x32_bf16 v[64:67], v[88:91], v[174:177], v[64:67]
	v_mfma_f32_16x16x32_bf16 v[68:71], v[112:115], v[174:177], v[68:71]
	v_mfma_f32_16x16x32_bf16 v[72:75], v[88:91], v[182:185], v[72:75]
	v_mfma_f32_16x16x32_bf16 v[76:79], v[112:115], v[182:185], v[76:79]
	v_mfma_f32_16x16x32_bf16 v[48:51], v[92:95], v[124:127], v[48:51]
	v_mfma_f32_16x16x32_bf16 v[52:55], v[116:119], v[124:127], v[52:55]
	v_mfma_f32_16x16x32_bf16 v[56:59], v[92:95], v[170:173], v[56:59]
	v_mfma_f32_16x16x32_bf16 v[60:63], v[116:119], v[170:173], v[60:63]
	v_mfma_f32_16x16x32_bf16 v[64:67], v[92:95], v[178:181], v[64:67]
	v_mfma_f32_16x16x32_bf16 v[68:71], v[116:119], v[178:181], v[68:71]
	v_mfma_f32_16x16x32_bf16 v[72:75], v[92:95], v[186:189], v[72:75]
	v_mfma_f32_16x16x32_bf16 v[76:79], v[116:119], v[186:189], v[76:79]
	s_setprio 0
	s_barrier
	s_add_i32 s97, s83, s70
	v_add_u32_e32 v223, s84, v213
	v_lshl_add_u64 v[198:199], v[198:199], 0, s[48:49]
	s_mov_b32 m0, s97
	s_add_i32 s28, s97, 0x2000
	ds_read_b128 v[190:193], v223
	ds_read_b128 v[194:197], v223 offset:1024
	ds_read_b128 v[202:205], v223 offset:2048
	ds_read_b128 v[206:209], v223 offset:3072
	global_load_lds_dwordx4 v[198:199], off
	v_lshl_add_u64 v[198:199], v[210:211], 0, s[48:49]
	s_mov_b32 m0, s28
	s_nop 0
	global_load_lds_dwordx4 v[198:199], off
	s_barrier
	s_waitcnt lgkmcnt(0)
	s_setprio 1
	s_waitcnt lgkmcnt(0)
	v_mfma_f32_16x16x32_bf16 v[96:99], v[190:193], v[120:123], v[96:99]
	v_mfma_f32_16x16x32_bf16 v[16:19], v[202:205], v[120:123], v[16:19]
	v_mfma_f32_16x16x32_bf16 v[20:23], v[190:193], v[166:169], v[20:23]
	v_mfma_f32_16x16x32_bf16 v[24:27], v[202:205], v[166:169], v[24:27]
	v_mfma_f32_16x16x32_bf16 v[28:31], v[190:193], v[174:177], v[28:31]
	v_mfma_f32_16x16x32_bf16 v[32:35], v[202:205], v[174:177], v[32:35]
	v_mfma_f32_16x16x32_bf16 v[36:39], v[190:193], v[182:185], v[36:39]
	v_mfma_f32_16x16x32_bf16 v[40:43], v[202:205], v[182:185], v[40:43]
	v_mfma_f32_16x16x32_bf16 v[96:99], v[194:197], v[124:127], v[96:99]
	v_mfma_f32_16x16x32_bf16 v[16:19], v[206:209], v[124:127], v[16:19]
	v_mfma_f32_16x16x32_bf16 v[20:23], v[194:197], v[170:173], v[20:23]
	v_mfma_f32_16x16x32_bf16 v[24:27], v[206:209], v[170:173], v[24:27]
	v_mfma_f32_16x16x32_bf16 v[28:31], v[194:197], v[178:181], v[28:31]
	v_mfma_f32_16x16x32_bf16 v[32:35], v[206:209], v[178:181], v[32:35]
	v_mfma_f32_16x16x32_bf16 v[36:39], v[194:197], v[186:189], v[36:39]
	v_mfma_f32_16x16x32_bf16 v[40:43], v[206:209], v[186:189], v[40:43]
	s_setprio 0
	s_mov_b32 m0, s74
	v_lshl_add_u64 v[198:199], v[224:225], 0, s[48:49]
	s_barrier
	ds_read_b128 v[120:123], v216 offset:49152
	ds_read_b128 v[124:127], v216 offset:50176
	ds_read_b128 v[166:169], v216 offset:51200
	ds_read_b128 v[170:173], v216 offset:52224
	ds_read_b128 v[174:177], v216 offset:53248
	ds_read_b128 v[178:181], v216 offset:54272
	ds_read_b128 v[182:185], v216 offset:55296
	ds_read_b128 v[186:189], v216 offset:56320
	global_load_lds_dwordx4 v[198:199], off
	v_lshl_add_u64 v[198:199], v[226:227], 0, s[48:49]
	s_mov_b32 m0, s75
	s_nop 0
	global_load_lds_dwordx4 v[198:199], off
	s_barrier
; #define PG8_STAGE(bufoff, gbase, voff) do { _Pragma("unroll") for (int _i = 0; _i < 2; ++_i) \
;         __builtin_amdgcn_global_load_lds((const unsigned*)((const char*)(gbase) + (voff)[_i]), (LAS unsigned*)(lds + (bufoff) + ldsw + _i * 8192), 16, 0, 0); } while (0)
; #define PG8_LDA(dst, b, h) do { _Pragma("unroll") for (int m = 0; m < 4; ++m) _Pragma("unroll") for (int k = 0; k < 2; ++k) dst[m][k] = *(const LAS bf16x8*)(lds + PG8_SA(b, h) + aoff + m * 2048 + k * 1024); } while (0)
; #define PG8_LDB(dst, b, h) do { _Pragma("unroll") for (int n = 0; n < 2; ++n) _Pragma("unroll") for (int k = 0; k < 2; ++k) dst[n][k] = *(const LAS bf16x8*)(lds + PG8_SB(b, h) + boff + n * 2048 + k * 1024); } while (0)
; #define PG8_WAIT_V(n) asm volatile("s_waitcnt vmcnt(" #n ")" ::: "memory")
; #define PG8_WAIT_L(n) asm volatile("s_waitcnt lgkmcnt(" #n ")" ::: "memory")
; #define PG8_BAR __builtin_amdgcn_s_barrier()
; #define PG8_SCHED __builtin_amdgcn_sched_barrier(0)
; template <class Epi>
; __device__ __forceinline__ void gemm_phase(LAS unsigned char* lds, const bf16_t* A, int lda, const bf16_t* Bt, int ldb, int M, int N, int K, int asel, const Epi& E, const int fixed_round = -1) {
;     ...
;             PG8_LDB(B0, 0, 0); PG8_SCHED; PG8_LDA(At, 0, 0); PG8_STAGE(PG8_SA(1, 1), a1 + hstepA, voffA);
;             PG8_WAIT_L(8); PG8_BAR; PG8_WAIT_L(0); PG8_MMA(0, 0, At, B0); PG8_BAR; PG8_SCHED;
;             PG8_LDB(B1, 0, 1); PG8_STAGE(PG8_SB(0, 0), b2, voffB);
;     ...
;             PG8_BAR; PG8_WAIT_L(0); PG8_MMA(1, 0, At, B0); PG8_BAR; PG8_SCHED;
;             PG8_STAGE(PG8_SB(1, 1), b3 + hstepB, voffB);
;             PG8_WAIT_V(6); PG8_BAR; PG8_MMA(1, 1, At, B1); PG8_BAR;
	s_waitcnt lgkmcnt(0)
	s_setprio 1
	s_waitcnt lgkmcnt(0)
	v_mfma_f32_16x16x32_bf16 v[128:131], v[88:91], v[120:123], v[128:131]
	v_mfma_f32_16x16x32_bf16 v[132:135], v[112:115], v[120:123], v[132:135]
	v_mfma_f32_16x16x32_bf16 v[136:139], v[88:91], v[166:169], v[136:139]
	v_mfma_f32_16x16x32_bf16 v[154:157], v[112:115], v[166:169], v[154:157]
	v_mfma_f32_16x16x32_bf16 v[158:161], v[88:91], v[174:177], v[158:161]
	v_mfma_f32_16x16x32_bf16 v[162:165], v[112:115], v[174:177], v[162:165]
	v_mfma_f32_16x16x32_bf16 v[0:3], v[88:91], v[182:185], v[0:3]
	v_mfma_f32_16x16x32_bf16 v[4:7], v[112:115], v[182:185], v[4:7]
	v_mfma_f32_16x16x32_bf16 v[128:131], v[92:95], v[124:127], v[128:131]
	v_mfma_f32_16x16x32_bf16 v[132:135], v[116:119], v[124:127], v[132:135]
	v_mfma_f32_16x16x32_bf16 v[136:139], v[92:95], v[170:173], v[136:139]
	v_mfma_f32_16x16x32_bf16 v[154:157], v[116:119], v[170:173], v[154:157]
	v_mfma_f32_16x16x32_bf16 v[158:161], v[92:95], v[178:181], v[158:161]
	v_mfma_f32_16x16x32_bf16 v[162:165], v[116:119], v[178:181], v[162:165]
	v_mfma_f32_16x16x32_bf16 v[0:3], v[92:95], v[186:189], v[0:3]
	v_mfma_f32_16x16x32_bf16 v[4:7], v[116:119], v[186:189], v[4:7]
	s_setprio 0
	s_barrier
	s_add_u32 s66, s66, 0x10180
	s_addc_u32 s67, s67, 0
	s_add_i32 s29, s84, s70
	v_lshl_add_u64 v[88:89], s[66:67], 0, v[142:143]
	s_mov_b32 m0, s29
	s_nop 0
	global_load_lds_dwordx4 v[88:89], off
	v_lshl_add_u64 v[88:89], s[66:67], 0, v[146:147]
	s_add_i32 s66, s29, 0x2000
	s_mov_b32 m0, s66
	s_nop 0
	global_load_lds_dwordx4 v[88:89], off
	s_waitcnt vmcnt(6)
	s_barrier
	s_setprio 1
	v_mfma_f32_16x16x32_bf16 v[8:11], v[190:193], v[120:123], v[8:11]
	v_mfma_f32_16x16x32_bf16 v[12:15], v[202:205], v[120:123], v[12:15]
	v_mfma_f32_16x16x32_bf16 v[44:47], v[190:193], v[166:169], v[44:47]
	v_mfma_f32_16x16x32_bf16 v[88:91], v[202:205], v[166:169], v[100:103]
	v_mfma_f32_16x16x32_bf16 v[92:95], v[190:193], v[174:177], v[104:107]
	v_mfma_f32_16x16x32_bf16 v[100:103], v[202:205], v[174:177], v[108:111]
	v_mfma_f32_16x16x32_bf16 v[80:83], v[190:193], v[182:185], v[80:83]
	v_mfma_f32_16x16x32_bf16 v[84:87], v[202:205], v[182:185], v[84:87]
	v_mfma_f32_16x16x32_bf16 v[8:11], v[194:197], v[124:127], v[8:11]
	v_mfma_f32_16x16x32_bf16 v[12:15], v[206:209], v[124:127], v[12:15]
	v_mfma_f32_16x16x32_bf16 v[44:47], v[194:197], v[170:173], v[44:47]
	v_mfma_f32_16x16x32_bf16 v[88:91], v[206:209], v[170:173], v[88:91]
	v_mfma_f32_16x16x32_bf16 v[92:95], v[194:197], v[178:181], v[92:95]
	v_mfma_f32_16x16x32_bf16 v[100:103], v[206:209], v[178:181], v[100:103]
	v_mfma_f32_16x16x32_bf16 v[80:83], v[194:197], v[186:189], v[80:83]
	v_mfma_f32_16x16x32_bf16 v[84:87], v[206:209], v[186:189], v[84:87]
	s_setprio 0
	s_barrier
	ds_read_b128 v[104:107], v215
	ds_read_b128 v[108:111], v215 offset:1024
	ds_read_b128 v[112:115], v215 offset:2048
	ds_read_b128 v[116:119], v215 offset:3072
	s_add_u32 s64, s64, 0x80180
	s_addc_u32 s65, s65, 0
	s_mov_b32 m0, vcc_hi
	v_lshl_add_u64 v[190:191], s[64:65], 0, v[140:141]
	ds_read_b128 v[120:123], v216
	ds_read_b128 v[124:127], v216 offset:1024
	ds_read_b128 v[166:169], v216 offset:2048
	ds_read_b128 v[170:173], v216 offset:3072
	ds_read_b128 v[174:177], v216 offset:4096
	ds_read_b128 v[178:181], v216 offset:5120
	ds_read_b128 v[182:185], v216 offset:6144
	ds_read_b128 v[186:189], v216 offset:7168
	global_load_lds_dwordx4 v[190:191], off
	v_lshl_add_u64 v[190:191], s[64:65], 0, v[144:145]
	s_mov_b32 m0, s55
	s_nop 0
	global_load_lds_dwordx4 v[190:191], off
	s_waitcnt lgkmcnt(8)
	s_barrier
	s_waitcnt lgkmcnt(0)
	s_setprio 1
	s_waitcnt lgkmcnt(0)
	v_mfma_f32_16x16x32_bf16 v[56:59], v[104:107], v[166:169], v[56:59]
	v_mfma_f32_16x16x32_bf16 v[190:193], v[108:111], v[170:173], v[56:59]
	v_mfma_f32_16x16x32_bf16 v[56:59], v[112:115], v[166:169], v[60:63]
	v_mfma_f32_16x16x32_bf16 v[60:63], v[116:119], v[170:173], v[56:59]
	v_mfma_f32_16x16x32_bf16 v[56:59], v[104:107], v[174:177], v[64:67]
	v_mfma_f32_16x16x32_bf16 v[64:67], v[108:111], v[178:181], v[56:59]
	v_mfma_f32_16x16x32_bf16 v[56:59], v[112:115], v[174:177], v[68:71]
	v_mfma_f32_16x16x32_bf16 v[68:71], v[116:119], v[178:181], v[56:59]
	v_mfma_f32_16x16x32_bf16 v[56:59], v[104:107], v[182:185], v[72:75]
	v_mfma_f32_16x16x32_bf16 v[48:51], v[104:107], v[120:123], v[48:51]
	v_mfma_f32_16x16x32_bf16 v[52:55], v[112:115], v[120:123], v[52:55]
	v_mfma_f32_16x16x32_bf16 v[72:75], v[108:111], v[186:189], v[56:59]
	v_mfma_f32_16x16x32_bf16 v[56:59], v[112:115], v[182:185], v[76:79]
	v_mfma_f32_16x16x32_bf16 v[48:51], v[108:111], v[124:127], v[48:51]
	v_mfma_f32_16x16x32_bf16 v[52:55], v[116:119], v[124:127], v[52:55]
	v_mfma_f32_16x16x32_bf16 v[76:79], v[116:119], v[186:189], v[56:59]
	s_setprio 0
	s_barrier
	s_mov_b32 m0, s96
	v_lshl_add_u64 v[198:199], s[0:1], 0, v[142:143]
	s_nop 0
	ds_read_b128 v[56:59], v217
	ds_read_b128 v[194:197], v217 offset:1024
	ds_read_b128 v[202:205], v217 offset:2048
	ds_read_b128 v[206:209], v217 offset:3072
	global_load_lds_dwordx4 v[198:199], off
	v_lshl_add_u64 v[210:211], s[0:1], 0, v[146:147]
	s_mov_b32 m0, s57
	s_nop 0
	global_load_lds_dwordx4 v[210:211], off
	s_barrier
; #define PG8_STAGE(bufoff, gbase, voff) do { _Pragma("unroll") for (int _i = 0; _i < 2; ++_i) \
;         __builtin_amdgcn_global_load_lds((const unsigned*)((const char*)(gbase) + (voff)[_i]), (LAS unsigned*)(lds + (bufoff) + ldsw + _i * 8192), 16, 0, 0); } while (0)
; #define PG8_LDA(dst, b, h) do { _Pragma("unroll") for (int m = 0; m < 4; ++m) _Pragma("unroll") for (int k = 0; k < 2; ++k) dst[m][k] = *(const LAS bf16x8*)(lds + PG8_SA(b, h) + aoff + m * 2048 + k * 1024); } while (0)
; #define PG8_LDB(dst, b, h) do { _Pragma("unroll") for (int n = 0; n < 2; ++n) _Pragma("unroll") for (int k = 0; k < 2; ++k) dst[n][k] = *(const LAS bf16x8*)(lds + PG8_SB(b, h) + boff + n * 2048 + k * 1024); } while (0)
; #define PG8_WAIT_V(n) asm volatile("s_waitcnt vmcnt(" #n ")" ::: "memory")
; #define PG8_WAIT_L(n) asm volatile("s_waitcnt lgkmcnt(" #n ")" ::: "memory")
; #define PG8_BAR __builtin_amdgcn_s_barrier()
; #define PG8_SCHED __builtin_amdgcn_sched_barrier(0)
; template <class Epi>
; __device__ __forceinline__ void gemm_phase(LAS unsigned char* lds, const bf16_t* A, int lda, const bf16_t* Bt, int ldb, int M, int N, int K, int asel, const Epi& E, const int fixed_round = -1) {
;     ...
;             PG8_BAR; PG8_WAIT_L(0); PG8_MMA(0, 1, At, B1); PG8_BAR;
;             PG8_LDA(At, 0, 1); PG8_STAGE(PG8_SA(0, 0), a2, voffA);
;             PG8_BAR; PG8_WAIT_L(0); PG8_MMA(1, 0, At, B0); PG8_BAR; PG8_SCHED;
;             PG8_STAGE(PG8_SB(0, 1), b2 + hstepB, voffB);
;             PG8_WAIT_V(6); PG8_BAR; PG8_MMA(1, 1, At, B1); PG8_BAR;
;             PG8_LDB(B0, 1, 0); PG8_SCHED; PG8_LDA(At, 1, 0); PG8_STAGE(PG8_SA(0, 1), a2 + hstepA, voffA);
	s_waitcnt lgkmcnt(0)
	s_setprio 1
	s_waitcnt lgkmcnt(0)
	v_mfma_f32_16x16x32_bf16 v[32:35], v[202:205], v[174:177], v[32:35]
	v_mfma_f32_16x16x32_bf16 v[20:23], v[56:59], v[166:169], v[20:23]
	v_mfma_f32_16x16x32_bf16 v[24:27], v[202:205], v[166:169], v[24:27]
	v_mfma_f32_16x16x32_bf16 v[166:169], v[206:209], v[178:181], v[32:35]
	v_mfma_f32_16x16x32_bf16 v[32:35], v[56:59], v[182:185], v[36:39]
	v_mfma_f32_16x16x32_bf16 v[96:99], v[56:59], v[120:123], v[96:99]
	v_mfma_f32_16x16x32_bf16 v[16:19], v[202:205], v[120:123], v[16:19]
	v_mfma_f32_16x16x32_bf16 v[28:31], v[56:59], v[174:177], v[28:31]
	v_mfma_f32_16x16x32_bf16 v[36:39], v[194:197], v[186:189], v[32:35]
	v_mfma_f32_16x16x32_bf16 v[32:35], v[202:205], v[182:185], v[40:43]
	v_mfma_f32_16x16x32_bf16 v[96:99], v[194:197], v[124:127], v[96:99]
	v_mfma_f32_16x16x32_bf16 v[16:19], v[206:209], v[124:127], v[16:19]
	v_mfma_f32_16x16x32_bf16 v[20:23], v[194:197], v[170:173], v[20:23]
	v_mfma_f32_16x16x32_bf16 v[24:27], v[206:209], v[170:173], v[24:27]
	v_mfma_f32_16x16x32_bf16 v[28:31], v[194:197], v[178:181], v[28:31]
	v_mfma_f32_16x16x32_bf16 v[170:173], v[206:209], v[186:189], v[32:35]
	s_setprio 0
	s_mov_b32 m0, s63
	v_lshl_add_u64 v[252:253], s[2:3], 0, v[140:141]
	s_barrier
	ds_read_b128 v[32:35], v216 offset:16384
	ds_read_b128 v[40:43], v216 offset:17408
	ds_read_b128 v[120:123], v216 offset:18432
	ds_read_b128 v[124:127], v216 offset:19456
	ds_read_b128 v[174:177], v216 offset:20480
	ds_read_b128 v[178:181], v216 offset:21504
	ds_read_b128 v[182:185], v216 offset:22528
	ds_read_b128 v[186:189], v216 offset:23552
	global_load_lds_dwordx4 v[252:253], off
	v_lshl_add_u64 v[148:149], s[2:3], 0, v[144:145]
	s_mov_b32 m0, s71
	s_nop 0
	global_load_lds_dwordx4 v[148:149], off
	s_barrier
	s_waitcnt lgkmcnt(0)
	s_setprio 1
	s_waitcnt lgkmcnt(0)
	v_mfma_f32_16x16x32_bf16 v[128:131], v[104:107], v[32:35], v[128:131]
	v_mfma_f32_16x16x32_bf16 v[224:227], v[108:111], v[40:43], v[128:131]
	v_mfma_f32_16x16x32_bf16 v[128:131], v[112:115], v[32:35], v[132:135]
	v_mfma_f32_16x16x32_bf16 v[228:231], v[116:119], v[40:43], v[128:131]
	v_mfma_f32_16x16x32_bf16 v[128:131], v[104:107], v[120:123], v[136:139]
	v_mfma_f32_16x16x32_bf16 v[136:139], v[108:111], v[124:127], v[128:131]
	v_mfma_f32_16x16x32_bf16 v[128:131], v[112:115], v[120:123], v[154:157]
	v_mfma_f32_16x16x32_bf16 v[154:157], v[116:119], v[124:127], v[128:131]
	v_mfma_f32_16x16x32_bf16 v[128:131], v[104:107], v[174:177], v[158:161]
	v_mfma_f32_16x16x32_bf16 v[158:161], v[108:111], v[178:181], v[128:131]
	v_mfma_f32_16x16x32_bf16 v[128:131], v[112:115], v[174:177], v[162:165]
	v_mfma_f32_16x16x32_bf16 v[0:3], v[104:107], v[182:185], v[0:3]
	v_mfma_f32_16x16x32_bf16 v[4:7], v[112:115], v[182:185], v[4:7]
	v_mfma_f32_16x16x32_bf16 v[162:165], v[116:119], v[178:181], v[128:131]
	v_mfma_f32_16x16x32_bf16 v[0:3], v[108:111], v[186:189], v[0:3]
	v_mfma_f32_16x16x32_bf16 v[4:7], v[116:119], v[186:189], v[4:7]
	s_setprio 0
	s_barrier
	s_add_u32 s64, s0, 0x10000
	s_addc_u32 s65, s1, 0
	s_mov_b32 m0, vcc_lo
	v_lshl_add_u64 v[104:105], s[64:65], 0, v[142:143]
	global_load_lds_dwordx4 v[104:105], off
	v_lshl_add_u64 v[104:105], s[64:65], 0, v[146:147]
	s_mov_b32 m0, s95
	s_nop 0
	global_load_lds_dwordx4 v[104:105], off
	s_waitcnt vmcnt(6)
	s_barrier
	s_setprio 1
	v_mfma_f32_16x16x32_bf16 v[8:11], v[56:59], v[32:35], v[8:11]
	v_mfma_f32_16x16x32_bf16 v[232:235], v[194:197], v[40:43], v[8:11]
	v_mfma_f32_16x16x32_bf16 v[8:11], v[202:205], v[32:35], v[12:15]
	v_mfma_f32_16x16x32_bf16 v[12:15], v[206:209], v[40:43], v[8:11]
	v_mfma_f32_16x16x32_bf16 v[8:11], v[56:59], v[120:123], v[44:47]
	v_mfma_f32_16x16x32_bf16 v[236:239], v[194:197], v[124:127], v[8:11]
	v_mfma_f32_16x16x32_bf16 v[8:11], v[202:205], v[120:123], v[88:91]
	v_mfma_f32_16x16x32_bf16 v[240:243], v[206:209], v[124:127], v[8:11]
	v_mfma_f32_16x16x32_bf16 v[8:11], v[56:59], v[174:177], v[92:95]
	v_mfma_f32_16x16x32_bf16 v[244:247], v[194:197], v[178:181], v[8:11]
	v_mfma_f32_16x16x32_bf16 v[8:11], v[202:205], v[174:177], v[100:103]
	v_mfma_f32_16x16x32_bf16 v[174:177], v[206:209], v[178:181], v[8:11]
	v_mfma_f32_16x16x32_bf16 v[8:11], v[56:59], v[182:185], v[80:83]
	v_mfma_f32_16x16x32_bf16 v[178:181], v[194:197], v[186:189], v[8:11]
	v_mfma_f32_16x16x32_bf16 v[8:11], v[202:205], v[182:185], v[84:87]
	v_mfma_f32_16x16x32_bf16 v[182:185], v[206:209], v[186:189], v[8:11]
	s_setprio 0
	s_barrier
	ds_read_b128 v[84:87], v153
	ds_read_b128 v[92:95], v153 offset:1024
	ds_read_b128 v[100:103], v153 offset:2048
	ds_read_b128 v[186:189], v153 offset:3072
	s_add_u32 s2, s2, 0x80000
	s_addc_u32 s3, s3, 0
	s_mov_b32 m0, s72
	v_lshl_add_u64 v[32:33], s[2:3], 0, v[140:141]
	ds_read_b128 v[8:11], v216 offset:32768
	ds_read_b128 v[44:47], v216 offset:33792
	ds_read_b128 v[80:83], v216 offset:34816
	ds_read_b128 v[88:91], v216 offset:35840
	ds_read_b128 v[108:111], v216 offset:36864
	ds_read_b128 v[194:197], v216 offset:37888
	ds_read_b128 v[202:205], v216 offset:38912
	ds_read_b128 v[206:209], v216 offset:39936
	global_load_lds_dwordx4 v[32:33], off
	v_lshl_add_u64 v[32:33], s[2:3], 0, v[144:145]
	s_mov_b32 m0, s73
	s_nop 0
	global_load_lds_dwordx4 v[32:33], off
	s_waitcnt lgkmcnt(8)
	s_barrier
; #define PG8_STAGE(bufoff, gbase, voff) do { _Pragma("unroll") for (int _i = 0; _i < 2; ++_i) \
;         __builtin_amdgcn_global_load_lds((const unsigned*)((const char*)(gbase) + (voff)[_i]), (LAS unsigned*)(lds + (bufoff) + ldsw + _i * 8192), 16, 0, 0); } while (0)
; #define PG8_LDA(dst, b, h) do { _Pragma("unroll") for (int m = 0; m < 4; ++m) _Pragma("unroll") for (int k = 0; k < 2; ++k) dst[m][k] = *(const LAS bf16x8*)(lds + PG8_SA(b, h) + aoff + m * 2048 + k * 1024); } while (0)
; #define PG8_LDB(dst, b, h) do { _Pragma("unroll") for (int n = 0; n < 2; ++n) _Pragma("unroll") for (int k = 0; k < 2; ++k) dst[n][k] = *(const LAS bf16x8*)(lds + PG8_SB(b, h) + boff + n * 2048 + k * 1024); } while (0)
; #define PG8_WAIT_V(n) asm volatile("s_waitcnt vmcnt(" #n ")" ::: "memory")
; #define PG8_WAIT_L(n) asm volatile("s_waitcnt lgkmcnt(" #n ")" ::: "memory")
; #define PG8_BAR __builtin_amdgcn_s_barrier()
; template <class Epi>
; __device__ __forceinline__ void gemm_phase(LAS unsigned char* lds, const bf16_t* A, int lda, const bf16_t* Bt, int ldb, int M, int N, int K, int asel, const Epi& E, const int fixed_round = -1) {
;     ...
;             PG8_LDB(B0, 0, 0); PG8_SCHED; PG8_LDA(At, 0, 0); PG8_STAGE(PG8_SA(1, 1), a1 + hstepA, voffA);
;             PG8_WAIT_L(8); PG8_BAR; PG8_WAIT_L(0); PG8_MMA(0, 0, At, B0); PG8_BAR; PG8_SCHED;
;             PG8_LDB(B1, 0, 1); PG8_STAGE(PG8_SB(0, 0), b2, voffB);
;             PG8_BAR; PG8_WAIT_L(0); PG8_MMA(0, 1, At, B1); PG8_BAR;
;             PG8_LDA(At, 0, 1); PG8_STAGE(PG8_SA(0, 0), a2, voffA);
;             PG8_BAR; PG8_WAIT_L(0); PG8_MMA(1, 0, At, B0); PG8_BAR; PG8_SCHED;
;             PG8_STAGE(PG8_SB(0, 1), b2 + hstepB, voffB);
;             PG8_WAIT_V(6); PG8_BAR; PG8_MMA(1, 1, At, B1); PG8_BAR;
;             PG8_LDB(B0, 1, 0); PG8_SCHED; PG8_LDA(At, 1, 0); PG8_STAGE(PG8_SA(0, 1), a2 + hstepA, voffA);
;             PG8_WAIT_L(8); PG8_BAR; PG8_WAIT_L(0); PG8_MMA(0, 0, At, B0); PG8_BAR; PG8_SCHED;
;             PG8_LDB(B1, 1, 1); PG8_STAGE(PG8_SB(1, 0), b3, voffB);
;             PG8_BAR; PG8_WAIT_L(0); PG8_MMA(0, 1, At, B1); PG8_BAR;
;             PG8_LDA(At, 1, 1); PG8_STAGE(PG8_SA(1, 0), a3, voffA);
;             PG8_BAR; PG8_WAIT_L(0); PG8_MMA(1, 0, At, B0); PG8_BAR; PG8_SCHED;
;             PG8_STAGE(PG8_SB(1, 1), b3 + hstepB, voffB);
;             PG8_WAIT_V(6); PG8_BAR; PG8_MMA(1, 1, At, B1); PG8_BAR;
	s_waitcnt lgkmcnt(0)
	s_setprio 1
	s_waitcnt lgkmcnt(0)
	v_mfma_f32_16x16x32_bf16 v[32:35], v[84:87], v[8:11], v[48:51]
	v_mfma_f32_16x16x32_bf16 v[128:131], v[92:95], v[44:47], v[32:35]
	v_mfma_f32_16x16x32_bf16 v[32:35], v[100:103], v[8:11], v[52:55]
	v_mfma_f32_16x16x32_bf16 v[56:59], v[186:189], v[44:47], v[32:35]
	v_mfma_f32_16x16x32_bf16 v[32:35], v[84:87], v[80:83], v[190:193]
	v_mfma_f32_16x16x32_bf16 v[120:123], v[92:95], v[88:91], v[32:35]
	v_mfma_f32_16x16x32_bf16 v[32:35], v[100:103], v[80:83], v[60:63]
	v_mfma_f32_16x16x32_bf16 v[48:51], v[186:189], v[88:91], v[32:35]
	v_mfma_f32_16x16x32_bf16 v[32:35], v[84:87], v[108:111], v[64:67]
	v_mfma_f32_16x16x32_bf16 v[112:115], v[92:95], v[194:197], v[32:35]
	v_mfma_f32_16x16x32_bf16 v[32:35], v[100:103], v[108:111], v[68:71]
	v_mfma_f32_16x16x32_bf16 v[40:43], v[186:189], v[194:197], v[32:35]
	v_mfma_f32_16x16x32_bf16 v[32:35], v[84:87], v[202:205], v[72:75]
	v_mfma_f32_16x16x32_bf16 v[104:107], v[92:95], v[206:209], v[32:35]
	v_mfma_f32_16x16x32_bf16 v[32:35], v[100:103], v[202:205], v[76:79]
	v_mfma_f32_16x16x32_bf16 v[32:35], v[186:189], v[206:209], v[32:35]
	s_setprio 0
	s_barrier
	s_mov_b32 m0, s97
	v_lshl_add_u64 v[52:53], v[198:199], 0, s[44:45]
	ds_read_b128 v[68:71], v223
	ds_read_b128 v[72:75], v223 offset:1024
	ds_read_b128 v[76:79], v223 offset:2048
	ds_read_b128 v[190:193], v223 offset:3072
	global_load_lds_dwordx4 v[52:53], off
	v_lshl_add_u64 v[52:53], v[210:211], 0, s[44:45]
	s_mov_b32 m0, s28
	s_nop 0
	global_load_lds_dwordx4 v[52:53], off
	s_barrier
	s_waitcnt lgkmcnt(0)
	s_setprio 1
	s_waitcnt lgkmcnt(0)
	v_mfma_f32_16x16x32_bf16 v[52:55], v[68:71], v[8:11], v[96:99]
	v_mfma_f32_16x16x32_bf16 v[8:11], v[76:79], v[8:11], v[16:19]
	v_mfma_f32_16x16x32_bf16 v[60:63], v[190:193], v[44:47], v[8:11]
	v_mfma_f32_16x16x32_bf16 v[8:11], v[68:71], v[80:83], v[20:23]
	v_mfma_f32_16x16x32_bf16 v[124:127], v[72:75], v[88:91], v[8:11]
	v_mfma_f32_16x16x32_bf16 v[8:11], v[76:79], v[80:83], v[24:27]
	v_mfma_f32_16x16x32_bf16 v[132:135], v[72:75], v[44:47], v[52:55]
	v_mfma_f32_16x16x32_bf16 v[52:55], v[190:193], v[88:91], v[8:11]
	v_mfma_f32_16x16x32_bf16 v[8:11], v[68:71], v[108:111], v[28:31]
	v_mfma_f32_16x16x32_bf16 v[116:119], v[72:75], v[194:197], v[8:11]
	v_mfma_f32_16x16x32_bf16 v[8:11], v[76:79], v[108:111], v[166:169]
	v_mfma_f32_16x16x32_bf16 v[44:47], v[190:193], v[194:197], v[8:11]
	v_mfma_f32_16x16x32_bf16 v[8:11], v[68:71], v[202:205], v[36:39]
	v_mfma_f32_16x16x32_bf16 v[108:111], v[72:75], v[206:209], v[8:11]
	v_mfma_f32_16x16x32_bf16 v[8:11], v[76:79], v[202:205], v[170:173]
	v_mfma_f32_16x16x32_bf16 v[36:39], v[190:193], v[206:209], v[8:11]
	s_setprio 0
	s_mov_b32 m0, s74
	s_nop 4
	v_lshl_add_u64 v[8:9], v[252:253], 0, s[44:45]
	s_barrier
	ds_read_b128 v[20:23], v216 offset:49152
	ds_read_b128 v[28:31], v216 offset:50176
	ds_read_b128 v[166:169], v216 offset:51200
	ds_read_b128 v[170:173], v216 offset:52224
	ds_read_b128 v[194:197], v216 offset:53248
	ds_read_b128 v[202:205], v216 offset:54272
	ds_read_b128 v[206:209], v216 offset:55296
	ds_read_b128 v[248:251], v216 offset:56320
	global_load_lds_dwordx4 v[8:9], off
	v_lshl_add_u64 v[8:9], v[148:149], 0, s[44:45]
	s_mov_b32 m0, s75
	s_nop 0
	global_load_lds_dwordx4 v[8:9], off
	s_barrier
	s_waitcnt lgkmcnt(0)
	s_setprio 1
	s_waitcnt lgkmcnt(0)
	v_mfma_f32_16x16x32_bf16 v[8:11], v[84:87], v[20:23], v[224:227]
	v_mfma_f32_16x16x32_bf16 v[96:99], v[92:95], v[28:31], v[8:11]
	v_mfma_f32_16x16x32_bf16 v[8:11], v[100:103], v[20:23], v[228:231]
	v_mfma_f32_16x16x32_bf16 v[24:27], v[186:189], v[28:31], v[8:11]
	v_mfma_f32_16x16x32_bf16 v[8:11], v[84:87], v[166:169], v[136:139]
	v_mfma_f32_16x16x32_bf16 v[88:91], v[92:95], v[170:173], v[8:11]
	v_mfma_f32_16x16x32_bf16 v[8:11], v[100:103], v[166:169], v[154:157]
	v_mfma_f32_16x16x32_bf16 v[16:19], v[186:189], v[170:173], v[8:11]
	v_mfma_f32_16x16x32_bf16 v[8:11], v[84:87], v[194:197], v[158:161]
	v_mfma_f32_16x16x32_bf16 v[0:3], v[84:87], v[206:209], v[0:3]
	v_mfma_f32_16x16x32_bf16 v[80:83], v[92:95], v[202:205], v[8:11]
	v_mfma_f32_16x16x32_bf16 v[8:11], v[100:103], v[194:197], v[162:165]
	v_mfma_f32_16x16x32_bf16 v[64:67], v[92:95], v[248:251], v[0:3]
	v_mfma_f32_16x16x32_bf16 v[0:3], v[100:103], v[206:209], v[4:7]
	v_mfma_f32_16x16x32_bf16 v[8:11], v[186:189], v[202:205], v[8:11]
	v_mfma_f32_16x16x32_bf16 v[0:3], v[186:189], v[248:251], v[0:3]
	s_setprio 0
	s_barrier
	s_add_u32 s0, s0, 0x10080
	s_addc_u32 s1, s1, 0
	s_mov_b32 m0, s29
	v_lshl_add_u64 v[4:5], s[0:1], 0, v[142:143]
	global_load_lds_dwordx4 v[4:5], off
	v_lshl_add_u64 v[4:5], s[0:1], 0, v[146:147]
	s_mov_b32 m0, s66
	s_nop 0
	global_load_lds_dwordx4 v[4:5], off
	s_waitcnt vmcnt(6)
	s_barrier
; #define PG8_STAGE(bufoff, gbase, voff) do { _Pragma("unroll") for (int _i = 0; _i < 2; ++_i) \
;         __builtin_amdgcn_global_load_lds((const unsigned*)((const char*)(gbase) + (voff)[_i]), (LAS unsigned*)(lds + (bufoff) + ldsw + _i * 8192), 16, 0, 0); } while (0)
; #define PG8_LDA(dst, b, h) do { _Pragma("unroll") for (int m = 0; m < 4; ++m) _Pragma("unroll") for (int k = 0; k < 2; ++k) dst[m][k] = *(const LAS bf16x8*)(lds + PG8_SA(b, h) + aoff + m * 2048 + k * 1024); } while (0)
; #define PG8_WAIT_V(n) asm volatile("s_waitcnt vmcnt(" #n ")" ::: "memory")
; #define PG8_WAIT_L(n) asm volatile("s_waitcnt lgkmcnt(" #n ")" ::: "memory")
; #define PG8_BAR __builtin_amdgcn_s_barrier()
; template <class Epi>
; __device__ __forceinline__ void gemm_phase(LAS unsigned char* lds, const bf16_t* A, int lda, const bf16_t* Bt, int ldb, int M, int N, int K, int asel, const Epi& E, const int fixed_round = -1) {
;     ...
;             PG8_WAIT_V(6); PG8_BAR; PG8_MMA(1, 1, At, B1); PG8_BAR;
;             PG8_LDB(B0, 1, 0); PG8_SCHED; PG8_LDA(At, 1, 0); PG8_STAGE(PG8_SA(0, 1), a2 + hstepA, voffA);
;             PG8_WAIT_L(8); PG8_BAR; PG8_WAIT_L(0); PG8_MMA(0, 0, At, B0); PG8_BAR; PG8_SCHED;
;             PG8_LDB(B1, 1, 1); PG8_STAGE(PG8_SB(1, 0), b3, voffB);
;             PG8_BAR; PG8_WAIT_L(0); PG8_MMA(0, 1, At, B1); PG8_BAR;
;             PG8_LDA(At, 1, 1); PG8_STAGE(PG8_SA(1, 0), a3, voffA);
;             PG8_BAR; PG8_WAIT_L(0); PG8_MMA(1, 0, At, B0); PG8_BAR; PG8_SCHED;
;             PG8_STAGE(PG8_SB(1, 1), b3 + hstepB, voffB);
;             PG8_WAIT_V(6); PG8_BAR; PG8_MMA(1, 1, At, B1); PG8_BAR;
;     __device__ __forceinline__ void operator()(const AccT& acc, const Unit& u, int wr, int wc, int fr, int fq) const {
;         const int row0 = u.pm * BM + wr * 64 + fr, ch0 = u.pn * HALF + wc * 32 + 4 * fq;
; #pragma unroll
;         for (int n = 0; n < 2; ++n) {
;             u32x2 xw[2][4];
; #pragma unroll
;             for (int ai = 0; ai < 2; ++ai)
; #pragma unroll
;                 for (int m = 0; m < 4; ++m) xw[ai][m] = *(const u32x2*)(XC + (size_t)(row0 + ai * HALF + m * 16) * DM + ch0 + 16 * n);
;             const f32x4 bra = *(const f32x4*)(b_ra + ch0 + 16 * n), bri = *(const f32x4*)(b_ri + ch0 + 16 * n), l = *(const f32x4*)(lam + ch0 + 16 * n);
;             f32x4 sp;
; #pragma unroll
;             for (int j = 0; j < 4; ++j) sp[j] = -8.0f * log1pf(__expf(-l[j]));
	s_setprio 1
	v_mfma_f32_16x16x32_bf16 v[4:7], v[68:71], v[20:23], v[232:235]
	v_mfma_f32_16x16x32_bf16 v[100:103], v[72:75], v[28:31], v[4:7]
	v_mfma_f32_16x16x32_bf16 v[4:7], v[76:79], v[20:23], v[12:15]
	v_mfma_f32_16x16x32_bf16 v[28:31], v[190:193], v[28:31], v[4:7]
	v_mfma_f32_16x16x32_bf16 v[4:7], v[68:71], v[166:169], v[236:239]
	v_mfma_f32_16x16x32_bf16 v[92:95], v[72:75], v[170:173], v[4:7]
	v_mfma_f32_16x16x32_bf16 v[4:7], v[76:79], v[166:169], v[240:243]
	v_mfma_f32_16x16x32_bf16 v[20:23], v[190:193], v[170:173], v[4:7]
	v_mfma_f32_16x16x32_bf16 v[4:7], v[68:71], v[194:197], v[244:247]
	v_mfma_f32_16x16x32_bf16 v[84:87], v[72:75], v[202:205], v[4:7]
	v_mfma_f32_16x16x32_bf16 v[4:7], v[76:79], v[194:197], v[174:177]
	v_mfma_f32_16x16x32_bf16 v[12:15], v[190:193], v[202:205], v[4:7]
	v_mfma_f32_16x16x32_bf16 v[4:7], v[68:71], v[206:209], v[178:181]
	v_mfma_f32_16x16x32_bf16 v[68:71], v[72:75], v[248:251], v[4:7]
	v_mfma_f32_16x16x32_bf16 v[4:7], v[76:79], v[206:209], v[182:185]
	v_mfma_f32_16x16x32_bf16 v[4:7], v[190:193], v[248:251], v[4:7]
	s_setprio 0
	v_readlane_b32 s8, v254, 8
	v_lshl_or_b32 v72, s94, 7, v214
	v_readlane_b32 s12, v254, 12
	v_readlane_b32 s13, v254, 13
	v_readlane_b32 s14, v254, 14
	v_readlane_b32 s15, v254, 15
	v_readlane_b32 s20, v254, 20
	v_readlane_b32 s21, v254, 21
	v_ashrrev_i32_e32 v73, 31, v72
	v_readlane_b32 s22, v254, 22
	v_readlane_b32 s23, v254, 23
	s_mov_b64 s[12:13], s[20:21]
	v_lshlrev_b64 v[174:175], 2, v[72:73]
	s_mov_b64 s[14:15], s[22:23]
	v_lshl_add_u64 v[172:173], s[14:15], 0, v[174:175]
	global_load_dwordx4 v[136:139], v[172:173], off
	v_lshl_add_u32 v206, s62, 8, v212
	v_ashrrev_i32_e32 v207, 31, v206
	v_or_b32_e32 v202, 16, v206
	v_lshl_add_u64 v[74:75], v[72:73], 1, s[6:7]
	v_lshlrev_b64 v[76:77], 12, v[206:207]
	v_ashrrev_i32_e32 v203, 31, v202
	v_or_b32_e32 v196, 32, v206
	v_lshl_add_u64 v[154:155], v[74:75], 0, v[76:77]
	v_lshlrev_b64 v[76:77], 12, v[202:203]
	v_ashrrev_i32_e32 v197, 31, v196
	v_or_b32_e32 v192, 48, v206
	v_lshl_add_u64 v[156:157], v[74:75], 0, v[76:77]
	v_lshlrev_b64 v[76:77], 12, v[196:197]
	v_ashrrev_i32_e32 v193, 31, v192
	v_add_u32_e32 v188, 0x80, v206
	v_lshl_add_u64 v[158:159], v[74:75], 0, v[76:77]
	v_lshlrev_b64 v[76:77], 12, v[192:193]
	v_ashrrev_i32_e32 v189, 31, v188
	v_add_u32_e32 v184, 0x90, v206
	v_lshl_add_u64 v[160:161], v[74:75], 0, v[76:77]
	v_lshlrev_b64 v[76:77], 12, v[188:189]
	v_ashrrev_i32_e32 v185, 31, v184
	v_add_u32_e32 v180, 0xa0, v206
	v_lshl_add_u64 v[162:163], v[74:75], 0, v[76:77]
	v_lshlrev_b64 v[76:77], 12, v[184:185]
	v_ashrrev_i32_e32 v181, 31, v180
	v_add_u32_e32 v170, 0xb0, v206
	v_readlane_b32 s9, v254, 9
	v_readlane_b32 s16, v254, 16
	v_readlane_b32 s17, v254, 17
	v_lshl_add_u64 v[164:165], v[74:75], 0, v[76:77]
	v_lshlrev_b64 v[76:77], 12, v[180:181]
	v_ashrrev_i32_e32 v171, 31, v170
	s_mov_b64 s[8:9], s[16:17]
	v_lshl_add_u64 v[166:167], v[74:75], 0, v[76:77]
	v_lshlrev_b64 v[76:77], 12, v[170:171]
	v_lshl_add_u64 v[176:177], s[8:9], 0, v[174:175]
	v_lshl_add_u64 v[168:169], v[74:75], 0, v[76:77]
	global_load_dwordx4 v[76:79], v[176:177], off
	v_lshl_add_u64 v[178:179], s[12:13], 0, v[174:175]
	global_load_dwordx4 v[72:75], v[178:179], off
	global_load_dwordx2 v[210:211], v[154:155], off
	global_load_dwordx2 v[208:209], v[156:157], off
	global_load_dwordx2 v[204:205], v[158:159], off
	global_load_dwordx2 v[198:199], v[160:161], off
	global_load_dwordx2 v[194:195], v[162:163], off
	global_load_dwordx2 v[190:191], v[164:165], off
	global_load_dwordx2 v[186:187], v[166:167], off
	global_load_dwordx2 v[182:183], v[168:169], off
	v_readlane_b32 s96, v254, 58
	s_mov_b64 s[2:3], s[52:53]
	s_mov_b32 s94, s54
	s_mov_b32 s62, s56
	s_mov_b64 s[66:67], s[60:61]
	s_mov_b64 s[64:65], s[58:59]
	v_readlane_b32 s97, v254, 59
	v_readlane_b32 s10, v254, 10
	v_readlane_b32 s11, v254, 11
	v_readlane_b32 s18, v254, 18
	v_readlane_b32 s19, v254, 19
	s_barrier
	s_waitcnt vmcnt(0)
	v_mul_f32_e32 v136, 0xbfb8aa3b, v136
	v_exp_f32_e32 v136, v136
	v_mul_f32_e32 v137, 0xbfb8aa3b, v137
	v_exp_f32_e32 v137, v137
	v_mul_f32_e32 v138, 0xbfb8aa3b, v138
	v_add_f32_e32 v153, 1.0, v136
	v_add_f32_e32 v148, -1.0, v153
	v_sub_f32_e32 v149, v148, v153
	v_add_f32_e32 v149, 1.0, v149
	v_sub_f32_e32 v148, v136, v148
	v_add_f32_e32 v223, v148, v149
	v_frexp_mant_f32_e32 v148, v153
	v_cmp_gt_f32_e32 vcc, s76, v148
	v_cvt_f64_f32_e32 v[148:149], v153
	v_frexp_exp_i32_f64_e32 v148, v[148:149]
	v_subbrev_co_u32_e32 v230, vcc, 0, v148, vcc
	v_sub_u32_e32 v148, 0, v230
	v_ldexp_f32 v149, v153, v148
	v_add_f32_e32 v153, -1.0, v149
	v_add_f32_e32 v224, 1.0, v149
	v_ldexp_f32 v148, v223, v148
	v_add_f32_e32 v223, 1.0, v153
	v_add_f32_e32 v225, -1.0, v224
	v_sub_f32_e32 v223, v149, v223
	v_sub_f32_e32 v149, v149, v225
	v_add_f32_e32 v223, v148, v223
	v_add_f32_e32 v148, v148, v149
	v_add_f32_e32 v231, v224, v148
	v_rcp_f32_e32 v233, v231
	v_sub_f32_e32 v149, v231, v224
	v_sub_f32_e32 v232, v148, v149
	v_add_f32_e32 v149, v153, v223
	v_sub_f32_e32 v148, v149, v153
	v_sub_f32_e32 v153, v223, v148
	v_mul_f32_e32 v223, v149, v233
	v_mul_f32_e32 v224, v231, v223
	v_fma_f32 v226, v223, v231, -v224
	v_fmac_f32_e32 v226, v223, v232
	v_add_f32_e32 v148, v224, v226
	v_sub_f32_e32 v225, v149, v148
	v_pk_add_f32 v[228:229], v[148:149], v[224:225] neg_lo:[0,1] neg_hi:[0,1]
	v_mov_b32_e32 v227, v148
	v_pk_add_f32 v[148:149], v[228:229], v[226:227] neg_lo:[0,1] neg_hi:[0,1]
	v_cmp_neq_f32_e32 vcc, s78, v136
	v_add_f32_e32 v149, v153, v149
	v_add_f32_e32 v148, v148, v149
	v_add_f32_e32 v149, v225, v148
	v_mul_f32_e32 v153, v233, v149
	v_mul_f32_e32 v224, v231, v153
	v_fma_f32 v226, v153, v231, -v224
; __device__ __forceinline__ float bf_lo(unsigned w) { return __uint_as_float(w << 16); }
; __device__ __forceinline__ float bf_hi(unsigned w) { return __uint_as_float(w & 0xffff0000u); }
;     __device__ __forceinline__ void operator()(const AccT& acc, const Unit& u, int wr, int wc, int fr, int fq) const {
;     ...
;             for (int j = 0; j < 4; ++j) sp[j] = -8.0f * log1pf(__expf(-l[j]));
; #pragma unroll
;             for (int ai = 0; ai < 2; ++ai)
; #pragma unroll
;                 for (int m = 0; m < 4; ++m) { const size_t off = (size_t)(row0 + ai * HALF + m * 16) * DM + ch0 + 16 * n;
;                     const f32x4 rp = acc[ai][0][m][n] + bra, ip = acc[ai][1][m][n] + bri;
;                     const u32x2 w = xw[ai][m]; const float xv[4] = {bf_lo(w.x), bf_hi(w.x), bf_lo(w.y), bf_hi(w.y)};
;                     u32x4 o;
; #pragma unroll
;                     for (int j = 0; j < 4; ++j) { const float r = __builtin_amdgcn_rcpf(1.0f + __expf(-rp[j])), ig = __builtin_amdgcn_rcpf(1.0f + __expf(-ip[j])); const float la = sp[j] * r; const float d = 1.0f - __expf(la);
	v_fmac_f32_e32 v226, v153, v232
	v_sub_f32_e32 v225, v225, v149
	v_add_f32_e32 v231, v148, v225
	v_add_f32_e32 v148, v224, v226
	v_sub_f32_e32 v225, v149, v148
	v_pk_add_f32 v[228:229], v[148:149], v[224:225] neg_lo:[0,1] neg_hi:[0,1]
	v_mov_b32_e32 v227, v148
	v_pk_add_f32 v[148:149], v[228:229], v[226:227] neg_lo:[0,1] neg_hi:[0,1]
	v_exp_f32_e32 v138, v138
	v_add_f32_e32 v149, v231, v149
	v_add_f32_e32 v148, v148, v149
	v_add_f32_e32 v149, v223, v153
	v_add_f32_e32 v148, v225, v148
	v_sub_f32_e32 v223, v149, v223
	v_mul_f32_e32 v148, v233, v148
	v_sub_f32_e32 v153, v153, v223
	v_add_f32_e32 v223, v153, v148
	v_add_f32_e32 v224, v149, v223
	v_mul_f32_e32 v226, v224, v224
	v_fmamk_f32 v148, v226, 0x3e9b6dac, v218
	v_fmaak_f32 v153, v226, v148, 0x3f2aaada
	v_cvt_f32_i32_e32 v148, v230
	v_sub_f32_e32 v149, v224, v149
	v_sub_f32_e32 v149, v223, v149
	v_ldexp_f32 v223, v149, 1
	v_mul_f32_e32 v149, v224, v226
	v_pk_mul_f32 v[226:227], v[148:149], v[152:153]
	v_ldexp_f32 v225, v224, 1
	v_fma_f32 v224, v148, s77, -v226
	v_fmac_f32_e32 v224, 0xb102e308, v148
	v_pk_add_f32 v[148:149], v[226:227], v[224:225]
	v_mov_b32_e32 v228, v226
	v_sub_f32_e32 v153, v149, v225
	v_sub_f32_e32 v153, v227, v153
	v_add_f32_e32 v229, v223, v153
	v_pk_add_f32 v[226:227], v[148:149], v[226:227] neg_lo:[0,1] neg_hi:[0,1]
	v_pk_add_f32 v[230:231], v[148:149], v[228:229]
	v_mov_b32_e32 v225, v148
	v_mov_b32_e32 v227, v231
	v_pk_add_f32 v[232:233], v[224:225], v[226:227] neg_lo:[0,1] neg_hi:[0,1]
	v_pk_add_f32 v[224:225], v[224:225], v[226:227]
	v_mov_b32_e32 v228, v229
	v_pk_add_f32 v[226:227], v[224:225], v[148:149] op_sel:[1,0] op_sel_hi:[0,1] neg_lo:[0,1] neg_hi:[0,1]
	v_pk_add_f32 v[234:235], v[230:231], v[226:227] op_sel_hi:[1,0] neg_lo:[0,1] neg_hi:[0,1]
	v_mov_b32_e32 v230, v231
	v_mov_b32_e32 v231, v225
	v_pk_mov_b32 v[226:227], v[148:149], v[226:227] op_sel:[1,0]
	v_mov_b32_e32 v229, v148
	v_pk_add_f32 v[226:227], v[230:231], v[226:227] neg_lo:[0,1] neg_hi:[0,1]
	v_mov_b32_e32 v234, v232
	v_pk_add_f32 v[148:149], v[228:229], v[226:227] neg_lo:[0,1] neg_hi:[0,1]
	v_mov_b32_e32 v233, v225
	v_pk_add_f32 v[226:227], v[234:235], v[148:149]
	v_mul_f32_e32 v139, 0xbfb8aa3b, v139
	v_pk_add_f32 v[228:229], v[226:227], v[226:227] op_sel:[0,1] op_sel_hi:[1,0]
	v_exp_f32_e32 v139, v139
	v_pk_add_f32 v[224:225], v[224:225], v[228:229] op_sel:[1,0] op_sel_hi:[0,1]
	v_mov_b32_e32 v227, v224
	v_pk_add_f32 v[230:231], v[226:227], v[232:233] neg_lo:[0,1] neg_hi:[0,1]
	v_mov_b32_e32 v149, v228
	v_sub_f32_e32 v153, v226, v230
	v_pk_add_f32 v[148:149], v[148:149], v[230:231] neg_lo:[0,1] neg_hi:[0,1]
	v_sub_f32_e32 v153, v232, v153
	v_add_f32_e32 v148, v148, v153
	v_add_f32_e32 v148, v148, v149
	v_add_f32_e32 v148, v224, v148
	v_cndmask_b32_e32 v148, v219, v148, vcc
	v_cmp_ngt_f32_e32 vcc, -1.0, v136
	v_add_f32_e32 v153, 1.0, v137
	v_add_f32_e32 v128, v128, v76
	v_cndmask_b32_e32 v148, v220, v148, vcc
	v_cmp_neq_f32_e32 vcc, -1.0, v136
	v_mul_f32_e32 v128, 0xbfb8aa3b, v128
	v_exp_f32_e32 v128, v128
	v_cndmask_b32_e32 v148, v221, v148, vcc
	v_cmp_lt_f32_e64 vcc, |v136|, s79
	v_add_f32_e32 v132, v132, v72
	v_add_f32_e32 v128, 1.0, v128
	v_cndmask_b32_e32 v136, v148, v136, vcc
	v_add_f32_e32 v148, -1.0, v153
	v_sub_f32_e32 v149, v148, v153
	v_add_f32_e32 v149, 1.0, v149
	v_sub_f32_e32 v148, v137, v148
	v_add_f32_e32 v223, v148, v149
	v_frexp_mant_f32_e32 v148, v153
	v_cmp_gt_f32_e32 vcc, s76, v148
	v_cvt_f64_f32_e32 v[148:149], v153
	v_frexp_exp_i32_f64_e32 v148, v[148:149]
	v_subbrev_co_u32_e32 v230, vcc, 0, v148, vcc
	v_sub_u32_e32 v148, 0, v230
	v_ldexp_f32 v149, v153, v148
	v_add_f32_e32 v153, -1.0, v149
	v_add_f32_e32 v224, 1.0, v149
	v_ldexp_f32 v148, v223, v148
	v_add_f32_e32 v223, 1.0, v153
	v_add_f32_e32 v225, -1.0, v224
	v_sub_f32_e32 v223, v149, v223
	v_sub_f32_e32 v149, v149, v225
	v_add_f32_e32 v223, v148, v223
	v_add_f32_e32 v148, v148, v149
	v_add_f32_e32 v231, v224, v148
	v_rcp_f32_e32 v233, v231
	v_sub_f32_e32 v149, v231, v224
	v_sub_f32_e32 v232, v148, v149
	v_add_f32_e32 v149, v153, v223
	v_sub_f32_e32 v148, v149, v153
	v_sub_f32_e32 v153, v223, v148
	v_mul_f32_e32 v223, v149, v233
	v_mul_f32_e32 v224, v231, v223
	v_fma_f32 v226, v223, v231, -v224
	v_fmac_f32_e32 v226, v223, v232
	v_add_f32_e32 v148, v224, v226
	v_sub_f32_e32 v225, v149, v148
	v_pk_add_f32 v[228:229], v[148:149], v[224:225] neg_lo:[0,1] neg_hi:[0,1]
	v_mov_b32_e32 v227, v148
	v_pk_add_f32 v[148:149], v[228:229], v[226:227] neg_lo:[0,1] neg_hi:[0,1]
	v_cmp_neq_f32_e32 vcc, s78, v137
	v_add_f32_e32 v149, v153, v149
	v_add_f32_e32 v148, v148, v149
	v_add_f32_e32 v149, v225, v148
	v_mul_f32_e32 v153, v233, v149
	v_mul_f32_e32 v224, v231, v153
	v_fma_f32 v226, v153, v231, -v224
	v_fmac_f32_e32 v226, v153, v232
	v_sub_f32_e32 v225, v225, v149
	v_add_f32_e32 v231, v148, v225
	v_add_f32_e32 v148, v224, v226
	v_sub_f32_e32 v225, v149, v148
	v_pk_add_f32 v[228:229], v[148:149], v[224:225] neg_lo:[0,1] neg_hi:[0,1]
	v_mov_b32_e32 v227, v148
	v_pk_add_f32 v[148:149], v[228:229], v[226:227] neg_lo:[0,1] neg_hi:[0,1]
	v_rcp_f32_e32 v128, v128
	v_add_f32_e32 v149, v231, v149
	v_add_f32_e32 v148, v148, v149
	v_add_f32_e32 v149, v223, v153
	v_add_f32_e32 v148, v225, v148
	v_sub_f32_e32 v223, v149, v223
	v_mul_f32_e32 v148, v233, v148
	v_sub_f32_e32 v153, v153, v223
	v_add_f32_e32 v223, v153, v148
	v_add_f32_e32 v224, v149, v223
	v_mul_f32_e32 v226, v224, v224
	v_fmamk_f32 v148, v226, 0x3e9b6dac, v218
	v_fmaak_f32 v153, v226, v148, 0x3f2aaada
	v_cvt_f32_i32_e32 v148, v230
	v_sub_f32_e32 v149, v224, v149
	v_sub_f32_e32 v149, v223, v149
	v_ldexp_f32 v223, v149, 1
	v_mul_f32_e32 v149, v224, v226
; __device__ __forceinline__ float bf_lo(unsigned w) { return __uint_as_float(w << 16); }
; __device__ __forceinline__ float bf_hi(unsigned w) { return __uint_as_float(w & 0xffff0000u); }
;     __device__ __forceinline__ void operator()(const AccT& acc, const Unit& u, int wr, int wc, int fr, int fq) const {
;     ...
;             for (int j = 0; j < 4; ++j) sp[j] = -8.0f * log1pf(__expf(-l[j]));
; #pragma unroll
;             for (int ai = 0; ai < 2; ++ai)
; #pragma unroll
;                 for (int m = 0; m < 4; ++m) { const size_t off = (size_t)(row0 + ai * HALF + m * 16) * DM + ch0 + 16 * n;
;                     const f32x4 rp = acc[ai][0][m][n] + bra, ip = acc[ai][1][m][n] + bri;
;                     const u32x2 w = xw[ai][m]; const float xv[4] = {bf_lo(w.x), bf_hi(w.x), bf_lo(w.y), bf_hi(w.y)};
;                     u32x4 o;
; #pragma unroll
;                     for (int j = 0; j < 4; ++j) { const float r = __builtin_amdgcn_rcpf(1.0f + __expf(-rp[j])), ig = __builtin_amdgcn_rcpf(1.0f + __expf(-ip[j])); const float la = sp[j] * r; const float d = 1.0f - __expf(la);
	v_pk_mul_f32 v[226:227], v[148:149], v[152:153]
	v_ldexp_f32 v225, v224, 1
	v_fma_f32 v224, v148, s77, -v226
	v_fmac_f32_e32 v224, 0xb102e308, v148
	v_pk_add_f32 v[148:149], v[226:227], v[224:225]
	v_mov_b32_e32 v228, v226
	v_sub_f32_e32 v153, v149, v225
	v_sub_f32_e32 v153, v227, v153
	v_add_f32_e32 v229, v223, v153
	v_pk_add_f32 v[226:227], v[148:149], v[226:227] neg_lo:[0,1] neg_hi:[0,1]
	v_pk_add_f32 v[230:231], v[148:149], v[228:229]
	v_mov_b32_e32 v225, v148
	v_mov_b32_e32 v227, v231
	v_pk_add_f32 v[232:233], v[224:225], v[226:227] neg_lo:[0,1] neg_hi:[0,1]
	v_pk_add_f32 v[224:225], v[224:225], v[226:227]
	v_mov_b32_e32 v228, v229
	v_pk_add_f32 v[226:227], v[224:225], v[148:149] op_sel:[1,0] op_sel_hi:[0,1] neg_lo:[0,1] neg_hi:[0,1]
	v_pk_add_f32 v[234:235], v[230:231], v[226:227] op_sel_hi:[1,0] neg_lo:[0,1] neg_hi:[0,1]
	v_mov_b32_e32 v230, v231
	v_mov_b32_e32 v231, v225
	v_pk_mov_b32 v[226:227], v[148:149], v[226:227] op_sel:[1,0]
	v_mov_b32_e32 v229, v148
	v_pk_add_f32 v[226:227], v[230:231], v[226:227] neg_lo:[0,1] neg_hi:[0,1]
	v_mov_b32_e32 v234, v232
	v_pk_add_f32 v[148:149], v[228:229], v[226:227] neg_lo:[0,1] neg_hi:[0,1]
	v_mov_b32_e32 v233, v225
	v_pk_add_f32 v[226:227], v[234:235], v[148:149]
	v_mul_f32_e32 v136, 0xc1000000, v136
	v_pk_add_f32 v[228:229], v[226:227], v[226:227] op_sel:[0,1] op_sel_hi:[1,0]
	v_mul_f32_e32 v128, v128, v136
	v_pk_add_f32 v[224:225], v[224:225], v[228:229] op_sel:[1,0] op_sel_hi:[0,1]
	v_mov_b32_e32 v227, v224
	v_pk_add_f32 v[230:231], v[226:227], v[232:233] neg_lo:[0,1] neg_hi:[0,1]
	v_mov_b32_e32 v149, v228
	v_sub_f32_e32 v153, v226, v230
	v_pk_add_f32 v[148:149], v[148:149], v[230:231] neg_lo:[0,1] neg_hi:[0,1]
	v_sub_f32_e32 v153, v232, v153
	v_add_f32_e32 v148, v148, v153
	v_add_f32_e32 v148, v148, v149
	v_add_f32_e32 v148, v224, v148
	v_cndmask_b32_e32 v148, v219, v148, vcc
	v_cmp_ngt_f32_e32 vcc, -1.0, v137
	v_add_f32_e32 v153, 1.0, v138
	v_mul_f32_e32 v128, 0x3fb8aa3b, v128
	v_cndmask_b32_e32 v148, v220, v148, vcc
	v_cmp_neq_f32_e32 vcc, -1.0, v137
	v_exp_f32_e32 v128, v128
	v_mul_f32_e32 v132, 0xbfb8aa3b, v132
	v_cndmask_b32_e32 v148, v221, v148, vcc
	v_cmp_lt_f32_e64 vcc, |v137|, s79
	v_exp_f32_e32 v132, v132
	v_sub_f32_e32 v128, 1.0, v128
	v_cndmask_b32_e32 v137, v148, v137, vcc
	v_add_f32_e32 v148, -1.0, v153
	v_sub_f32_e32 v149, v148, v153
	v_add_f32_e32 v149, 1.0, v149
	v_sub_f32_e32 v148, v138, v148
	v_add_f32_e32 v223, v148, v149
	v_frexp_mant_f32_e32 v148, v153
	v_cmp_gt_f32_e32 vcc, s76, v148
	v_cvt_f64_f32_e32 v[148:149], v153
	v_frexp_exp_i32_f64_e32 v148, v[148:149]
	v_subbrev_co_u32_e32 v230, vcc, 0, v148, vcc
	v_sub_u32_e32 v148, 0, v230
	v_ldexp_f32 v149, v153, v148
	v_add_f32_e32 v153, -1.0, v149
	v_add_f32_e32 v224, 1.0, v149
	v_ldexp_f32 v148, v223, v148
	v_add_f32_e32 v223, 1.0, v153
	v_add_f32_e32 v225, -1.0, v224
	v_sub_f32_e32 v223, v149, v223
	v_sub_f32_e32 v149, v149, v225
	v_add_f32_e32 v223, v148, v223
	v_add_f32_e32 v148, v148, v149
	v_add_f32_e32 v231, v224, v148
	v_rcp_f32_e32 v233, v231
	v_sub_f32_e32 v149, v231, v224
	v_sub_f32_e32 v232, v148, v149
	v_add_f32_e32 v149, v153, v223
	v_sub_f32_e32 v148, v149, v153
	v_sub_f32_e32 v153, v223, v148
	v_mul_f32_e32 v223, v149, v233
	v_mul_f32_e32 v224, v231, v223
	v_fma_f32 v226, v223, v231, -v224
	v_fmac_f32_e32 v226, v223, v232
	v_add_f32_e32 v148, v224, v226
	v_sub_f32_e32 v225, v149, v148
	v_pk_add_f32 v[228:229], v[148:149], v[224:225] neg_lo:[0,1] neg_hi:[0,1]
	v_mov_b32_e32 v227, v148
	v_pk_add_f32 v[148:149], v[228:229], v[226:227] neg_lo:[0,1] neg_hi:[0,1]
	v_cmp_neq_f32_e32 vcc, s78, v138
	v_add_f32_e32 v149, v153, v149
	v_add_f32_e32 v148, v148, v149
	v_add_f32_e32 v149, v225, v148
	v_mul_f32_e32 v153, v233, v149
	v_mul_f32_e32 v224, v231, v153
	v_fma_f32 v226, v153, v231, -v224
	v_fmac_f32_e32 v226, v153, v232
	v_sub_f32_e32 v225, v225, v149
	v_add_f32_e32 v231, v148, v225
	v_add_f32_e32 v148, v224, v226
	v_sub_f32_e32 v225, v149, v148
	v_pk_add_f32 v[228:229], v[148:149], v[224:225] neg_lo:[0,1] neg_hi:[0,1]
	v_mov_b32_e32 v227, v148
	v_pk_add_f32 v[148:149], v[228:229], v[226:227] neg_lo:[0,1] neg_hi:[0,1]
	v_add_f32_e32 v132, 1.0, v132
	v_add_f32_e32 v149, v231, v149
	v_add_f32_e32 v148, v148, v149
	v_add_f32_e32 v149, v223, v153
	v_add_f32_e32 v148, v225, v148
	v_sub_f32_e32 v223, v149, v223
	v_mul_f32_e32 v148, v233, v148
	v_sub_f32_e32 v153, v153, v223
	v_add_f32_e32 v223, v153, v148
	v_add_f32_e32 v224, v149, v223
	v_mul_f32_e32 v226, v224, v224
	v_fmamk_f32 v148, v226, 0x3e9b6dac, v218
	v_fmaak_f32 v153, v226, v148, 0x3f2aaada
	v_cvt_f32_i32_e32 v148, v230
	v_sub_f32_e32 v149, v224, v149
	v_sub_f32_e32 v149, v223, v149
	v_ldexp_f32 v223, v149, 1
	v_mul_f32_e32 v149, v224, v226
	v_pk_mul_f32 v[226:227], v[148:149], v[152:153]
	v_ldexp_f32 v225, v224, 1
	v_fma_f32 v224, v148, s77, -v226
	v_fmac_f32_e32 v224, 0xb102e308, v148
	v_pk_add_f32 v[148:149], v[226:227], v[224:225]
	v_mov_b32_e32 v228, v226
	v_sub_f32_e32 v153, v149, v225
	v_sub_f32_e32 v153, v227, v153
	v_add_f32_e32 v229, v223, v153
	v_pk_add_f32 v[226:227], v[148:149], v[226:227] neg_lo:[0,1] neg_hi:[0,1]
	v_pk_add_f32 v[230:231], v[148:149], v[228:229]
	v_mov_b32_e32 v225, v148
	v_mov_b32_e32 v227, v231
	v_pk_add_f32 v[232:233], v[224:225], v[226:227] neg_lo:[0,1] neg_hi:[0,1]
	v_pk_add_f32 v[224:225], v[224:225], v[226:227]
	v_mov_b32_e32 v228, v229
	v_pk_add_f32 v[226:227], v[224:225], v[148:149] op_sel:[1,0] op_sel_hi:[0,1] neg_lo:[0,1] neg_hi:[0,1]
	v_pk_add_f32 v[234:235], v[230:231], v[226:227] op_sel_hi:[1,0] neg_lo:[0,1] neg_hi:[0,1]
	v_mov_b32_e32 v230, v231
	v_mov_b32_e32 v231, v225
	v_pk_mov_b32 v[226:227], v[148:149], v[226:227] op_sel:[1,0]
; __device__ __forceinline__ float bf_lo(unsigned w) { return __uint_as_float(w << 16); }
; __device__ __forceinline__ float bf_hi(unsigned w) { return __uint_as_float(w & 0xffff0000u); }
;     __device__ __forceinline__ void operator()(const AccT& acc, const Unit& u, int wr, int wc, int fr, int fq) const {
;     ...
;             for (int j = 0; j < 4; ++j) sp[j] = -8.0f * log1pf(__expf(-l[j]));
; #pragma unroll
;             for (int ai = 0; ai < 2; ++ai)
; #pragma unroll
;                 for (int m = 0; m < 4; ++m) { const size_t off = (size_t)(row0 + ai * HALF + m * 16) * DM + ch0 + 16 * n;
;                     const f32x4 rp = acc[ai][0][m][n] + bra, ip = acc[ai][1][m][n] + bri;
;                     const u32x2 w = xw[ai][m]; const float xv[4] = {bf_lo(w.x), bf_hi(w.x), bf_lo(w.y), bf_hi(w.y)};
;                     u32x4 o;
; #pragma unroll
;                     for (int j = 0; j < 4; ++j) { const float r = __builtin_amdgcn_rcpf(1.0f + __expf(-rp[j])), ig = __builtin_amdgcn_rcpf(1.0f + __expf(-ip[j])); const float la = sp[j] * r; const float d = 1.0f - __expf(la);
	v_mov_b32_e32 v229, v148
	v_pk_add_f32 v[226:227], v[230:231], v[226:227] neg_lo:[0,1] neg_hi:[0,1]
	v_mov_b32_e32 v234, v232
	v_pk_add_f32 v[148:149], v[228:229], v[226:227] neg_lo:[0,1] neg_hi:[0,1]
	v_mov_b32_e32 v233, v225
	v_pk_add_f32 v[226:227], v[234:235], v[148:149]
	v_rcp_f32_e32 v132, v132
	v_pk_add_f32 v[228:229], v[226:227], v[226:227] op_sel:[0,1] op_sel_hi:[1,0]
	v_mul_f32_e32 v137, 0xc1000000, v137
	v_pk_add_f32 v[224:225], v[224:225], v[228:229] op_sel:[1,0] op_sel_hi:[0,1]
	v_mov_b32_e32 v227, v224
	v_pk_add_f32 v[230:231], v[226:227], v[232:233] neg_lo:[0,1] neg_hi:[0,1]
	v_mov_b32_e32 v149, v228
	v_sub_f32_e32 v153, v226, v230
	v_pk_add_f32 v[148:149], v[148:149], v[230:231] neg_lo:[0,1] neg_hi:[0,1]
	v_sub_f32_e32 v153, v232, v153
	v_add_f32_e32 v148, v148, v153
	v_add_f32_e32 v148, v148, v149
	v_add_f32_e32 v148, v224, v148
	v_cndmask_b32_e32 v148, v219, v148, vcc
	v_cmp_ngt_f32_e32 vcc, -1.0, v138
	v_add_f32_e32 v153, 1.0, v139
	v_add_f32_e32 v120, v120, v76
	v_cndmask_b32_e32 v148, v220, v148, vcc
	v_cmp_neq_f32_e32 vcc, -1.0, v138
	v_mul_f32_e32 v120, 0xbfb8aa3b, v120
	v_exp_f32_e32 v120, v120
	v_cndmask_b32_e32 v148, v221, v148, vcc
	v_cmp_lt_f32_e64 vcc, |v138|, s79
	v_add_f32_e32 v124, v124, v72
	v_add_f32_e32 v120, 1.0, v120
	v_cndmask_b32_e32 v138, v148, v138, vcc
	v_add_f32_e32 v148, -1.0, v153
	v_sub_f32_e32 v149, v148, v153
	v_add_f32_e32 v149, 1.0, v149
	v_sub_f32_e32 v148, v139, v148
	v_add_f32_e32 v223, v148, v149
	v_frexp_mant_f32_e32 v148, v153
	v_cmp_gt_f32_e32 vcc, s76, v148
	v_cvt_f64_f32_e32 v[148:149], v153
	v_frexp_exp_i32_f64_e32 v148, v[148:149]
	v_subbrev_co_u32_e32 v230, vcc, 0, v148, vcc
	v_sub_u32_e32 v148, 0, v230
	v_ldexp_f32 v149, v153, v148
	v_add_f32_e32 v153, -1.0, v149
	v_add_f32_e32 v224, 1.0, v149
	v_ldexp_f32 v148, v223, v148
	v_add_f32_e32 v223, 1.0, v153
	v_add_f32_e32 v225, -1.0, v224
	v_sub_f32_e32 v223, v149, v223
	v_sub_f32_e32 v149, v149, v225
	v_add_f32_e32 v223, v148, v223
	v_add_f32_e32 v148, v148, v149
	v_add_f32_e32 v231, v224, v148
	v_rcp_f32_e32 v233, v231
	v_sub_f32_e32 v149, v231, v224
	v_sub_f32_e32 v232, v148, v149
	v_add_f32_e32 v149, v153, v223
	v_sub_f32_e32 v148, v149, v153
	v_sub_f32_e32 v153, v223, v148
	v_mul_f32_e32 v223, v149, v233
	v_mul_f32_e32 v224, v231, v223
	v_fma_f32 v226, v223, v231, -v224
	v_fmac_f32_e32 v226, v223, v232
	v_add_f32_e32 v148, v224, v226
	v_sub_f32_e32 v225, v149, v148
	v_pk_add_f32 v[228:229], v[148:149], v[224:225] neg_lo:[0,1] neg_hi:[0,1]
	v_mov_b32_e32 v227, v148
	v_pk_add_f32 v[148:149], v[228:229], v[226:227] neg_lo:[0,1] neg_hi:[0,1]
	v_cmp_neq_f32_e32 vcc, s78, v139
	v_add_f32_e32 v149, v153, v149
	v_add_f32_e32 v148, v148, v149
	v_add_f32_e32 v149, v225, v148
	v_mul_f32_e32 v153, v233, v149
	v_mul_f32_e32 v224, v231, v153
	v_fma_f32 v226, v153, v231, -v224
	v_fmac_f32_e32 v226, v153, v232
	v_sub_f32_e32 v225, v225, v149
	v_add_f32_e32 v231, v148, v225
	v_add_f32_e32 v148, v224, v226
	v_sub_f32_e32 v225, v149, v148
	v_pk_add_f32 v[228:229], v[148:149], v[224:225] neg_lo:[0,1] neg_hi:[0,1]
	v_mov_b32_e32 v227, v148
	v_pk_add_f32 v[148:149], v[228:229], v[226:227] neg_lo:[0,1] neg_hi:[0,1]
	v_mul_f32_e32 v138, 0xc1000000, v138
	v_add_f32_e32 v149, v231, v149
	v_add_f32_e32 v148, v148, v149
	v_add_f32_e32 v149, v223, v153
	v_add_f32_e32 v148, v225, v148
	v_sub_f32_e32 v223, v149, v223
	v_mul_f32_e32 v148, v233, v148
	v_sub_f32_e32 v153, v153, v223
	v_add_f32_e32 v223, v153, v148
	v_add_f32_e32 v224, v149, v223
	v_mul_f32_e32 v226, v224, v224
	v_fmamk_f32 v148, v226, 0x3e9b6dac, v218
	v_fmaak_f32 v153, v226, v148, 0x3f2aaada
	v_cvt_f32_i32_e32 v148, v230
	v_sub_f32_e32 v149, v224, v149
	v_sub_f32_e32 v149, v223, v149
	v_ldexp_f32 v223, v149, 1
	v_mul_f32_e32 v149, v224, v226
	v_pk_mul_f32 v[226:227], v[148:149], v[152:153]
	v_ldexp_f32 v225, v224, 1
	v_fma_f32 v224, v148, s77, -v226
	v_fmac_f32_e32 v224, 0xb102e308, v148
	v_pk_add_f32 v[148:149], v[226:227], v[224:225]
	v_mov_b32_e32 v228, v226
	v_sub_f32_e32 v153, v149, v225
	v_sub_f32_e32 v153, v227, v153
	v_add_f32_e32 v229, v223, v153
	v_pk_add_f32 v[226:227], v[148:149], v[226:227] neg_lo:[0,1] neg_hi:[0,1]
	v_pk_add_f32 v[230:231], v[148:149], v[228:229]
	v_mov_b32_e32 v225, v148
	v_mov_b32_e32 v227, v231
	v_pk_add_f32 v[232:233], v[224:225], v[226:227] neg_lo:[0,1] neg_hi:[0,1]
	v_pk_add_f32 v[224:225], v[224:225], v[226:227]
	v_mov_b32_e32 v228, v229
	v_pk_add_f32 v[226:227], v[224:225], v[148:149] op_sel:[1,0] op_sel_hi:[0,1] neg_lo:[0,1] neg_hi:[0,1]
	v_pk_add_f32 v[234:235], v[230:231], v[226:227] op_sel_hi:[1,0] neg_lo:[0,1] neg_hi:[0,1]
	v_mov_b32_e32 v230, v231
	v_mov_b32_e32 v231, v225
	v_pk_mov_b32 v[226:227], v[148:149], v[226:227] op_sel:[1,0]
	v_mov_b32_e32 v229, v148
	v_pk_add_f32 v[226:227], v[230:231], v[226:227] neg_lo:[0,1] neg_hi:[0,1]
	v_mov_b32_e32 v234, v232
	v_pk_add_f32 v[148:149], v[228:229], v[226:227] neg_lo:[0,1] neg_hi:[0,1]
	v_mov_b32_e32 v233, v225
	v_pk_add_f32 v[226:227], v[234:235], v[148:149]
	v_rcp_f32_e32 v120, v120
	v_pk_add_f32 v[228:229], v[226:227], v[226:227] op_sel:[0,1] op_sel_hi:[1,0]
	v_mul_f32_e32 v124, 0xbfb8aa3b, v124
	v_pk_add_f32 v[224:225], v[224:225], v[228:229] op_sel:[1,0] op_sel_hi:[0,1]
	v_mov_b32_e32 v227, v224
	v_pk_add_f32 v[230:231], v[226:227], v[232:233] neg_lo:[0,1] neg_hi:[0,1]
	v_mov_b32_e32 v149, v228
	v_sub_f32_e32 v153, v226, v230
	v_pk_add_f32 v[148:149], v[148:149], v[230:231] neg_lo:[0,1] neg_hi:[0,1]
	v_sub_f32_e32 v153, v232, v153
	v_add_f32_e32 v148, v148, v153
	v_add_f32_e32 v148, v148, v149
	v_add_f32_e32 v148, v224, v148
	v_cndmask_b32_e32 v148, v219, v148, vcc
	v_cmp_ngt_f32_e32 vcc, -1.0, v139
; __device__ __forceinline__ unsigned cvt_pk_bf16(float lo, float hi) { const bf16x2_t r = __builtin_convertvector((f32x2){lo, hi}, bf16x2_t); return __builtin_bit_cast(unsigned, r); }
; __device__ __forceinline__ float bf_lo(unsigned w) { return __uint_as_float(w << 16); }
; __device__ __forceinline__ float bf_hi(unsigned w) { return __uint_as_float(w & 0xffff0000u); }
;     __device__ __forceinline__ void operator()(const AccT& acc, const Unit& u, int wr, int wc, int fr, int fq) const {
;     ...
;             for (int ai = 0; ai < 2; ++ai)
; #pragma unroll
;                 for (int m = 0; m < 4; ++m) { const size_t off = (size_t)(row0 + ai * HALF + m * 16) * DM + ch0 + 16 * n;
;                     const f32x4 rp = acc[ai][0][m][n] + bra, ip = acc[ai][1][m][n] + bri;
;                     const u32x2 w = xw[ai][m]; const float xv[4] = {bf_lo(w.x), bf_hi(w.x), bf_lo(w.y), bf_hi(w.y)};
;                     u32x4 o;
; #pragma unroll
;                     for (int j = 0; j < 4; ++j) { const float r = __builtin_amdgcn_rcpf(1.0f + __expf(-rp[j])), ig = __builtin_amdgcn_rcpf(1.0f + __expf(-ip[j])); const float la = sp[j] * r; const float d = 1.0f - __expf(la);
;                         o[j] = cvt_pk_bf16(d, __builtin_amdgcn_sqrtf(fmaxf(d * (2.0f - d), 0.f)) * (ig * xv[j])); }
;                     *(u32x4*)(AU + off) = o; }
	v_and_b32_e32 v149, 0xffff0000, v210
	v_lshlrev_b32_e32 v153, 16, v211
	v_cndmask_b32_e32 v148, v220, v148, vcc
	v_cmp_neq_f32_e32 vcc, -1.0, v139
	v_mul_f32_e32 v120, v120, v136
	v_mul_f32_e32 v120, 0x3fb8aa3b, v120
	v_cndmask_b32_e32 v148, v221, v148, vcc
	v_cmp_lt_f32_e64 vcc, |v139|, s79
	v_exp_f32_e32 v120, v120
	v_exp_f32_e32 v124, v124
	v_cndmask_b32_e32 v139, v148, v139, vcc
	v_lshlrev_b32_e32 v148, 16, v210
	v_and_b32_e32 v210, 0xffff0000, v211
	v_sub_f32_e32 v211, 2.0, v128
	v_mul_f32_e32 v211, v128, v211
	v_max_f32_e32 v211, 0, v211
	v_sqrt_f32_e32 v211, v211
	v_mul_f32_e32 v132, v132, v148
	v_mul_f32_e32 v139, 0xc1000000, v139
	v_sub_f32_e32 v120, 1.0, v120
	v_mul_f32_e32 v132, v132, v211
	v_cvt_pk_bf16_f32 v132, v128, v132
	v_add_f32_e32 v128, v129, v77
	v_mul_f32_e32 v128, 0xbfb8aa3b, v128
	v_exp_f32_e32 v128, v128
	v_add_f32_e32 v129, v133, v73
	v_mul_f32_e32 v129, 0xbfb8aa3b, v129
	v_exp_f32_e32 v129, v129
	v_add_f32_e32 v128, 1.0, v128
	v_rcp_f32_e32 v128, v128
	v_add_f32_e32 v124, 1.0, v124
	v_add_f32_e32 v129, 1.0, v129
	v_rcp_f32_e32 v129, v129
	v_mul_f32_e32 v128, v128, v137
	v_mul_f32_e32 v128, 0x3fb8aa3b, v128
	v_exp_f32_e32 v128, v128
	v_mul_f32_e32 v129, v129, v149
	v_rcp_f32_e32 v124, v124
	v_add_f32_e32 v112, v112, v76
	v_sub_f32_e32 v128, 1.0, v128
	v_sub_f32_e32 v133, 2.0, v128
	v_mul_f32_e32 v133, v128, v133
	v_max_f32_e32 v133, 0, v133
	v_sqrt_f32_e32 v133, v133
	v_mul_f32_e32 v112, 0xbfb8aa3b, v112
	v_exp_f32_e32 v112, v112
	v_add_f32_e32 v116, v116, v72
	v_mul_f32_e32 v129, v129, v133
	v_cvt_pk_bf16_f32 v133, v128, v129
	v_add_f32_e32 v128, v130, v78
	v_mul_f32_e32 v128, 0xbfb8aa3b, v128
	v_exp_f32_e32 v128, v128
	v_add_f32_e32 v129, v134, v74
	v_mul_f32_e32 v129, 0xbfb8aa3b, v129
	v_exp_f32_e32 v129, v129
	v_add_f32_e32 v128, 1.0, v128
	v_rcp_f32_e32 v128, v128
	v_add_f32_e32 v112, 1.0, v112
	v_add_f32_e32 v129, 1.0, v129
	v_rcp_f32_e32 v129, v129
	v_mul_f32_e32 v128, v128, v138
	v_mul_f32_e32 v128, 0x3fb8aa3b, v128
	v_exp_f32_e32 v128, v128
	v_mul_f32_e32 v129, v129, v153
	v_rcp_f32_e32 v112, v112
	v_mul_f32_e32 v116, 0xbfb8aa3b, v116
	v_sub_f32_e32 v128, 1.0, v128
	v_sub_f32_e32 v130, 2.0, v128
	v_mul_f32_e32 v130, v128, v130
	v_max_f32_e32 v130, 0, v130
	v_sqrt_f32_e32 v130, v130
	v_mul_f32_e32 v112, v112, v136
	v_mul_f32_e32 v112, 0x3fb8aa3b, v112
	v_exp_f32_e32 v112, v112
	v_mul_f32_e32 v129, v129, v130
	v_cvt_pk_bf16_f32 v134, v128, v129
	v_add_f32_e32 v128, v131, v79
	v_mul_f32_e32 v128, 0xbfb8aa3b, v128
	v_exp_f32_e32 v128, v128
	v_add_f32_e32 v129, v135, v75
	v_mul_f32_e32 v129, 0xbfb8aa3b, v129
	v_exp_f32_e32 v129, v129
	v_add_f32_e32 v128, 1.0, v128
	v_rcp_f32_e32 v128, v128
	v_and_b32_e32 v131, 0xffff0000, v208
	v_add_f32_e32 v129, 1.0, v129
	v_rcp_f32_e32 v129, v129
	v_mul_f32_e32 v128, v128, v139
	v_mul_f32_e32 v128, 0x3fb8aa3b, v128
	v_exp_f32_e32 v128, v128
	v_mul_f32_e32 v129, v129, v210
	v_exp_f32_e32 v116, v116
	v_sub_f32_e32 v112, 1.0, v112
	v_sub_f32_e32 v128, 1.0, v128
	v_sub_f32_e32 v130, 2.0, v128
	v_mul_f32_e32 v130, v128, v130
	v_max_f32_e32 v130, 0, v130
	v_sqrt_f32_e32 v130, v130
	v_add_f32_e32 v116, 1.0, v116
	v_rcp_f32_e32 v116, v116
	v_add_f32_e32 v104, v104, v76
	v_mul_f32_e32 v129, v129, v130
	v_cvt_pk_bf16_f32 v135, v128, v129
	v_lshlrev_b64 v[128:129], 13, v[206:207]
	v_lshl_add_u64 v[128:129], s[42:43], 0, v[128:129]
	v_lshl_add_u64 v[128:129], v[128:129], 0, v[174:175]
	global_store_dwordx4 v[128:129], v[132:135], off
	v_lshlrev_b32_e32 v130, 16, v208
	v_mul_f32_e32 v124, v124, v130
	v_sub_f32_e32 v134, 2.0, v120
	v_mul_f32_e32 v134, v120, v134
	v_max_f32_e32 v134, 0, v134
	v_sqrt_f32_e32 v134, v134
	v_lshlrev_b32_e32 v132, 16, v209
	v_and_b32_e32 v133, 0xffff0000, v209
	v_mul_f32_e32 v104, 0xbfb8aa3b, v104
	v_mul_f32_e32 v124, v124, v134
	v_cvt_pk_bf16_f32 v124, v120, v124
	v_add_f32_e32 v120, v121, v77
	v_mul_f32_e32 v120, 0xbfb8aa3b, v120
	v_exp_f32_e32 v120, v120
	v_add_f32_e32 v121, v125, v73
	v_mul_f32_e32 v121, 0xbfb8aa3b, v121
	v_exp_f32_e32 v121, v121
	v_add_f32_e32 v120, 1.0, v120
	v_rcp_f32_e32 v120, v120
	v_exp_f32_e32 v104, v104
	v_add_f32_e32 v121, 1.0, v121
	v_rcp_f32_e32 v121, v121
	v_mul_f32_e32 v120, v120, v137
	v_mul_f32_e32 v120, 0x3fb8aa3b, v120
	v_exp_f32_e32 v120, v120
	v_mul_f32_e32 v121, v121, v131
	v_add_f32_e32 v104, 1.0, v104
	v_rcp_f32_e32 v104, v104
	v_sub_f32_e32 v120, 1.0, v120
	v_sub_f32_e32 v125, 2.0, v120
	v_mul_f32_e32 v125, v120, v125
	v_max_f32_e32 v125, 0, v125
	v_sqrt_f32_e32 v125, v125
	v_mul_f32_e32 v104, v104, v136
	v_mul_f32_e32 v104, 0x3fb8aa3b, v104
	v_add_f32_e32 v108, v108, v72
	v_mul_f32_e32 v121, v121, v125
	v_cvt_pk_bf16_f32 v125, v120, v121
	v_add_f32_e32 v120, v122, v78
	v_mul_f32_e32 v120, 0xbfb8aa3b, v120
	v_exp_f32_e32 v120, v120
	v_add_f32_e32 v121, v126, v74
	v_mul_f32_e32 v121, 0xbfb8aa3b, v121
	v_exp_f32_e32 v121, v121
	v_add_f32_e32 v120, 1.0, v120
	v_rcp_f32_e32 v120, v120
	v_exp_f32_e32 v104, v104
	v_add_f32_e32 v121, 1.0, v121
	v_rcp_f32_e32 v121, v121
	v_mul_f32_e32 v120, v120, v138
	v_mul_f32_e32 v120, 0x3fb8aa3b, v120
	v_exp_f32_e32 v120, v120
	v_mul_f32_e32 v121, v121, v132
	v_mul_f32_e32 v108, 0xbfb8aa3b, v108
	v_exp_f32_e32 v108, v108
	v_sub_f32_e32 v120, 1.0, v120
	v_sub_f32_e32 v122, 2.0, v120
	v_mul_f32_e32 v122, v120, v122
	v_max_f32_e32 v122, 0, v122
	v_sqrt_f32_e32 v122, v122
	v_sub_f32_e32 v104, 1.0, v104
	v_add_f32_e32 v108, 1.0, v108
	v_rcp_f32_e32 v108, v108
	v_mul_f32_e32 v121, v121, v122
	v_cvt_pk_bf16_f32 v126, v120, v121
	v_add_f32_e32 v120, v123, v79
	v_mul_f32_e32 v120, 0xbfb8aa3b, v120
	v_exp_f32_e32 v120, v120
	v_add_f32_e32 v121, v127, v75
	v_mul_f32_e32 v121, 0xbfb8aa3b, v121
; __device__ __forceinline__ unsigned cvt_pk_bf16(float lo, float hi) { const bf16x2_t r = __builtin_convertvector((f32x2){lo, hi}, bf16x2_t); return __builtin_bit_cast(unsigned, r); }
; __device__ __forceinline__ float bf_lo(unsigned w) { return __uint_as_float(w << 16); }
; __device__ __forceinline__ float bf_hi(unsigned w) { return __uint_as_float(w & 0xffff0000u); }
;     __device__ __forceinline__ void operator()(const AccT& acc, const Unit& u, int wr, int wc, int fr, int fq) const {
;     ...
;             for (int ai = 0; ai < 2; ++ai)
; #pragma unroll
;                 for (int m = 0; m < 4; ++m) { const size_t off = (size_t)(row0 + ai * HALF + m * 16) * DM + ch0 + 16 * n;
;                     const f32x4 rp = acc[ai][0][m][n] + bra, ip = acc[ai][1][m][n] + bri;
;                     const u32x2 w = xw[ai][m]; const float xv[4] = {bf_lo(w.x), bf_hi(w.x), bf_lo(w.y), bf_hi(w.y)};
;                     u32x4 o;
; #pragma unroll
;                     for (int j = 0; j < 4; ++j) { const float r = __builtin_amdgcn_rcpf(1.0f + __expf(-rp[j])), ig = __builtin_amdgcn_rcpf(1.0f + __expf(-ip[j])); const float la = sp[j] * r; const float d = 1.0f - __expf(la);
;                         o[j] = cvt_pk_bf16(d, __builtin_amdgcn_sqrtf(fmaxf(d * (2.0f - d), 0.f)) * (ig * xv[j])); }
;                     *(u32x4*)(AU + off) = o; }
	v_exp_f32_e32 v121, v121
	v_add_f32_e32 v120, 1.0, v120
	v_rcp_f32_e32 v120, v120
	v_and_b32_e32 v123, 0xffff0000, v204
	v_add_f32_e32 v121, 1.0, v121
	v_rcp_f32_e32 v121, v121
	v_mul_f32_e32 v120, v120, v139
	v_mul_f32_e32 v120, 0x3fb8aa3b, v120
	v_exp_f32_e32 v120, v120
	v_mul_f32_e32 v121, v121, v133
	v_add_f32_e32 v96, v96, v76
	v_mul_f32_e32 v96, 0xbfb8aa3b, v96
	v_sub_f32_e32 v120, 1.0, v120
	v_sub_f32_e32 v122, 2.0, v120
	v_mul_f32_e32 v122, v120, v122
	v_max_f32_e32 v122, 0, v122
	v_sqrt_f32_e32 v122, v122
	v_exp_f32_e32 v96, v96
	v_add_f32_e32 v100, v100, v72
	v_mul_f32_e32 v100, 0xbfb8aa3b, v100
	v_mul_f32_e32 v121, v121, v122
	v_cvt_pk_bf16_f32 v127, v120, v121
	v_lshlrev_b64 v[120:121], 13, v[202:203]
	v_lshl_add_u64 v[120:121], s[42:43], 0, v[120:121]
	v_lshl_add_u64 v[120:121], v[120:121], 0, v[174:175]
	global_store_dwordx4 v[120:121], v[124:127], off
	v_lshlrev_b32_e32 v122, 16, v204
	v_mul_f32_e32 v116, v116, v122
	v_sub_f32_e32 v126, 2.0, v112
	v_mul_f32_e32 v126, v112, v126
	v_max_f32_e32 v126, 0, v126
	v_sqrt_f32_e32 v126, v126
	v_lshlrev_b32_e32 v124, 16, v205
	v_and_b32_e32 v125, 0xffff0000, v205
	v_add_f32_e32 v96, 1.0, v96
	v_mul_f32_e32 v116, v116, v126
	v_cvt_pk_bf16_f32 v116, v112, v116
	v_add_f32_e32 v112, v113, v77
	v_mul_f32_e32 v112, 0xbfb8aa3b, v112
	v_exp_f32_e32 v112, v112
	v_add_f32_e32 v113, v117, v73
	v_mul_f32_e32 v113, 0xbfb8aa3b, v113
	v_exp_f32_e32 v113, v113
	v_add_f32_e32 v112, 1.0, v112
	v_rcp_f32_e32 v112, v112
	v_rcp_f32_e32 v96, v96
	v_add_f32_e32 v113, 1.0, v113
	v_rcp_f32_e32 v113, v113
	v_mul_f32_e32 v112, v112, v137
	v_mul_f32_e32 v112, 0x3fb8aa3b, v112
	v_exp_f32_e32 v112, v112
	v_mul_f32_e32 v113, v113, v123
	v_mul_f32_e32 v96, v96, v136
	v_mul_f32_e32 v96, 0x3fb8aa3b, v96
	v_sub_f32_e32 v112, 1.0, v112
	v_sub_f32_e32 v117, 2.0, v112
	v_mul_f32_e32 v117, v112, v117
	v_max_f32_e32 v117, 0, v117
	v_sqrt_f32_e32 v117, v117
	v_exp_f32_e32 v96, v96
	v_exp_f32_e32 v100, v100
	v_add_f32_e32 v88, v88, v76
	v_mul_f32_e32 v113, v113, v117
	v_cvt_pk_bf16_f32 v117, v112, v113
	v_add_f32_e32 v112, v114, v78
	v_mul_f32_e32 v112, 0xbfb8aa3b, v112
	v_exp_f32_e32 v112, v112
	v_add_f32_e32 v113, v118, v74
	v_mul_f32_e32 v113, 0xbfb8aa3b, v113
	v_exp_f32_e32 v113, v113
	v_add_f32_e32 v112, 1.0, v112
	v_rcp_f32_e32 v112, v112
	v_sub_f32_e32 v96, 1.0, v96
	v_add_f32_e32 v113, 1.0, v113
	v_rcp_f32_e32 v113, v113
	v_mul_f32_e32 v112, v112, v138
	v_mul_f32_e32 v112, 0x3fb8aa3b, v112
	v_exp_f32_e32 v112, v112
	v_mul_f32_e32 v113, v113, v124
	v_add_f32_e32 v100, 1.0, v100
	v_rcp_f32_e32 v100, v100
	v_sub_f32_e32 v112, 1.0, v112
	v_sub_f32_e32 v114, 2.0, v112
	v_mul_f32_e32 v114, v112, v114
	v_max_f32_e32 v114, 0, v114
	v_sqrt_f32_e32 v114, v114
	v_mul_f32_e32 v88, 0xbfb8aa3b, v88
	v_exp_f32_e32 v88, v88
	v_add_f32_e32 v92, v92, v72
	v_mul_f32_e32 v113, v113, v114
	v_cvt_pk_bf16_f32 v118, v112, v113
	v_add_f32_e32 v112, v115, v79
	v_mul_f32_e32 v112, 0xbfb8aa3b, v112
	v_exp_f32_e32 v112, v112
	v_add_f32_e32 v113, v119, v75
	v_mul_f32_e32 v113, 0xbfb8aa3b, v113
	v_exp_f32_e32 v113, v113
	v_add_f32_e32 v112, 1.0, v112
	v_rcp_f32_e32 v112, v112
	v_and_b32_e32 v115, 0xffff0000, v198
	v_add_f32_e32 v113, 1.0, v113
	v_rcp_f32_e32 v113, v113
	v_mul_f32_e32 v112, v112, v139
	v_mul_f32_e32 v112, 0x3fb8aa3b, v112
	v_exp_f32_e32 v112, v112
	v_mul_f32_e32 v113, v113, v125
	v_add_f32_e32 v88, 1.0, v88
	v_rcp_f32_e32 v88, v88
	v_sub_f32_e32 v112, 1.0, v112
	v_sub_f32_e32 v114, 2.0, v112
	v_mul_f32_e32 v114, v112, v114
	v_max_f32_e32 v114, 0, v114
	v_sqrt_f32_e32 v114, v114
	v_mul_f32_e32 v88, v88, v136
	v_mul_f32_e32 v88, 0x3fb8aa3b, v88
	v_exp_f32_e32 v88, v88
	v_mul_f32_e32 v113, v113, v114
	v_cvt_pk_bf16_f32 v119, v112, v113
	v_lshlrev_b64 v[112:113], 13, v[196:197]
	v_lshl_add_u64 v[112:113], s[42:43], 0, v[112:113]
	v_lshl_add_u64 v[112:113], v[112:113], 0, v[174:175]
	global_store_dwordx4 v[112:113], v[116:119], off
	v_lshlrev_b32_e32 v114, 16, v198
	v_mul_f32_e32 v108, v108, v114
	v_sub_f32_e32 v118, 2.0, v104
	v_mul_f32_e32 v118, v104, v118
	v_max_f32_e32 v118, 0, v118
	v_sqrt_f32_e32 v118, v118
	v_lshlrev_b32_e32 v116, 16, v199
	v_and_b32_e32 v117, 0xffff0000, v199
	v_mul_f32_e32 v92, 0xbfb8aa3b, v92
	v_mul_f32_e32 v108, v108, v118
	v_cvt_pk_bf16_f32 v108, v104, v108
	v_add_f32_e32 v104, v105, v77
	v_mul_f32_e32 v104, 0xbfb8aa3b, v104
	v_exp_f32_e32 v104, v104
	v_add_f32_e32 v105, v109, v73
	v_mul_f32_e32 v105, 0xbfb8aa3b, v105
	v_exp_f32_e32 v105, v105
	v_add_f32_e32 v104, 1.0, v104
	v_rcp_f32_e32 v104, v104
	v_exp_f32_e32 v92, v92
	v_add_f32_e32 v105, 1.0, v105
	v_rcp_f32_e32 v105, v105
	v_mul_f32_e32 v104, v104, v137
	v_mul_f32_e32 v104, 0x3fb8aa3b, v104
	v_exp_f32_e32 v104, v104
	v_mul_f32_e32 v105, v105, v115
	v_sub_f32_e32 v88, 1.0, v88
	v_add_f32_e32 v92, 1.0, v92
	v_sub_f32_e32 v104, 1.0, v104
	v_sub_f32_e32 v109, 2.0, v104
	v_mul_f32_e32 v109, v104, v109
	v_max_f32_e32 v109, 0, v109
	v_sqrt_f32_e32 v109, v109
	v_rcp_f32_e32 v92, v92
	v_add_f32_e32 v80, v80, v76
	v_mul_f32_e32 v80, 0xbfb8aa3b, v80
	v_mul_f32_e32 v105, v105, v109
	v_cvt_pk_bf16_f32 v109, v104, v105
	v_add_f32_e32 v104, v106, v78
	v_mul_f32_e32 v104, 0xbfb8aa3b, v104
	v_exp_f32_e32 v104, v104
	v_add_f32_e32 v105, v110, v74
	v_mul_f32_e32 v105, 0xbfb8aa3b, v105
	v_exp_f32_e32 v105, v105
	v_add_f32_e32 v104, 1.0, v104
	v_rcp_f32_e32 v104, v104
	v_exp_f32_e32 v80, v80
	v_add_f32_e32 v105, 1.0, v105
	v_rcp_f32_e32 v105, v105
	v_mul_f32_e32 v104, v104, v138
	v_mul_f32_e32 v104, 0x3fb8aa3b, v104
	v_exp_f32_e32 v104, v104
	v_mul_f32_e32 v105, v105, v116
	v_add_f32_e32 v80, 1.0, v80
	v_rcp_f32_e32 v80, v80
	v_sub_f32_e32 v104, 1.0, v104
; __device__ __forceinline__ unsigned cvt_pk_bf16(float lo, float hi) { const bf16x2_t r = __builtin_convertvector((f32x2){lo, hi}, bf16x2_t); return __builtin_bit_cast(unsigned, r); }
; __device__ __forceinline__ float bf_lo(unsigned w) { return __uint_as_float(w << 16); }
; __device__ __forceinline__ float bf_hi(unsigned w) { return __uint_as_float(w & 0xffff0000u); }
;     __device__ __forceinline__ void operator()(const AccT& acc, const Unit& u, int wr, int wc, int fr, int fq) const {
;     ...
;                 for (int m = 0; m < 4; ++m) xw[ai][m] = *(const u32x2*)(XC + (size_t)(row0 + ai * HALF + m * 16) * DM + ch0 + 16 * n);
;             const f32x4 bra = *(const f32x4*)(b_ra + ch0 + 16 * n), bri = *(const f32x4*)(b_ri + ch0 + 16 * n), l = *(const f32x4*)(lam + ch0 + 16 * n);
;             f32x4 sp;
; #pragma unroll
;             for (int j = 0; j < 4; ++j) sp[j] = -8.0f * log1pf(__expf(-l[j]));
; #pragma unroll
;             for (int ai = 0; ai < 2; ++ai)
; #pragma unroll
;                 for (int m = 0; m < 4; ++m) { const size_t off = (size_t)(row0 + ai * HALF + m * 16) * DM + ch0 + 16 * n;
;                     const f32x4 rp = acc[ai][0][m][n] + bra, ip = acc[ai][1][m][n] + bri;
;                     const u32x2 w = xw[ai][m]; const float xv[4] = {bf_lo(w.x), bf_hi(w.x), bf_lo(w.y), bf_hi(w.y)};
;                     u32x4 o;
; #pragma unroll
;                     for (int j = 0; j < 4; ++j) { const float r = __builtin_amdgcn_rcpf(1.0f + __expf(-rp[j])), ig = __builtin_amdgcn_rcpf(1.0f + __expf(-ip[j])); const float la = sp[j] * r; const float d = 1.0f - __expf(la);
;                         o[j] = cvt_pk_bf16(d, __builtin_amdgcn_sqrtf(fmaxf(d * (2.0f - d), 0.f)) * (ig * xv[j])); }
;                     *(u32x4*)(AU + off) = o; }
	v_sub_f32_e32 v106, 2.0, v104
	v_mul_f32_e32 v106, v104, v106
	v_max_f32_e32 v106, 0, v106
	v_sqrt_f32_e32 v106, v106
	v_mul_f32_e32 v80, v80, v136
	v_mul_f32_e32 v80, 0x3fb8aa3b, v80
	v_add_f32_e32 v84, v84, v72
	v_mul_f32_e32 v105, v105, v106
	v_cvt_pk_bf16_f32 v110, v104, v105
	v_add_f32_e32 v104, v107, v79
	v_mul_f32_e32 v104, 0xbfb8aa3b, v104
	v_exp_f32_e32 v104, v104
	v_add_f32_e32 v105, v111, v75
	v_mul_f32_e32 v105, 0xbfb8aa3b, v105
	v_exp_f32_e32 v105, v105
	v_add_f32_e32 v104, 1.0, v104
	v_rcp_f32_e32 v104, v104
	v_and_b32_e32 v107, 0xffff0000, v194
	v_add_f32_e32 v105, 1.0, v105
	v_rcp_f32_e32 v105, v105
	v_mul_f32_e32 v104, v104, v139
	v_mul_f32_e32 v104, 0x3fb8aa3b, v104
	v_exp_f32_e32 v104, v104
	v_mul_f32_e32 v105, v105, v117
	v_exp_f32_e32 v80, v80
	v_mul_f32_e32 v84, 0xbfb8aa3b, v84
	v_sub_f32_e32 v104, 1.0, v104
	v_sub_f32_e32 v106, 2.0, v104
	v_mul_f32_e32 v106, v104, v106
	v_max_f32_e32 v106, 0, v106
	v_sqrt_f32_e32 v106, v106
	v_exp_f32_e32 v84, v84
	v_sub_f32_e32 v80, 1.0, v80
	v_add_f32_e32 v64, v64, v76
	v_mul_f32_e32 v105, v105, v106
	v_cvt_pk_bf16_f32 v111, v104, v105
	v_lshlrev_b64 v[104:105], 13, v[192:193]
	v_lshl_add_u64 v[104:105], s[42:43], 0, v[104:105]
	v_lshl_add_u64 v[104:105], v[104:105], 0, v[174:175]
	global_store_dwordx4 v[104:105], v[108:111], off
	global_load_dwordx2 v[114:115], v[154:155], off offset:32
	global_load_dwordx2 v[122:123], v[156:157], off offset:32
	global_load_dwordx2 v[148:149], v[158:159], off offset:32
	global_load_dwordx2 v[192:193], v[160:161], off offset:32
	global_load_dwordx2 v[202:203], v[162:163], off offset:32
	global_load_dwordx2 v[208:209], v[164:165], off offset:32
	global_load_dwordx2 v[210:211], v[166:167], off offset:32
	global_load_dwordx2 v[224:225], v[168:169], off offset:32
	global_load_dwordx4 v[116:119], v[176:177], off offset:64
	global_load_dwordx4 v[196:199], v[178:179], off offset:64
	global_load_dwordx4 v[204:207], v[172:173], off offset:64
	v_lshlrev_b32_e32 v106, 16, v194
	v_mul_f32_e32 v100, v100, v106
	v_sub_f32_e32 v110, 2.0, v96
	v_mul_f32_e32 v110, v96, v110
	v_max_f32_e32 v110, 0, v110
	v_sqrt_f32_e32 v110, v110
	v_lshlrev_b32_e32 v108, 16, v195
	v_and_b32_e32 v109, 0xffff0000, v195
	v_add_f32_e32 v84, 1.0, v84
	v_mul_f32_e32 v100, v100, v110
	v_cvt_pk_bf16_f32 v100, v96, v100
	v_add_f32_e32 v96, v97, v77
	v_mul_f32_e32 v96, 0xbfb8aa3b, v96
	v_exp_f32_e32 v96, v96
	v_add_f32_e32 v97, v101, v73
	v_mul_f32_e32 v97, 0xbfb8aa3b, v97
	v_exp_f32_e32 v97, v97
	v_add_f32_e32 v96, 1.0, v96
	v_rcp_f32_e32 v96, v96
	v_rcp_f32_e32 v84, v84
	v_add_f32_e32 v97, 1.0, v97
	v_rcp_f32_e32 v97, v97
	v_mul_f32_e32 v96, v96, v137
	v_mul_f32_e32 v96, 0x3fb8aa3b, v96
	v_exp_f32_e32 v96, v96
	v_mul_f32_e32 v97, v97, v107
	v_mul_f32_e32 v64, 0xbfb8aa3b, v64
	v_exp_f32_e32 v64, v64
	v_sub_f32_e32 v96, 1.0, v96
	v_sub_f32_e32 v101, 2.0, v96
	v_mul_f32_e32 v101, v96, v101
	v_max_f32_e32 v101, 0, v101
	v_sqrt_f32_e32 v101, v101
	v_add_f32_e32 v64, 1.0, v64
	v_rcp_f32_e32 v64, v64
	v_add_f32_e32 v68, v68, v72
	v_mul_f32_e32 v97, v97, v101
	v_cvt_pk_bf16_f32 v101, v96, v97
	v_add_f32_e32 v96, v98, v78
	v_mul_f32_e32 v96, 0xbfb8aa3b, v96
	v_exp_f32_e32 v96, v96
	v_add_f32_e32 v97, v102, v74
	v_mul_f32_e32 v97, 0xbfb8aa3b, v97
	v_exp_f32_e32 v97, v97
	v_add_f32_e32 v96, 1.0, v96
	v_rcp_f32_e32 v96, v96
	v_mul_f32_e32 v64, v64, v136
	v_add_f32_e32 v97, 1.0, v97
	v_rcp_f32_e32 v97, v97
	v_mul_f32_e32 v96, v96, v138
	v_mul_f32_e32 v96, 0x3fb8aa3b, v96
	v_exp_f32_e32 v96, v96
	v_mul_f32_e32 v97, v97, v108
	v_mul_f32_e32 v64, 0x3fb8aa3b, v64
	v_exp_f32_e32 v64, v64
	v_sub_f32_e32 v96, 1.0, v96
	v_sub_f32_e32 v98, 2.0, v96
	v_mul_f32_e32 v98, v96, v98
	v_max_f32_e32 v98, 0, v98
	v_sqrt_f32_e32 v98, v98
	v_add_f32_e32 v65, v65, v77
	v_mul_f32_e32 v68, 0xbfb8aa3b, v68
	v_mul_f32_e32 v65, 0xbfb8aa3b, v65
	v_mul_f32_e32 v97, v97, v98
	v_cvt_pk_bf16_f32 v102, v96, v97
	v_add_f32_e32 v96, v99, v79
	v_mul_f32_e32 v96, 0xbfb8aa3b, v96
	v_exp_f32_e32 v96, v96
	v_add_f32_e32 v97, v103, v75
	v_mul_f32_e32 v97, 0xbfb8aa3b, v97
	v_exp_f32_e32 v97, v97
	v_add_f32_e32 v96, 1.0, v96
	v_rcp_f32_e32 v96, v96
	v_and_b32_e32 v99, 0xffff0000, v190
	v_add_f32_e32 v97, 1.0, v97
	v_rcp_f32_e32 v97, v97
	v_mul_f32_e32 v96, v96, v139
	v_mul_f32_e32 v96, 0x3fb8aa3b, v96
	v_exp_f32_e32 v96, v96
	v_mul_f32_e32 v97, v97, v109
	v_exp_f32_e32 v68, v68
	v_exp_f32_e32 v65, v65
	v_sub_f32_e32 v96, 1.0, v96
	v_sub_f32_e32 v98, 2.0, v96
	v_mul_f32_e32 v98, v96, v98
	v_max_f32_e32 v98, 0, v98
	v_sqrt_f32_e32 v98, v98
	v_sub_f32_e32 v64, 1.0, v64
	v_sub_f32_e32 v72, 2.0, v64
	v_add_f32_e32 v68, 1.0, v68
	v_mul_f32_e32 v97, v97, v98
	v_cvt_pk_bf16_f32 v103, v96, v97
	v_lshlrev_b64 v[96:97], 13, v[188:189]
	v_lshl_add_u64 v[96:97], s[42:43], 0, v[96:97]
	v_lshl_add_u64 v[96:97], v[96:97], 0, v[174:175]
	global_store_dwordx4 v[96:97], v[100:103], off
	v_lshlrev_b32_e32 v98, 16, v190
	v_mul_f32_e32 v92, v92, v98
	v_sub_f32_e32 v102, 2.0, v88
	v_mul_f32_e32 v102, v88, v102
	v_max_f32_e32 v102, 0, v102
	v_sqrt_f32_e32 v102, v102
	v_lshlrev_b32_e32 v100, 16, v191
	v_and_b32_e32 v101, 0xffff0000, v191
	v_mul_f32_e32 v72, v64, v72
	v_mul_f32_e32 v92, v92, v102
	v_cvt_pk_bf16_f32 v92, v88, v92
	v_add_f32_e32 v88, v89, v77
	v_mul_f32_e32 v88, 0xbfb8aa3b, v88
	v_exp_f32_e32 v88, v88
	v_add_f32_e32 v89, v93, v73
	v_mul_f32_e32 v89, 0xbfb8aa3b, v89
	v_exp_f32_e32 v89, v89
	v_add_f32_e32 v88, 1.0, v88
	v_rcp_f32_e32 v88, v88
	v_add_f32_e32 v65, 1.0, v65
	v_add_f32_e32 v89, 1.0, v89
	v_rcp_f32_e32 v89, v89
	v_mul_f32_e32 v88, v88, v137
	v_mul_f32_e32 v88, 0x3fb8aa3b, v88
	v_exp_f32_e32 v88, v88
	v_mul_f32_e32 v89, v89, v99
; __device__ __forceinline__ unsigned cvt_pk_bf16(float lo, float hi) { const bf16x2_t r = __builtin_convertvector((f32x2){lo, hi}, bf16x2_t); return __builtin_bit_cast(unsigned, r); }
; __device__ __forceinline__ float bf_lo(unsigned w) { return __uint_as_float(w << 16); }
; __device__ __forceinline__ float bf_hi(unsigned w) { return __uint_as_float(w & 0xffff0000u); }
;     __device__ __forceinline__ void operator()(const AccT& acc, const Unit& u, int wr, int wc, int fr, int fq) const {
;     ...
;                 for (int m = 0; m < 4; ++m) xw[ai][m] = *(const u32x2*)(XC + (size_t)(row0 + ai * HALF + m * 16) * DM + ch0 + 16 * n);
;             const f32x4 bra = *(const f32x4*)(b_ra + ch0 + 16 * n), bri = *(const f32x4*)(b_ri + ch0 + 16 * n), l = *(const f32x4*)(lam + ch0 + 16 * n);
;             f32x4 sp;
; #pragma unroll
;             for (int j = 0; j < 4; ++j) sp[j] = -8.0f * log1pf(__expf(-l[j]));
; #pragma unroll
;             for (int ai = 0; ai < 2; ++ai)
; #pragma unroll
;                 for (int m = 0; m < 4; ++m) { const size_t off = (size_t)(row0 + ai * HALF + m * 16) * DM + ch0 + 16 * n;
;                     const f32x4 rp = acc[ai][0][m][n] + bra, ip = acc[ai][1][m][n] + bri;
;                     const u32x2 w = xw[ai][m]; const float xv[4] = {bf_lo(w.x), bf_hi(w.x), bf_lo(w.y), bf_hi(w.y)};
;                     u32x4 o;
; #pragma unroll
;                     for (int j = 0; j < 4; ++j) { const float r = __builtin_amdgcn_rcpf(1.0f + __expf(-rp[j])), ig = __builtin_amdgcn_rcpf(1.0f + __expf(-ip[j])); const float la = sp[j] * r; const float d = 1.0f - __expf(la);
;                         o[j] = cvt_pk_bf16(d, __builtin_amdgcn_sqrtf(fmaxf(d * (2.0f - d), 0.f)) * (ig * xv[j])); }
;                     *(u32x4*)(AU + off) = o; }
	v_rcp_f32_e32 v68, v68
	v_max_f32_e32 v72, 0, v72
	v_sub_f32_e32 v88, 1.0, v88
	v_sub_f32_e32 v93, 2.0, v88
	v_mul_f32_e32 v93, v88, v93
	v_max_f32_e32 v93, 0, v93
	v_sqrt_f32_e32 v93, v93
	v_rcp_f32_e32 v65, v65
	v_sqrt_f32_e32 v72, v72
	v_add_f32_e32 v66, v66, v78
	v_mul_f32_e32 v89, v89, v93
	v_cvt_pk_bf16_f32 v93, v88, v89
	v_add_f32_e32 v88, v90, v78
	v_mul_f32_e32 v88, 0xbfb8aa3b, v88
	v_exp_f32_e32 v88, v88
	v_add_f32_e32 v89, v94, v74
	v_mul_f32_e32 v89, 0xbfb8aa3b, v89
	v_exp_f32_e32 v89, v89
	v_add_f32_e32 v88, 1.0, v88
	v_rcp_f32_e32 v88, v88
	v_mul_f32_e32 v65, v65, v137
	v_add_f32_e32 v89, 1.0, v89
	v_rcp_f32_e32 v89, v89
	v_mul_f32_e32 v88, v88, v138
	v_mul_f32_e32 v88, 0x3fb8aa3b, v88
	v_exp_f32_e32 v88, v88
	v_mul_f32_e32 v89, v89, v100
	v_mul_f32_e32 v65, 0x3fb8aa3b, v65
	v_exp_f32_e32 v65, v65
	v_sub_f32_e32 v88, 1.0, v88
	v_sub_f32_e32 v90, 2.0, v88
	v_mul_f32_e32 v90, v88, v90
	v_max_f32_e32 v90, 0, v90
	v_sqrt_f32_e32 v90, v90
	v_mul_f32_e32 v66, 0xbfb8aa3b, v66
	v_exp_f32_e32 v66, v66
	v_sub_f32_e32 v65, 1.0, v65
	v_mul_f32_e32 v89, v89, v90
	v_cvt_pk_bf16_f32 v94, v88, v89
	v_add_f32_e32 v88, v91, v79
	v_mul_f32_e32 v88, 0xbfb8aa3b, v88
	v_exp_f32_e32 v88, v88
	v_add_f32_e32 v89, v95, v75
	v_mul_f32_e32 v89, 0xbfb8aa3b, v89
	v_exp_f32_e32 v89, v89
	v_add_f32_e32 v88, 1.0, v88
	v_rcp_f32_e32 v88, v88
	v_and_b32_e32 v91, 0xffff0000, v186
	v_add_f32_e32 v89, 1.0, v89
	v_rcp_f32_e32 v89, v89
	v_mul_f32_e32 v88, v88, v139
	v_mul_f32_e32 v88, 0x3fb8aa3b, v88
	v_exp_f32_e32 v88, v88
	v_mul_f32_e32 v89, v89, v101
	v_add_f32_e32 v66, 1.0, v66
	v_rcp_f32_e32 v66, v66
	v_sub_f32_e32 v88, 1.0, v88
	v_sub_f32_e32 v90, 2.0, v88
	v_mul_f32_e32 v90, v88, v90
	v_max_f32_e32 v90, 0, v90
	v_sqrt_f32_e32 v90, v90
	v_mul_f32_e32 v66, v66, v138
	v_mul_f32_e32 v66, 0x3fb8aa3b, v66
	v_exp_f32_e32 v66, v66
	v_mul_f32_e32 v89, v89, v90
	v_cvt_pk_bf16_f32 v95, v88, v89
	v_lshlrev_b64 v[88:89], 13, v[184:185]
	v_lshl_add_u64 v[88:89], s[42:43], 0, v[88:89]
	v_lshl_add_u64 v[88:89], v[88:89], 0, v[174:175]
	global_store_dwordx4 v[88:89], v[92:95], off
	v_lshlrev_b32_e32 v90, 16, v186
	v_mul_f32_e32 v84, v84, v90
	v_sub_f32_e32 v94, 2.0, v80
	v_mul_f32_e32 v94, v80, v94
	v_max_f32_e32 v94, 0, v94
	v_sqrt_f32_e32 v94, v94
	v_lshlrev_b32_e32 v92, 16, v187
	v_and_b32_e32 v93, 0xffff0000, v187
	v_add_f32_e32 v67, v67, v79
	v_mul_f32_e32 v84, v84, v94
	v_cvt_pk_bf16_f32 v84, v80, v84
	v_add_f32_e32 v80, v81, v77
	v_mul_f32_e32 v80, 0xbfb8aa3b, v80
	v_exp_f32_e32 v80, v80
	v_add_f32_e32 v81, v85, v73
	v_mul_f32_e32 v81, 0xbfb8aa3b, v81
	v_exp_f32_e32 v81, v81
	v_add_f32_e32 v80, 1.0, v80
	v_rcp_f32_e32 v80, v80
	v_mul_f32_e32 v67, 0xbfb8aa3b, v67
	v_add_f32_e32 v81, 1.0, v81
	v_rcp_f32_e32 v81, v81
	v_mul_f32_e32 v80, v80, v137
	v_mul_f32_e32 v80, 0x3fb8aa3b, v80
	v_exp_f32_e32 v80, v80
	v_mul_f32_e32 v81, v81, v91
	v_exp_f32_e32 v67, v67
	v_sub_f32_e32 v66, 1.0, v66
	v_sub_f32_e32 v80, 1.0, v80
	v_sub_f32_e32 v85, 2.0, v80
	v_mul_f32_e32 v85, v80, v85
	v_max_f32_e32 v85, 0, v85
	v_sqrt_f32_e32 v85, v85
	v_add_f32_e32 v67, 1.0, v67
	v_rcp_f32_e32 v67, v67
	v_mul_f32_e32 v81, v81, v85
	v_cvt_pk_bf16_f32 v85, v80, v81
	v_add_f32_e32 v80, v82, v78
	v_mul_f32_e32 v80, 0xbfb8aa3b, v80
	v_exp_f32_e32 v80, v80
	v_add_f32_e32 v81, v86, v74
	v_mul_f32_e32 v81, 0xbfb8aa3b, v81
	v_exp_f32_e32 v81, v81
	v_add_f32_e32 v80, 1.0, v80
	v_rcp_f32_e32 v80, v80
	v_mul_f32_e32 v67, v67, v139
	v_add_f32_e32 v81, 1.0, v81
	v_rcp_f32_e32 v81, v81
	v_mul_f32_e32 v80, v80, v138
	v_mul_f32_e32 v80, 0x3fb8aa3b, v80
	v_exp_f32_e32 v80, v80
	v_mul_f32_e32 v81, v81, v92
	v_mul_f32_e32 v67, 0x3fb8aa3b, v67
	v_exp_f32_e32 v67, v67
	v_sub_f32_e32 v80, 1.0, v80
	v_sub_f32_e32 v82, 2.0, v80
	v_mul_f32_e32 v82, v80, v82
	v_max_f32_e32 v82, 0, v82
	v_sqrt_f32_e32 v82, v82
	v_sub_f32_e32 v67, 1.0, v67
	v_mul_f32_e32 v81, v81, v82
	v_cvt_pk_bf16_f32 v86, v80, v81
	v_add_f32_e32 v80, v83, v79
	v_mul_f32_e32 v80, 0xbfb8aa3b, v80
	v_exp_f32_e32 v80, v80
	v_add_f32_e32 v81, v87, v75
	v_mul_f32_e32 v81, 0xbfb8aa3b, v81
	v_exp_f32_e32 v81, v81
	v_add_f32_e32 v80, 1.0, v80
	v_rcp_f32_e32 v80, v80
	v_and_b32_e32 v83, 0xffff0000, v182
	v_add_f32_e32 v81, 1.0, v81
	v_rcp_f32_e32 v81, v81
	v_mul_f32_e32 v80, v80, v139
	v_mul_f32_e32 v80, 0x3fb8aa3b, v80
	v_exp_f32_e32 v80, v80
	v_mul_f32_e32 v81, v81, v93
	v_sub_f32_e32 v80, 1.0, v80
	v_sub_f32_e32 v82, 2.0, v80
	v_mul_f32_e32 v82, v80, v82
	v_max_f32_e32 v82, 0, v82
	v_sqrt_f32_e32 v82, v82
	s_nop 0
	v_mul_f32_e32 v81, v81, v82
	v_lshlrev_b32_e32 v82, 16, v182
	v_mul_f32_e32 v68, v68, v82
	v_mul_f32_e32 v68, v68, v72
	v_cvt_pk_bf16_f32 v64, v64, v68
	v_add_f32_e32 v68, v69, v73
	v_mul_f32_e32 v68, 0xbfb8aa3b, v68
	v_exp_f32_e32 v68, v68
	v_sub_f32_e32 v69, 2.0, v65
	v_mul_f32_e32 v69, v65, v69
	v_max_f32_e32 v69, 0, v69
	v_add_f32_e32 v68, 1.0, v68
	v_rcp_f32_e32 v68, v68
	v_sqrt_f32_e32 v69, v69
	v_cvt_pk_bf16_f32 v87, v80, v81
	v_lshlrev_b64 v[80:81], 13, v[180:181]
	v_mul_f32_e32 v68, v68, v83
	v_mul_f32_e32 v68, v68, v69
	v_cvt_pk_bf16_f32 v65, v65, v68
	v_add_f32_e32 v68, v70, v74
	v_mul_f32_e32 v68, 0xbfb8aa3b, v68
	v_exp_f32_e32 v68, v68
	v_sub_f32_e32 v69, 2.0, v66
	v_mul_f32_e32 v69, v66, v69
	v_max_f32_e32 v69, 0, v69
	v_add_f32_e32 v68, 1.0, v68
	v_rcp_f32_e32 v68, v68
	v_lshl_add_u64 v[80:81], s[42:43], 0, v[80:81]
	v_sqrt_f32_e32 v69, v69
	v_lshl_add_u64 v[80:81], v[80:81], 0, v[174:175]
	global_store_dwordx4 v[80:81], v[84:87], off
	s_nop 1
	v_lshlrev_b32_e32 v84, 16, v183
	v_mul_f32_e32 v68, v68, v84
	v_mul_f32_e32 v68, v68, v69
	v_cvt_pk_bf16_f32 v66, v66, v68
	v_add_f32_e32 v68, v71, v75
	v_mul_f32_e32 v68, 0xbfb8aa3b, v68
	v_exp_f32_e32 v68, v68
	v_sub_f32_e32 v69, 2.0, v67
	v_mul_f32_e32 v69, v67, v69
	v_max_f32_e32 v69, 0, v69
	v_add_f32_e32 v68, 1.0, v68
	v_rcp_f32_e32 v68, v68
	v_sqrt_f32_e32 v69, v69
	v_and_b32_e32 v85, 0xffff0000, v183
	v_mul_f32_e32 v68, v68, v85
	v_mul_f32_e32 v68, v68, v69
	v_cvt_pk_bf16_f32 v67, v67, v68
	v_lshlrev_b64 v[68:69], 13, v[170:171]
	v_lshl_add_u64 v[68:69], s[42:43], 0, v[68:69]
	v_lshl_add_u64 v[76:77], v[68:69], 0, v[174:175]
	global_store_dwordx4 v[76:77], v[64:67], off
	s_waitcnt vmcnt(4)
; __device__ __forceinline__ float bf_lo(unsigned w) { return __uint_as_float(w << 16); }
; __device__ __forceinline__ float bf_hi(unsigned w) { return __uint_as_float(w & 0xffff0000u); }
;     __device__ __forceinline__ void operator()(const AccT& acc, const Unit& u, int wr, int wc, int fr, int fq) const {
;     ...
;                 for (int m = 0; m < 4; ++m) xw[ai][m] = *(const u32x2*)(XC + (size_t)(row0 + ai * HALF + m * 16) * DM + ch0 + 16 * n);
;             const f32x4 bra = *(const f32x4*)(b_ra + ch0 + 16 * n), bri = *(const f32x4*)(b_ri + ch0 + 16 * n), l = *(const f32x4*)(lam + ch0 + 16 * n);
;             f32x4 sp;
; #pragma unroll
;             for (int j = 0; j < 4; ++j) sp[j] = -8.0f * log1pf(__expf(-l[j]));
; #pragma unroll
;             for (int ai = 0; ai < 2; ++ai)
; #pragma unroll
;                 for (int m = 0; m < 4; ++m) { const size_t off = (size_t)(row0 + ai * HALF + m * 16) * DM + ch0 + 16 * n;
;                     const f32x4 rp = acc[ai][0][m][n] + bra, ip = acc[ai][1][m][n] + bri;
;                     const u32x2 w = xw[ai][m]; const float xv[4] = {bf_lo(w.x), bf_hi(w.x), bf_lo(w.y), bf_hi(w.y)};
;                     u32x4 o;
; #pragma unroll
;                     for (int j = 0; j < 4; ++j) { const float r = __builtin_amdgcn_rcpf(1.0f + __expf(-rp[j])), ig = __builtin_amdgcn_rcpf(1.0f + __expf(-ip[j])); const float la = sp[j] * r; const float d = 1.0f - __expf(la);
	v_mov_b32_e32 v98, v114
	v_mov_b32_e32 v99, v115
	v_mov_b32_e32 v94, v122
	v_mov_b32_e32 v95, v123
	v_mov_b32_e32 v92, v148
	v_mov_b32_e32 v93, v149
	v_mov_b32_e32 v90, v192
	v_mov_b32_e32 v91, v193
	v_mov_b32_e32 v86, v202
	v_mov_b32_e32 v87, v203
	v_mov_b32_e32 v84, v208
	v_mov_b32_e32 v85, v209
	v_mov_b32_e32 v82, v210
	v_mov_b32_e32 v83, v211
	v_mov_b32_e32 v78, v224
	v_mov_b32_e32 v79, v225
	v_mov_b32_e32 v68, v116
	v_mov_b32_e32 v69, v117
	v_mov_b32_e32 v70, v118
	v_mov_b32_e32 v71, v119
	v_mov_b32_e32 v64, v196
	v_mov_b32_e32 v65, v197
	v_mov_b32_e32 v66, v198
	v_mov_b32_e32 v67, v199
	v_mov_b32_e32 v72, v204
	v_mov_b32_e32 v73, v205
	v_mov_b32_e32 v74, v206
	v_mov_b32_e32 v75, v207
	v_add_f32_e32 v56, v56, v68
	v_mul_f32_e32 v56, 0xbfb8aa3b, v56
	v_mul_f32_e32 v72, 0xbfb8aa3b, v72
	v_exp_f32_e32 v72, v72
	v_mul_f32_e32 v73, 0xbfb8aa3b, v73
	v_exp_f32_e32 v73, v73
	v_mul_f32_e32 v74, 0xbfb8aa3b, v74
	v_add_f32_e32 v102, 1.0, v72
	v_add_f32_e32 v100, -1.0, v102
	v_sub_f32_e32 v101, v100, v102
	v_add_f32_e32 v101, 1.0, v101
	v_sub_f32_e32 v100, v72, v100
	v_add_f32_e32 v103, v100, v101
	v_frexp_mant_f32_e32 v100, v102
	v_cmp_gt_f32_e32 vcc, s76, v100
	v_cvt_f64_f32_e32 v[100:101], v102
	v_frexp_exp_i32_f64_e32 v100, v[100:101]
	v_subbrev_co_u32_e32 v110, vcc, 0, v100, vcc
	v_sub_u32_e32 v100, 0, v110
	v_ldexp_f32 v101, v102, v100
	v_add_f32_e32 v102, -1.0, v101
	v_add_f32_e32 v106, 1.0, v101
	v_ldexp_f32 v100, v103, v100
	v_add_f32_e32 v103, 1.0, v102
	v_add_f32_e32 v107, -1.0, v106
	v_sub_f32_e32 v103, v101, v103
	v_sub_f32_e32 v101, v101, v107
	v_add_f32_e32 v103, v100, v103
	v_add_f32_e32 v100, v100, v101
	v_add_f32_e32 v111, v106, v100
	v_rcp_f32_e32 v115, v111
	v_sub_f32_e32 v101, v111, v106
	v_sub_f32_e32 v114, v100, v101
	v_add_f32_e32 v101, v102, v103
	v_mul_f32_e32 v117, v101, v115
	v_sub_f32_e32 v100, v101, v102
	v_mul_f32_e32 v102, v111, v117
	v_fma_f32 v106, v117, v111, -v102
	v_fmac_f32_e32 v106, v117, v114
	v_sub_f32_e32 v116, v103, v100
	v_add_f32_e32 v100, v102, v106
	v_sub_f32_e32 v103, v101, v100
	v_pk_add_f32 v[108:109], v[100:101], v[102:103] neg_lo:[0,1] neg_hi:[0,1]
	v_mov_b32_e32 v107, v100
	v_pk_add_f32 v[100:101], v[108:109], v[106:107] neg_lo:[0,1] neg_hi:[0,1]
	v_cmp_neq_f32_e32 vcc, s78, v72
	v_add_f32_e32 v101, v116, v101
	v_add_f32_e32 v100, v100, v101
	v_add_f32_e32 v101, v103, v100
	v_mul_f32_e32 v116, v115, v101
	v_mul_f32_e32 v102, v111, v116
	v_fma_f32 v106, v116, v111, -v102
	v_fmac_f32_e32 v106, v116, v114
	v_sub_f32_e32 v103, v103, v101
	v_add_f32_e32 v111, v100, v103
	v_add_f32_e32 v100, v102, v106
	v_sub_f32_e32 v103, v101, v100
	v_pk_add_f32 v[108:109], v[100:101], v[102:103] neg_lo:[0,1] neg_hi:[0,1]
	v_mov_b32_e32 v107, v100
	v_pk_add_f32 v[100:101], v[108:109], v[106:107] neg_lo:[0,1] neg_hi:[0,1]
	v_exp_f32_e32 v74, v74
	v_add_f32_e32 v101, v111, v101
	v_add_f32_e32 v100, v100, v101
	v_add_f32_e32 v101, v117, v116
	v_add_f32_e32 v100, v103, v100
	v_sub_f32_e32 v102, v101, v117
	v_mul_f32_e32 v100, v115, v100
	v_sub_f32_e32 v102, v116, v102
	v_add_f32_e32 v102, v102, v100
	v_add_f32_e32 v106, v101, v102
	v_mul_f32_e32 v107, v106, v106
	v_fmamk_f32 v100, v107, 0x3e9b6dac, v218
	v_fmaak_f32 v153, v107, v100, 0x3f2aaada
	v_cvt_f32_i32_e32 v100, v110
	v_sub_f32_e32 v101, v106, v101
	v_sub_f32_e32 v101, v102, v101
	v_ldexp_f32 v108, v101, 1
	v_mul_f32_e32 v101, v106, v107
	v_ldexp_f32 v103, v106, 1
	v_pk_mul_f32 v[106:107], v[100:101], v[152:153]
	v_mul_f32_e32 v75, 0xbfb8aa3b, v75
	v_fma_f32 v102, v100, s77, -v106
	v_fmac_f32_e32 v102, 0xb102e308, v100
	v_pk_add_f32 v[100:101], v[106:107], v[102:103]
	v_exp_f32_e32 v75, v75
	v_sub_f32_e32 v103, v101, v103
	v_sub_f32_e32 v103, v107, v103
	v_add_f32_e32 v109, v108, v103
	v_mov_b32_e32 v108, v106
	v_pk_add_f32 v[106:107], v[100:101], v[106:107] neg_lo:[0,1] neg_hi:[0,1]
	v_pk_add_f32 v[110:111], v[100:101], v[108:109]
	v_mov_b32_e32 v103, v100
	v_mov_b32_e32 v107, v111
	v_pk_add_f32 v[114:115], v[102:103], v[106:107] neg_lo:[0,1] neg_hi:[0,1]
	v_pk_add_f32 v[102:103], v[102:103], v[106:107]
	v_mov_b32_e32 v108, v109
	v_pk_add_f32 v[106:107], v[102:103], v[100:101] op_sel:[1,0] op_sel_hi:[0,1] neg_lo:[0,1] neg_hi:[0,1]
	v_pk_add_f32 v[116:117], v[110:111], v[106:107] op_sel_hi:[1,0] neg_lo:[0,1] neg_hi:[0,1]
	v_mov_b32_e32 v110, v111
	v_mov_b32_e32 v111, v103
	v_pk_mov_b32 v[106:107], v[100:101], v[106:107] op_sel:[1,0]
	v_mov_b32_e32 v109, v100
	v_pk_add_f32 v[106:107], v[110:111], v[106:107] neg_lo:[0,1] neg_hi:[0,1]
	v_mov_b32_e32 v116, v114
	v_pk_add_f32 v[100:101], v[108:109], v[106:107] neg_lo:[0,1] neg_hi:[0,1]
	v_mov_b32_e32 v115, v103
	v_pk_add_f32 v[106:107], v[116:117], v[100:101]
	v_exp_f32_e32 v56, v56
	v_pk_add_f32 v[108:109], v[106:107], v[106:107] op_sel:[0,1] op_sel_hi:[1,0]
	v_add_f32_e32 v60, v60, v64
	v_pk_add_f32 v[102:103], v[102:103], v[108:109] op_sel:[1,0] op_sel_hi:[0,1]
	v_mov_b32_e32 v107, v102
	v_pk_add_f32 v[110:111], v[106:107], v[114:115] neg_lo:[0,1] neg_hi:[0,1]
	v_mov_b32_e32 v101, v108
	v_sub_f32_e32 v103, v106, v110
	v_pk_add_f32 v[100:101], v[100:101], v[110:111] neg_lo:[0,1] neg_hi:[0,1]
	v_sub_f32_e32 v103, v114, v103
	v_add_f32_e32 v100, v100, v103
	v_add_f32_e32 v100, v100, v101
	v_add_f32_e32 v100, v102, v100
	v_cndmask_b32_e32 v100, v219, v100, vcc
	v_cmp_ngt_f32_e32 vcc, -1.0, v72
	v_add_f32_e32 v102, 1.0, v73
	v_add_f32_e32 v56, 1.0, v56
	v_cndmask_b32_e32 v100, v220, v100, vcc
	v_cmp_neq_f32_e32 vcc, -1.0, v72
	v_rcp_f32_e32 v56, v56
	v_add_f32_e32 v57, v57, v69
	v_cndmask_b32_e32 v100, v221, v100, vcc
	v_cmp_lt_f32_e64 vcc, |v72|, s79
	v_mul_f32_e32 v60, 0xbfb8aa3b, v60
	v_mul_f32_e32 v57, 0xbfb8aa3b, v57
; __device__ __forceinline__ float bf_lo(unsigned w) { return __uint_as_float(w << 16); }
; __device__ __forceinline__ float bf_hi(unsigned w) { return __uint_as_float(w & 0xffff0000u); }
;     __device__ __forceinline__ void operator()(const AccT& acc, const Unit& u, int wr, int wc, int fr, int fq) const {
;     ...
;             for (int j = 0; j < 4; ++j) sp[j] = -8.0f * log1pf(__expf(-l[j]));
; #pragma unroll
;             for (int ai = 0; ai < 2; ++ai)
; #pragma unroll
;                 for (int m = 0; m < 4; ++m) { const size_t off = (size_t)(row0 + ai * HALF + m * 16) * DM + ch0 + 16 * n;
;                     const f32x4 rp = acc[ai][0][m][n] + bra, ip = acc[ai][1][m][n] + bri;
;                     const u32x2 w = xw[ai][m]; const float xv[4] = {bf_lo(w.x), bf_hi(w.x), bf_lo(w.y), bf_hi(w.y)};
;                     u32x4 o;
; #pragma unroll
;                     for (int j = 0; j < 4; ++j) { const float r = __builtin_amdgcn_rcpf(1.0f + __expf(-rp[j])), ig = __builtin_amdgcn_rcpf(1.0f + __expf(-ip[j])); const float la = sp[j] * r; const float d = 1.0f - __expf(la);
	v_cndmask_b32_e32 v72, v100, v72, vcc
	v_add_f32_e32 v100, -1.0, v102
	v_sub_f32_e32 v101, v100, v102
	v_add_f32_e32 v101, 1.0, v101
	v_sub_f32_e32 v100, v73, v100
	v_add_f32_e32 v103, v100, v101
	v_frexp_mant_f32_e32 v100, v102
	v_cmp_gt_f32_e32 vcc, s76, v100
	v_cvt_f64_f32_e32 v[100:101], v102
	v_frexp_exp_i32_f64_e32 v100, v[100:101]
	v_subbrev_co_u32_e32 v110, vcc, 0, v100, vcc
	v_sub_u32_e32 v100, 0, v110
	v_ldexp_f32 v101, v102, v100
	v_add_f32_e32 v102, -1.0, v101
	v_add_f32_e32 v106, 1.0, v101
	v_ldexp_f32 v100, v103, v100
	v_add_f32_e32 v103, 1.0, v102
	v_add_f32_e32 v107, -1.0, v106
	v_sub_f32_e32 v103, v101, v103
	v_sub_f32_e32 v101, v101, v107
	v_add_f32_e32 v103, v100, v103
	v_add_f32_e32 v100, v100, v101
	v_add_f32_e32 v111, v106, v100
	v_rcp_f32_e32 v115, v111
	v_sub_f32_e32 v101, v111, v106
	v_sub_f32_e32 v114, v100, v101
	v_add_f32_e32 v101, v102, v103
	v_mul_f32_e32 v117, v101, v115
	v_sub_f32_e32 v100, v101, v102
	v_mul_f32_e32 v102, v111, v117
	v_fma_f32 v106, v117, v111, -v102
	v_fmac_f32_e32 v106, v117, v114
	v_sub_f32_e32 v116, v103, v100
	v_add_f32_e32 v100, v102, v106
	v_sub_f32_e32 v103, v101, v100
	v_pk_add_f32 v[108:109], v[100:101], v[102:103] neg_lo:[0,1] neg_hi:[0,1]
	v_mov_b32_e32 v107, v100
	v_pk_add_f32 v[100:101], v[108:109], v[106:107] neg_lo:[0,1] neg_hi:[0,1]
	v_cmp_neq_f32_e32 vcc, s78, v73
	v_add_f32_e32 v101, v116, v101
	v_add_f32_e32 v100, v100, v101
	v_add_f32_e32 v101, v103, v100
	v_mul_f32_e32 v116, v115, v101
	v_mul_f32_e32 v102, v111, v116
	v_fma_f32 v106, v116, v111, -v102
	v_fmac_f32_e32 v106, v116, v114
	v_sub_f32_e32 v103, v103, v101
	v_add_f32_e32 v111, v100, v103
	v_add_f32_e32 v100, v102, v106
	v_sub_f32_e32 v103, v101, v100
	v_pk_add_f32 v[108:109], v[100:101], v[102:103] neg_lo:[0,1] neg_hi:[0,1]
	v_mov_b32_e32 v107, v100
	v_pk_add_f32 v[100:101], v[108:109], v[106:107] neg_lo:[0,1] neg_hi:[0,1]
	v_mul_f32_e32 v72, 0xc1000000, v72
	v_add_f32_e32 v101, v111, v101
	v_add_f32_e32 v100, v100, v101
	v_add_f32_e32 v101, v117, v116
	v_add_f32_e32 v100, v103, v100
	v_sub_f32_e32 v102, v101, v117
	v_mul_f32_e32 v100, v115, v100
	v_sub_f32_e32 v102, v116, v102
	v_add_f32_e32 v102, v102, v100
	v_add_f32_e32 v106, v101, v102
	v_mul_f32_e32 v107, v106, v106
	v_fmamk_f32 v100, v107, 0x3e9b6dac, v218
	v_fmaak_f32 v153, v107, v100, 0x3f2aaada
	v_cvt_f32_i32_e32 v100, v110
	v_sub_f32_e32 v101, v106, v101
	v_sub_f32_e32 v101, v102, v101
	v_ldexp_f32 v108, v101, 1
	v_mul_f32_e32 v101, v106, v107
	v_ldexp_f32 v103, v106, 1
	v_pk_mul_f32 v[106:107], v[100:101], v[152:153]
	v_mul_f32_e32 v56, v56, v72
	v_fma_f32 v102, v100, s77, -v106
	v_fmac_f32_e32 v102, 0xb102e308, v100
	v_pk_add_f32 v[100:101], v[106:107], v[102:103]
	v_mul_f32_e32 v56, 0x3fb8aa3b, v56
	v_sub_f32_e32 v103, v101, v103
	v_sub_f32_e32 v103, v107, v103
	v_add_f32_e32 v109, v108, v103
	v_mov_b32_e32 v108, v106
	v_pk_add_f32 v[106:107], v[100:101], v[106:107] neg_lo:[0,1] neg_hi:[0,1]
	v_pk_add_f32 v[110:111], v[100:101], v[108:109]
	v_mov_b32_e32 v103, v100
	v_mov_b32_e32 v107, v111
	v_pk_add_f32 v[114:115], v[102:103], v[106:107] neg_lo:[0,1] neg_hi:[0,1]
	v_pk_add_f32 v[102:103], v[102:103], v[106:107]
	v_mov_b32_e32 v108, v109
	v_pk_add_f32 v[106:107], v[102:103], v[100:101] op_sel:[1,0] op_sel_hi:[0,1] neg_lo:[0,1] neg_hi:[0,1]
	v_pk_add_f32 v[116:117], v[110:111], v[106:107] op_sel_hi:[1,0] neg_lo:[0,1] neg_hi:[0,1]
	v_mov_b32_e32 v110, v111
	v_mov_b32_e32 v111, v103
	v_pk_mov_b32 v[106:107], v[100:101], v[106:107] op_sel:[1,0]
	v_mov_b32_e32 v109, v100
	v_pk_add_f32 v[106:107], v[110:111], v[106:107] neg_lo:[0,1] neg_hi:[0,1]
	v_mov_b32_e32 v116, v114
	v_pk_add_f32 v[100:101], v[108:109], v[106:107] neg_lo:[0,1] neg_hi:[0,1]
	v_mov_b32_e32 v115, v103
	v_pk_add_f32 v[106:107], v[116:117], v[100:101]
	v_exp_f32_e32 v56, v56
	v_pk_add_f32 v[108:109], v[106:107], v[106:107] op_sel:[0,1] op_sel_hi:[1,0]
	v_exp_f32_e32 v60, v60
	v_pk_add_f32 v[102:103], v[102:103], v[108:109] op_sel:[1,0] op_sel_hi:[0,1]
	v_mov_b32_e32 v107, v102
	v_pk_add_f32 v[110:111], v[106:107], v[114:115] neg_lo:[0,1] neg_hi:[0,1]
	v_mov_b32_e32 v101, v108
	v_sub_f32_e32 v103, v106, v110
	v_pk_add_f32 v[100:101], v[100:101], v[110:111] neg_lo:[0,1] neg_hi:[0,1]
	v_sub_f32_e32 v103, v114, v103
	v_add_f32_e32 v100, v100, v103
	v_add_f32_e32 v100, v100, v101
	v_add_f32_e32 v100, v102, v100
	v_cndmask_b32_e32 v100, v219, v100, vcc
	v_cmp_ngt_f32_e32 vcc, -1.0, v73
	v_add_f32_e32 v102, 1.0, v74
	v_exp_f32_e32 v57, v57
	v_cndmask_b32_e32 v100, v220, v100, vcc
	v_cmp_neq_f32_e32 vcc, -1.0, v73
	v_sub_f32_e32 v56, 1.0, v56
	v_add_f32_e32 v60, 1.0, v60
	v_cndmask_b32_e32 v100, v221, v100, vcc
	v_cmp_lt_f32_e64 vcc, |v73|, s79
	v_add_f32_e32 v57, 1.0, v57
	v_rcp_f32_e32 v60, v60
	v_cndmask_b32_e32 v73, v100, v73, vcc
	v_add_f32_e32 v100, -1.0, v102
	v_sub_f32_e32 v101, v100, v102
	v_add_f32_e32 v101, 1.0, v101
	v_sub_f32_e32 v100, v74, v100
	v_add_f32_e32 v103, v100, v101
	v_frexp_mant_f32_e32 v100, v102
	v_cmp_gt_f32_e32 vcc, s76, v100
	v_cvt_f64_f32_e32 v[100:101], v102
	v_frexp_exp_i32_f64_e32 v100, v[100:101]
	v_subbrev_co_u32_e32 v110, vcc, 0, v100, vcc
	v_sub_u32_e32 v100, 0, v110
	v_ldexp_f32 v101, v102, v100
	v_add_f32_e32 v102, -1.0, v101
	v_add_f32_e32 v106, 1.0, v101
	v_ldexp_f32 v100, v103, v100
	v_add_f32_e32 v103, 1.0, v102
	v_add_f32_e32 v107, -1.0, v106
	v_sub_f32_e32 v103, v101, v103
	v_sub_f32_e32 v101, v101, v107
	v_add_f32_e32 v103, v100, v103
	v_add_f32_e32 v100, v100, v101
	v_add_f32_e32 v111, v106, v100
	v_rcp_f32_e32 v115, v111
	v_sub_f32_e32 v101, v111, v106
	v_sub_f32_e32 v114, v100, v101
	v_add_f32_e32 v101, v102, v103
	v_mul_f32_e32 v117, v101, v115
; __device__ __forceinline__ float bf_lo(unsigned w) { return __uint_as_float(w << 16); }
; __device__ __forceinline__ float bf_hi(unsigned w) { return __uint_as_float(w & 0xffff0000u); }
;     __device__ __forceinline__ void operator()(const AccT& acc, const Unit& u, int wr, int wc, int fr, int fq) const {
;     ...
;             for (int j = 0; j < 4; ++j) sp[j] = -8.0f * log1pf(__expf(-l[j]));
; #pragma unroll
;             for (int ai = 0; ai < 2; ++ai)
; #pragma unroll
;                 for (int m = 0; m < 4; ++m) { const size_t off = (size_t)(row0 + ai * HALF + m * 16) * DM + ch0 + 16 * n;
;                     const f32x4 rp = acc[ai][0][m][n] + bra, ip = acc[ai][1][m][n] + bri;
;                     const u32x2 w = xw[ai][m]; const float xv[4] = {bf_lo(w.x), bf_hi(w.x), bf_lo(w.y), bf_hi(w.y)};
;                     u32x4 o;
; #pragma unroll
;                     for (int j = 0; j < 4; ++j) { const float r = __builtin_amdgcn_rcpf(1.0f + __expf(-rp[j])), ig = __builtin_amdgcn_rcpf(1.0f + __expf(-ip[j])); const float la = sp[j] * r; const float d = 1.0f - __expf(la);
	v_sub_f32_e32 v100, v101, v102
	v_mul_f32_e32 v102, v111, v117
	v_fma_f32 v106, v117, v111, -v102
	v_fmac_f32_e32 v106, v117, v114
	v_sub_f32_e32 v116, v103, v100
	v_add_f32_e32 v100, v102, v106
	v_sub_f32_e32 v103, v101, v100
	v_pk_add_f32 v[108:109], v[100:101], v[102:103] neg_lo:[0,1] neg_hi:[0,1]
	v_mov_b32_e32 v107, v100
	v_pk_add_f32 v[100:101], v[108:109], v[106:107] neg_lo:[0,1] neg_hi:[0,1]
	v_cmp_neq_f32_e32 vcc, s78, v74
	v_add_f32_e32 v101, v116, v101
	v_add_f32_e32 v100, v100, v101
	v_add_f32_e32 v101, v103, v100
	v_mul_f32_e32 v116, v115, v101
	v_mul_f32_e32 v102, v111, v116
	v_fma_f32 v106, v116, v111, -v102
	v_fmac_f32_e32 v106, v116, v114
	v_sub_f32_e32 v103, v103, v101
	v_add_f32_e32 v111, v100, v103
	v_add_f32_e32 v100, v102, v106
	v_sub_f32_e32 v103, v101, v100
	v_pk_add_f32 v[108:109], v[100:101], v[102:103] neg_lo:[0,1] neg_hi:[0,1]
	v_mov_b32_e32 v107, v100
	v_pk_add_f32 v[100:101], v[108:109], v[106:107] neg_lo:[0,1] neg_hi:[0,1]
	v_rcp_f32_e32 v57, v57
	v_add_f32_e32 v101, v111, v101
	v_add_f32_e32 v100, v100, v101
	v_add_f32_e32 v101, v117, v116
	v_add_f32_e32 v100, v103, v100
	v_sub_f32_e32 v102, v101, v117
	v_mul_f32_e32 v100, v115, v100
	v_sub_f32_e32 v102, v116, v102
	v_add_f32_e32 v102, v102, v100
	v_add_f32_e32 v106, v101, v102
	v_mul_f32_e32 v107, v106, v106
	v_fmamk_f32 v100, v107, 0x3e9b6dac, v218
	v_fmaak_f32 v153, v107, v100, 0x3f2aaada
	v_cvt_f32_i32_e32 v100, v110
	v_sub_f32_e32 v101, v106, v101
	v_sub_f32_e32 v101, v102, v101
	v_ldexp_f32 v108, v101, 1
	v_mul_f32_e32 v101, v106, v107
	v_ldexp_f32 v103, v106, 1
	v_pk_mul_f32 v[106:107], v[100:101], v[152:153]
	v_mul_f32_e32 v73, 0xc1000000, v73
	v_fma_f32 v102, v100, s77, -v106
	v_fmac_f32_e32 v102, 0xb102e308, v100
	v_pk_add_f32 v[100:101], v[106:107], v[102:103]
	v_mul_f32_e32 v57, v57, v73
	v_sub_f32_e32 v103, v101, v103
	v_sub_f32_e32 v103, v107, v103
	v_add_f32_e32 v109, v108, v103
	v_mov_b32_e32 v108, v106
	v_pk_add_f32 v[106:107], v[100:101], v[106:107] neg_lo:[0,1] neg_hi:[0,1]
	v_pk_add_f32 v[110:111], v[100:101], v[108:109]
	v_mov_b32_e32 v103, v100
	v_mov_b32_e32 v107, v111
	v_pk_add_f32 v[114:115], v[102:103], v[106:107] neg_lo:[0,1] neg_hi:[0,1]
	v_pk_add_f32 v[102:103], v[102:103], v[106:107]
	v_mov_b32_e32 v108, v109
	v_pk_add_f32 v[106:107], v[102:103], v[100:101] op_sel:[1,0] op_sel_hi:[0,1] neg_lo:[0,1] neg_hi:[0,1]
	v_pk_add_f32 v[116:117], v[110:111], v[106:107] op_sel_hi:[1,0] neg_lo:[0,1] neg_hi:[0,1]
	v_mov_b32_e32 v110, v111
	v_mov_b32_e32 v111, v103
	v_pk_mov_b32 v[106:107], v[100:101], v[106:107] op_sel:[1,0]
	v_mov_b32_e32 v109, v100
	v_pk_add_f32 v[106:107], v[110:111], v[106:107] neg_lo:[0,1] neg_hi:[0,1]
	v_mov_b32_e32 v116, v114
	v_pk_add_f32 v[100:101], v[108:109], v[106:107] neg_lo:[0,1] neg_hi:[0,1]
	v_mov_b32_e32 v115, v103
	v_pk_add_f32 v[106:107], v[116:117], v[100:101]
	v_mul_f32_e32 v57, 0x3fb8aa3b, v57
	v_pk_add_f32 v[108:109], v[106:107], v[106:107] op_sel:[0,1] op_sel_hi:[1,0]
	v_exp_f32_e32 v57, v57
	v_pk_add_f32 v[102:103], v[102:103], v[108:109] op_sel:[1,0] op_sel_hi:[0,1]
	v_mov_b32_e32 v107, v102
	v_pk_add_f32 v[110:111], v[106:107], v[114:115] neg_lo:[0,1] neg_hi:[0,1]
	v_mov_b32_e32 v101, v108
	v_sub_f32_e32 v103, v106, v110
	v_pk_add_f32 v[100:101], v[100:101], v[110:111] neg_lo:[0,1] neg_hi:[0,1]
	v_sub_f32_e32 v103, v114, v103
	v_add_f32_e32 v100, v100, v103
	v_add_f32_e32 v100, v100, v101
	v_add_f32_e32 v100, v102, v100
	v_cndmask_b32_e32 v100, v219, v100, vcc
	v_cmp_ngt_f32_e32 vcc, -1.0, v74
	v_add_f32_e32 v102, 1.0, v75
	v_add_f32_e32 v58, v58, v70
	v_cndmask_b32_e32 v100, v220, v100, vcc
	v_cmp_neq_f32_e32 vcc, -1.0, v74
	v_mul_f32_e32 v58, 0xbfb8aa3b, v58
	v_exp_f32_e32 v58, v58
	v_cndmask_b32_e32 v100, v221, v100, vcc
	v_cmp_lt_f32_e64 vcc, |v74|, s79
	v_sub_f32_e32 v57, 1.0, v57
	v_add_f32_e32 v58, 1.0, v58
	v_cndmask_b32_e32 v74, v100, v74, vcc
	v_add_f32_e32 v100, -1.0, v102
	v_sub_f32_e32 v101, v100, v102
	v_add_f32_e32 v101, 1.0, v101
	v_sub_f32_e32 v100, v75, v100
	v_add_f32_e32 v103, v100, v101
	v_frexp_mant_f32_e32 v100, v102
	v_cmp_gt_f32_e32 vcc, s76, v100
	v_cvt_f64_f32_e32 v[100:101], v102
	v_frexp_exp_i32_f64_e32 v100, v[100:101]
	v_subbrev_co_u32_e32 v110, vcc, 0, v100, vcc
	v_sub_u32_e32 v100, 0, v110
	v_ldexp_f32 v101, v102, v100
	v_add_f32_e32 v102, -1.0, v101
	v_add_f32_e32 v106, 1.0, v101
	v_ldexp_f32 v100, v103, v100
	v_add_f32_e32 v103, 1.0, v102
	v_add_f32_e32 v107, -1.0, v106
	v_sub_f32_e32 v103, v101, v103
	v_sub_f32_e32 v101, v101, v107
	v_add_f32_e32 v103, v100, v103
	v_add_f32_e32 v100, v100, v101
	v_add_f32_e32 v111, v106, v100
	v_rcp_f32_e32 v115, v111
	v_sub_f32_e32 v101, v111, v106
	v_sub_f32_e32 v114, v100, v101
	v_add_f32_e32 v101, v102, v103
	v_mul_f32_e32 v117, v101, v115
	v_sub_f32_e32 v100, v101, v102
	v_mul_f32_e32 v102, v111, v117
	v_fma_f32 v106, v117, v111, -v102
	v_fmac_f32_e32 v106, v117, v114
	v_sub_f32_e32 v116, v103, v100
	v_add_f32_e32 v100, v102, v106
	v_sub_f32_e32 v103, v101, v100
	v_pk_add_f32 v[108:109], v[100:101], v[102:103] neg_lo:[0,1] neg_hi:[0,1]
	v_mov_b32_e32 v107, v100
	v_pk_add_f32 v[100:101], v[108:109], v[106:107] neg_lo:[0,1] neg_hi:[0,1]
	v_cmp_neq_f32_e32 vcc, s78, v75
	v_add_f32_e32 v101, v116, v101
	v_add_f32_e32 v100, v100, v101
	v_add_f32_e32 v101, v103, v100
	v_mul_f32_e32 v116, v115, v101
	v_mul_f32_e32 v102, v111, v116
	v_fma_f32 v106, v116, v111, -v102
	v_fmac_f32_e32 v106, v116, v114
	v_sub_f32_e32 v103, v103, v101
	v_add_f32_e32 v111, v100, v103
	v_add_f32_e32 v100, v102, v106
	v_sub_f32_e32 v103, v101, v100
	v_pk_add_f32 v[108:109], v[100:101], v[102:103] neg_lo:[0,1] neg_hi:[0,1]
	v_mov_b32_e32 v107, v100
; __device__ __forceinline__ unsigned cvt_pk_bf16(float lo, float hi) { const bf16x2_t r = __builtin_convertvector((f32x2){lo, hi}, bf16x2_t); return __builtin_bit_cast(unsigned, r); }
; __device__ __forceinline__ float bf_lo(unsigned w) { return __uint_as_float(w << 16); }
; __device__ __forceinline__ float bf_hi(unsigned w) { return __uint_as_float(w & 0xffff0000u); }
;     __device__ __forceinline__ void operator()(const AccT& acc, const Unit& u, int wr, int wc, int fr, int fq) const {
;     ...
;             for (int ai = 0; ai < 2; ++ai)
; #pragma unroll
;                 for (int m = 0; m < 4; ++m) { const size_t off = (size_t)(row0 + ai * HALF + m * 16) * DM + ch0 + 16 * n;
;                     const f32x4 rp = acc[ai][0][m][n] + bra, ip = acc[ai][1][m][n] + bri;
;                     const u32x2 w = xw[ai][m]; const float xv[4] = {bf_lo(w.x), bf_hi(w.x), bf_lo(w.y), bf_hi(w.y)};
;                     u32x4 o;
; #pragma unroll
;                     for (int j = 0; j < 4; ++j) { const float r = __builtin_amdgcn_rcpf(1.0f + __expf(-rp[j])), ig = __builtin_amdgcn_rcpf(1.0f + __expf(-ip[j])); const float la = sp[j] * r; const float d = 1.0f - __expf(la);
;                         o[j] = cvt_pk_bf16(d, __builtin_amdgcn_sqrtf(fmaxf(d * (2.0f - d), 0.f)) * (ig * xv[j])); }
;                     *(u32x4*)(AU + off) = o; }
	v_pk_add_f32 v[100:101], v[108:109], v[106:107] neg_lo:[0,1] neg_hi:[0,1]
	v_rcp_f32_e32 v58, v58
	v_add_f32_e32 v101, v111, v101
	v_add_f32_e32 v100, v100, v101
	v_add_f32_e32 v101, v117, v116
	v_add_f32_e32 v100, v103, v100
	v_sub_f32_e32 v102, v101, v117
	v_mul_f32_e32 v100, v115, v100
	v_sub_f32_e32 v102, v116, v102
	v_add_f32_e32 v102, v102, v100
	v_add_f32_e32 v106, v101, v102
	v_mul_f32_e32 v107, v106, v106
	v_fmamk_f32 v100, v107, 0x3e9b6dac, v218
	v_fmaak_f32 v153, v107, v100, 0x3f2aaada
	v_cvt_f32_i32_e32 v100, v110
	v_sub_f32_e32 v101, v106, v101
	v_sub_f32_e32 v101, v102, v101
	v_ldexp_f32 v108, v101, 1
	v_mul_f32_e32 v101, v106, v107
	v_ldexp_f32 v103, v106, 1
	v_pk_mul_f32 v[106:107], v[100:101], v[152:153]
	v_mul_f32_e32 v74, 0xc1000000, v74
	v_fma_f32 v102, v100, s77, -v106
	v_fmac_f32_e32 v102, 0xb102e308, v100
	v_pk_add_f32 v[100:101], v[106:107], v[102:103]
	v_mul_f32_e32 v58, v58, v74
	v_sub_f32_e32 v103, v101, v103
	v_sub_f32_e32 v103, v107, v103
	v_add_f32_e32 v109, v108, v103
	v_mov_b32_e32 v108, v106
	v_pk_add_f32 v[106:107], v[100:101], v[106:107] neg_lo:[0,1] neg_hi:[0,1]
	v_pk_add_f32 v[110:111], v[100:101], v[108:109]
	v_mov_b32_e32 v103, v100
	v_mov_b32_e32 v107, v111
	v_pk_add_f32 v[114:115], v[102:103], v[106:107] neg_lo:[0,1] neg_hi:[0,1]
	v_pk_add_f32 v[102:103], v[102:103], v[106:107]
	v_mov_b32_e32 v108, v109
	v_pk_add_f32 v[106:107], v[102:103], v[100:101] op_sel:[1,0] op_sel_hi:[0,1] neg_lo:[0,1] neg_hi:[0,1]
	v_pk_add_f32 v[116:117], v[110:111], v[106:107] op_sel_hi:[1,0] neg_lo:[0,1] neg_hi:[0,1]
	v_mov_b32_e32 v110, v111
	v_mov_b32_e32 v111, v103
	v_pk_mov_b32 v[106:107], v[100:101], v[106:107] op_sel:[1,0]
	v_mov_b32_e32 v109, v100
	v_pk_add_f32 v[106:107], v[110:111], v[106:107] neg_lo:[0,1] neg_hi:[0,1]
	v_mov_b32_e32 v116, v114
	v_pk_add_f32 v[100:101], v[108:109], v[106:107] neg_lo:[0,1] neg_hi:[0,1]
	v_mov_b32_e32 v115, v103
	v_pk_add_f32 v[106:107], v[116:117], v[100:101]
	v_mul_f32_e32 v58, 0x3fb8aa3b, v58
	v_pk_add_f32 v[108:109], v[106:107], v[106:107] op_sel:[0,1] op_sel_hi:[1,0]
	v_exp_f32_e32 v58, v58
	v_pk_add_f32 v[102:103], v[102:103], v[108:109] op_sel:[1,0] op_sel_hi:[0,1]
	v_mov_b32_e32 v107, v102
	v_pk_add_f32 v[110:111], v[106:107], v[114:115] neg_lo:[0,1] neg_hi:[0,1]
	v_mov_b32_e32 v101, v108
	v_sub_f32_e32 v103, v106, v110
	v_pk_add_f32 v[100:101], v[100:101], v[110:111] neg_lo:[0,1] neg_hi:[0,1]
	v_sub_f32_e32 v103, v114, v103
	v_add_f32_e32 v100, v100, v103
	v_add_f32_e32 v100, v100, v101
	v_add_f32_e32 v100, v102, v100
	v_sub_f32_e32 v102, 2.0, v56
	v_mul_f32_e32 v102, v56, v102
	v_cndmask_b32_e32 v100, v219, v100, vcc
	v_cmp_ngt_f32_e32 vcc, -1.0, v75
	v_max_f32_e32 v102, 0, v102
	v_sqrt_f32_e32 v102, v102
	v_cndmask_b32_e32 v100, v220, v100, vcc
	v_cmp_neq_f32_e32 vcc, -1.0, v75
	v_add_f32_e32 v59, v59, v71
	v_mul_f32_e32 v59, 0xbfb8aa3b, v59
	v_cndmask_b32_e32 v100, v221, v100, vcc
	v_cmp_lt_f32_e64 vcc, |v75|, s79
	v_exp_f32_e32 v59, v59
	v_sub_f32_e32 v58, 1.0, v58
	v_cndmask_b32_e32 v75, v100, v75, vcc
	v_lshlrev_b32_e32 v100, 16, v98
	v_mul_f32_e32 v60, v60, v100
	v_mul_f32_e32 v60, v60, v102
	v_cvt_pk_bf16_f32 v56, v56, v60
	v_add_f32_e32 v60, v61, v65
	v_mul_f32_e32 v60, 0xbfb8aa3b, v60
	v_exp_f32_e32 v60, v60
	v_sub_f32_e32 v61, 2.0, v57
	v_mul_f32_e32 v61, v57, v61
	v_max_f32_e32 v61, 0, v61
	v_add_f32_e32 v60, 1.0, v60
	v_rcp_f32_e32 v60, v60
	v_sqrt_f32_e32 v61, v61
	v_and_b32_e32 v98, 0xffff0000, v98
	v_add_f32_e32 v59, 1.0, v59
	v_mul_f32_e32 v60, v60, v98
	v_mul_f32_e32 v60, v60, v61
	v_cvt_pk_bf16_f32 v57, v57, v60
	v_add_f32_e32 v60, v62, v66
	v_mul_f32_e32 v60, 0xbfb8aa3b, v60
	v_exp_f32_e32 v60, v60
	v_sub_f32_e32 v61, 2.0, v58
	v_mul_f32_e32 v61, v58, v61
	v_max_f32_e32 v61, 0, v61
	v_add_f32_e32 v60, 1.0, v60
	v_rcp_f32_e32 v60, v60
	v_rcp_f32_e32 v59, v59
	v_sqrt_f32_e32 v61, v61
	v_add_f32_e32 v48, v48, v68
	v_mul_f32_e32 v48, 0xbfb8aa3b, v48
	v_mul_f32_e32 v75, 0xc1000000, v75
	v_lshlrev_b32_e32 v101, 16, v99
	v_exp_f32_e32 v48, v48
	v_mul_f32_e32 v60, v60, v101
	v_mul_f32_e32 v59, v59, v75
	v_mul_f32_e32 v60, v60, v61
	v_mul_f32_e32 v59, 0x3fb8aa3b, v59
	v_cvt_pk_bf16_f32 v58, v58, v60
	v_add_f32_e32 v60, v63, v67
	v_exp_f32_e32 v59, v59
	v_mul_f32_e32 v60, 0xbfb8aa3b, v60
	v_add_f32_e32 v48, 1.0, v48
	v_exp_f32_e32 v60, v60
	v_rcp_f32_e32 v48, v48
	v_sub_f32_e32 v59, 1.0, v59
	v_sub_f32_e32 v61, 2.0, v59
	v_add_f32_e32 v60, 1.0, v60
	v_mul_f32_e32 v61, v59, v61
	v_mul_f32_e32 v48, v48, v72
	v_rcp_f32_e32 v60, v60
	v_max_f32_e32 v61, 0, v61
	v_mul_f32_e32 v48, 0x3fb8aa3b, v48
	v_sqrt_f32_e32 v61, v61
	v_add_f32_e32 v52, v52, v64
	v_exp_f32_e32 v48, v48
	v_add_f32_e32 v49, v49, v69
	v_mul_f32_e32 v52, 0xbfb8aa3b, v52
	v_mul_f32_e32 v49, 0xbfb8aa3b, v49
	v_and_b32_e32 v99, 0xffff0000, v99
	v_exp_f32_e32 v52, v52
	v_exp_f32_e32 v49, v49
	v_mul_f32_e32 v60, v60, v99
	v_mul_f32_e32 v60, v60, v61
	v_sub_f32_e32 v48, 1.0, v48
	v_cvt_pk_bf16_f32 v59, v59, v60
	v_sub_f32_e32 v60, 2.0, v48
	v_add_f32_e32 v52, 1.0, v52
	v_mul_f32_e32 v60, v48, v60
	v_add_f32_e32 v49, 1.0, v49
	v_rcp_f32_e32 v52, v52
	v_max_f32_e32 v60, 0, v60
	v_rcp_f32_e32 v49, v49
	v_sqrt_f32_e32 v60, v60
	global_store_dwordx4 v[128:129], v[56:59], off offset:64
	v_add_f32_e32 v50, v50, v70
	v_mul_f32_e32 v49, v49, v73
	v_lshlrev_b32_e32 v56, 16, v94
	v_mul_f32_e32 v52, v52, v56
	v_mul_f32_e32 v52, v52, v60
	v_mul_f32_e32 v49, 0x3fb8aa3b, v49
	v_cvt_pk_bf16_f32 v48, v48, v52
	v_add_f32_e32 v52, v53, v65
	v_exp_f32_e32 v49, v49
	v_mul_f32_e32 v52, 0xbfb8aa3b, v52
	v_mul_f32_e32 v50, 0xbfb8aa3b, v50
	v_exp_f32_e32 v52, v52
	v_exp_f32_e32 v50, v50
	v_sub_f32_e32 v49, 1.0, v49
; __device__ __forceinline__ unsigned cvt_pk_bf16(float lo, float hi) { const bf16x2_t r = __builtin_convertvector((f32x2){lo, hi}, bf16x2_t); return __builtin_bit_cast(unsigned, r); }
; __device__ __forceinline__ float bf_lo(unsigned w) { return __uint_as_float(w << 16); }
; __device__ __forceinline__ float bf_hi(unsigned w) { return __uint_as_float(w & 0xffff0000u); }
;     __device__ __forceinline__ void operator()(const AccT& acc, const Unit& u, int wr, int wc, int fr, int fq) const {
;     ...
;             for (int ai = 0; ai < 2; ++ai)
; #pragma unroll
;                 for (int m = 0; m < 4; ++m) { const size_t off = (size_t)(row0 + ai * HALF + m * 16) * DM + ch0 + 16 * n;
;                     const f32x4 rp = acc[ai][0][m][n] + bra, ip = acc[ai][1][m][n] + bri;
;                     const u32x2 w = xw[ai][m]; const float xv[4] = {bf_lo(w.x), bf_hi(w.x), bf_lo(w.y), bf_hi(w.y)};
;                     u32x4 o;
; #pragma unroll
;                     for (int j = 0; j < 4; ++j) { const float r = __builtin_amdgcn_rcpf(1.0f + __expf(-rp[j])), ig = __builtin_amdgcn_rcpf(1.0f + __expf(-ip[j])); const float la = sp[j] * r; const float d = 1.0f - __expf(la);
;                         o[j] = cvt_pk_bf16(d, __builtin_amdgcn_sqrtf(fmaxf(d * (2.0f - d), 0.f)) * (ig * xv[j])); }
;                     *(u32x4*)(AU + off) = o; }
	v_sub_f32_e32 v53, 2.0, v49
	v_add_f32_e32 v52, 1.0, v52
	v_mul_f32_e32 v53, v49, v53
	v_add_f32_e32 v50, 1.0, v50
	v_rcp_f32_e32 v52, v52
	v_max_f32_e32 v53, 0, v53
	v_rcp_f32_e32 v50, v50
	v_sqrt_f32_e32 v53, v53
	v_and_b32_e32 v57, 0xffff0000, v94
	v_mul_f32_e32 v52, v52, v57
	v_mul_f32_e32 v50, v50, v74
	v_mul_f32_e32 v52, v52, v53
	v_mul_f32_e32 v50, 0x3fb8aa3b, v50
	v_cvt_pk_bf16_f32 v49, v49, v52
	v_add_f32_e32 v52, v54, v66
	v_exp_f32_e32 v50, v50
	v_add_f32_e32 v51, v51, v71
	v_mul_f32_e32 v52, 0xbfb8aa3b, v52
	v_mul_f32_e32 v51, 0xbfb8aa3b, v51
	v_exp_f32_e32 v52, v52
	v_exp_f32_e32 v51, v51
	v_sub_f32_e32 v50, 1.0, v50
	v_sub_f32_e32 v53, 2.0, v50
	v_add_f32_e32 v52, 1.0, v52
	v_mul_f32_e32 v53, v50, v53
	v_add_f32_e32 v51, 1.0, v51
	v_rcp_f32_e32 v52, v52
	v_max_f32_e32 v53, 0, v53
	v_rcp_f32_e32 v51, v51
	v_sqrt_f32_e32 v53, v53
	v_add_f32_e32 v40, v40, v68
	v_mul_f32_e32 v40, 0xbfb8aa3b, v40
	v_lshlrev_b32_e32 v58, 16, v95
	v_exp_f32_e32 v40, v40
	v_mul_f32_e32 v52, v52, v58
	v_mul_f32_e32 v51, v51, v75
	v_mul_f32_e32 v52, v52, v53
	v_mul_f32_e32 v51, 0x3fb8aa3b, v51
	v_cvt_pk_bf16_f32 v50, v50, v52
	v_add_f32_e32 v52, v55, v67
	v_exp_f32_e32 v51, v51
	v_mul_f32_e32 v52, 0xbfb8aa3b, v52
	v_add_f32_e32 v40, 1.0, v40
	v_exp_f32_e32 v52, v52
	v_rcp_f32_e32 v40, v40
	v_sub_f32_e32 v51, 1.0, v51
	v_sub_f32_e32 v53, 2.0, v51
	v_add_f32_e32 v52, 1.0, v52
	v_mul_f32_e32 v53, v51, v53
	v_mul_f32_e32 v40, v40, v72
	v_rcp_f32_e32 v52, v52
	v_max_f32_e32 v53, 0, v53
	v_mul_f32_e32 v40, 0x3fb8aa3b, v40
	v_sqrt_f32_e32 v53, v53
	v_add_f32_e32 v44, v44, v64
	v_exp_f32_e32 v40, v40
	v_add_f32_e32 v41, v41, v69
	v_mul_f32_e32 v44, 0xbfb8aa3b, v44
	v_mul_f32_e32 v41, 0xbfb8aa3b, v41
	v_and_b32_e32 v59, 0xffff0000, v95
	v_exp_f32_e32 v44, v44
	v_exp_f32_e32 v41, v41
	v_mul_f32_e32 v52, v52, v59
	v_mul_f32_e32 v52, v52, v53
	v_sub_f32_e32 v40, 1.0, v40
	v_cvt_pk_bf16_f32 v51, v51, v52
	v_sub_f32_e32 v52, 2.0, v40
	v_add_f32_e32 v44, 1.0, v44
	v_mul_f32_e32 v52, v40, v52
	v_add_f32_e32 v41, 1.0, v41
	v_rcp_f32_e32 v44, v44
	v_max_f32_e32 v52, 0, v52
	v_rcp_f32_e32 v41, v41
	v_sqrt_f32_e32 v52, v52
	global_store_dwordx4 v[120:121], v[48:51], off offset:64
	v_add_f32_e32 v42, v42, v70
	v_mul_f32_e32 v41, v41, v73
	v_lshlrev_b32_e32 v48, 16, v92
	v_mul_f32_e32 v44, v44, v48
	v_mul_f32_e32 v44, v44, v52
	v_mul_f32_e32 v41, 0x3fb8aa3b, v41
	v_cvt_pk_bf16_f32 v40, v40, v44
	v_add_f32_e32 v44, v45, v65
	v_exp_f32_e32 v41, v41
	v_mul_f32_e32 v44, 0xbfb8aa3b, v44
	v_mul_f32_e32 v42, 0xbfb8aa3b, v42
	v_exp_f32_e32 v44, v44
	v_exp_f32_e32 v42, v42
	v_sub_f32_e32 v41, 1.0, v41
	v_sub_f32_e32 v45, 2.0, v41
	v_add_f32_e32 v44, 1.0, v44
	v_mul_f32_e32 v45, v41, v45
	v_add_f32_e32 v42, 1.0, v42
	v_rcp_f32_e32 v44, v44
	v_max_f32_e32 v45, 0, v45
	v_rcp_f32_e32 v42, v42
	v_sqrt_f32_e32 v45, v45
	v_and_b32_e32 v49, 0xffff0000, v92
	v_mul_f32_e32 v44, v44, v49
	v_mul_f32_e32 v42, v42, v74
	v_mul_f32_e32 v44, v44, v45
	v_mul_f32_e32 v42, 0x3fb8aa3b, v42
	v_cvt_pk_bf16_f32 v41, v41, v44
	v_add_f32_e32 v44, v46, v66
	v_exp_f32_e32 v42, v42
	v_add_f32_e32 v43, v43, v71
	v_mul_f32_e32 v44, 0xbfb8aa3b, v44
	v_mul_f32_e32 v43, 0xbfb8aa3b, v43
	v_exp_f32_e32 v44, v44
	v_exp_f32_e32 v43, v43
	v_sub_f32_e32 v42, 1.0, v42
	v_sub_f32_e32 v45, 2.0, v42
	v_add_f32_e32 v44, 1.0, v44
	v_mul_f32_e32 v45, v42, v45
	v_add_f32_e32 v43, 1.0, v43
	v_rcp_f32_e32 v44, v44
	v_max_f32_e32 v45, 0, v45
	v_rcp_f32_e32 v43, v43
	v_sqrt_f32_e32 v45, v45
	v_add_f32_e32 v32, v32, v68
	v_mul_f32_e32 v32, 0xbfb8aa3b, v32
	v_lshlrev_b32_e32 v50, 16, v93
	v_exp_f32_e32 v32, v32
	v_mul_f32_e32 v44, v44, v50
	v_mul_f32_e32 v43, v43, v75
	v_mul_f32_e32 v44, v44, v45
	v_mul_f32_e32 v43, 0x3fb8aa3b, v43
	v_cvt_pk_bf16_f32 v42, v42, v44
	v_add_f32_e32 v44, v47, v67
	v_exp_f32_e32 v43, v43
	v_mul_f32_e32 v44, 0xbfb8aa3b, v44
	v_add_f32_e32 v32, 1.0, v32
	v_exp_f32_e32 v44, v44
	v_rcp_f32_e32 v32, v32
	v_sub_f32_e32 v43, 1.0, v43
	v_sub_f32_e32 v45, 2.0, v43
	v_add_f32_e32 v44, 1.0, v44
	v_mul_f32_e32 v45, v43, v45
	v_mul_f32_e32 v32, v32, v72
	v_rcp_f32_e32 v44, v44
	v_max_f32_e32 v45, 0, v45
	v_mul_f32_e32 v32, 0x3fb8aa3b, v32
	v_sqrt_f32_e32 v45, v45
	v_add_f32_e32 v36, v36, v64
	v_exp_f32_e32 v32, v32
	v_add_f32_e32 v33, v33, v69
	v_mul_f32_e32 v36, 0xbfb8aa3b, v36
	v_mul_f32_e32 v33, 0xbfb8aa3b, v33
	v_and_b32_e32 v51, 0xffff0000, v93
	v_exp_f32_e32 v36, v36
	v_exp_f32_e32 v33, v33
	v_mul_f32_e32 v44, v44, v51
	v_mul_f32_e32 v44, v44, v45
	v_sub_f32_e32 v32, 1.0, v32
	v_cvt_pk_bf16_f32 v43, v43, v44
	v_sub_f32_e32 v44, 2.0, v32
	v_add_f32_e32 v36, 1.0, v36
	v_mul_f32_e32 v44, v32, v44
	v_add_f32_e32 v33, 1.0, v33
	v_rcp_f32_e32 v36, v36
	v_max_f32_e32 v44, 0, v44
	v_rcp_f32_e32 v33, v33
	v_sqrt_f32_e32 v44, v44
	global_store_dwordx4 v[112:113], v[40:43], off offset:64
	v_add_f32_e32 v34, v34, v70
	v_mul_f32_e32 v33, v33, v73
	v_lshlrev_b32_e32 v40, 16, v90
	v_mul_f32_e32 v36, v36, v40
	v_mul_f32_e32 v36, v36, v44
	v_mul_f32_e32 v33, 0x3fb8aa3b, v33
	v_cvt_pk_bf16_f32 v32, v32, v36
	v_add_f32_e32 v36, v37, v65
	v_exp_f32_e32 v33, v33
	v_mul_f32_e32 v36, 0xbfb8aa3b, v36
	v_mul_f32_e32 v34, 0xbfb8aa3b, v34
	v_exp_f32_e32 v36, v36
	v_exp_f32_e32 v34, v34
	v_sub_f32_e32 v33, 1.0, v33
	v_sub_f32_e32 v37, 2.0, v33
	v_add_f32_e32 v36, 1.0, v36
	v_mul_f32_e32 v37, v33, v37
	v_add_f32_e32 v34, 1.0, v34
	v_rcp_f32_e32 v36, v36
	v_max_f32_e32 v37, 0, v37
	v_rcp_f32_e32 v34, v34
	v_sqrt_f32_e32 v37, v37
	v_and_b32_e32 v41, 0xffff0000, v90
	v_mul_f32_e32 v36, v36, v41
	v_mul_f32_e32 v34, v34, v74
	v_mul_f32_e32 v36, v36, v37
	v_mul_f32_e32 v34, 0x3fb8aa3b, v34
	v_cvt_pk_bf16_f32 v33, v33, v36
	v_add_f32_e32 v36, v38, v66
; __device__ __forceinline__ unsigned cvt_pk_bf16(float lo, float hi) { const bf16x2_t r = __builtin_convertvector((f32x2){lo, hi}, bf16x2_t); return __builtin_bit_cast(unsigned, r); }
; __device__ __forceinline__ float bf_lo(unsigned w) { return __uint_as_float(w << 16); }
; __device__ __forceinline__ float bf_hi(unsigned w) { return __uint_as_float(w & 0xffff0000u); }
;     __device__ __forceinline__ void operator()(const AccT& acc, const Unit& u, int wr, int wc, int fr, int fq) const {
;     ...
;             for (int ai = 0; ai < 2; ++ai)
; #pragma unroll
;                 for (int m = 0; m < 4; ++m) { const size_t off = (size_t)(row0 + ai * HALF + m * 16) * DM + ch0 + 16 * n;
;                     const f32x4 rp = acc[ai][0][m][n] + bra, ip = acc[ai][1][m][n] + bri;
;                     const u32x2 w = xw[ai][m]; const float xv[4] = {bf_lo(w.x), bf_hi(w.x), bf_lo(w.y), bf_hi(w.y)};
;                     u32x4 o;
; #pragma unroll
;                     for (int j = 0; j < 4; ++j) { const float r = __builtin_amdgcn_rcpf(1.0f + __expf(-rp[j])), ig = __builtin_amdgcn_rcpf(1.0f + __expf(-ip[j])); const float la = sp[j] * r; const float d = 1.0f - __expf(la);
;                         o[j] = cvt_pk_bf16(d, __builtin_amdgcn_sqrtf(fmaxf(d * (2.0f - d), 0.f)) * (ig * xv[j])); }
;                     *(u32x4*)(AU + off) = o; }
	v_exp_f32_e32 v34, v34
	v_add_f32_e32 v35, v35, v71
	v_mul_f32_e32 v36, 0xbfb8aa3b, v36
	v_mul_f32_e32 v35, 0xbfb8aa3b, v35
	v_exp_f32_e32 v36, v36
	v_exp_f32_e32 v35, v35
	v_sub_f32_e32 v34, 1.0, v34
	v_sub_f32_e32 v37, 2.0, v34
	v_add_f32_e32 v36, 1.0, v36
	v_mul_f32_e32 v37, v34, v37
	v_add_f32_e32 v35, 1.0, v35
	v_rcp_f32_e32 v36, v36
	v_max_f32_e32 v37, 0, v37
	v_rcp_f32_e32 v35, v35
	v_sqrt_f32_e32 v37, v37
	v_add_f32_e32 v24, v24, v68
	v_mul_f32_e32 v24, 0xbfb8aa3b, v24
	v_lshlrev_b32_e32 v42, 16, v91
	v_exp_f32_e32 v24, v24
	v_mul_f32_e32 v36, v36, v42
	v_mul_f32_e32 v35, v35, v75
	v_mul_f32_e32 v36, v36, v37
	v_mul_f32_e32 v35, 0x3fb8aa3b, v35
	v_cvt_pk_bf16_f32 v34, v34, v36
	v_add_f32_e32 v36, v39, v67
	v_exp_f32_e32 v35, v35
	v_mul_f32_e32 v36, 0xbfb8aa3b, v36
	v_add_f32_e32 v24, 1.0, v24
	v_exp_f32_e32 v36, v36
	v_rcp_f32_e32 v24, v24
	v_sub_f32_e32 v35, 1.0, v35
	v_sub_f32_e32 v37, 2.0, v35
	v_add_f32_e32 v36, 1.0, v36
	v_mul_f32_e32 v37, v35, v37
	v_mul_f32_e32 v24, v24, v72
	v_rcp_f32_e32 v36, v36
	v_max_f32_e32 v37, 0, v37
	v_mul_f32_e32 v24, 0x3fb8aa3b, v24
	v_sqrt_f32_e32 v37, v37
	v_add_f32_e32 v28, v28, v64
	v_exp_f32_e32 v24, v24
	v_add_f32_e32 v25, v25, v69
	v_mul_f32_e32 v28, 0xbfb8aa3b, v28
	v_mul_f32_e32 v25, 0xbfb8aa3b, v25
	v_and_b32_e32 v43, 0xffff0000, v91
	v_exp_f32_e32 v28, v28
	v_exp_f32_e32 v25, v25
	v_mul_f32_e32 v36, v36, v43
	v_mul_f32_e32 v36, v36, v37
	v_sub_f32_e32 v24, 1.0, v24
	v_cvt_pk_bf16_f32 v35, v35, v36
	v_sub_f32_e32 v36, 2.0, v24
	v_add_f32_e32 v28, 1.0, v28
	v_mul_f32_e32 v36, v24, v36
	v_add_f32_e32 v25, 1.0, v25
	v_rcp_f32_e32 v28, v28
	v_max_f32_e32 v36, 0, v36
	v_rcp_f32_e32 v25, v25
	v_sqrt_f32_e32 v36, v36
	global_store_dwordx4 v[104:105], v[32:35], off offset:64
	v_add_f32_e32 v26, v26, v70
	v_mul_f32_e32 v25, v25, v73
	v_lshlrev_b32_e32 v32, 16, v86
	v_mul_f32_e32 v28, v28, v32
	v_mul_f32_e32 v28, v28, v36
	v_mul_f32_e32 v25, 0x3fb8aa3b, v25
	v_cvt_pk_bf16_f32 v24, v24, v28
	v_add_f32_e32 v28, v29, v65
	v_exp_f32_e32 v25, v25
	v_mul_f32_e32 v28, 0xbfb8aa3b, v28
	v_mul_f32_e32 v26, 0xbfb8aa3b, v26
	v_exp_f32_e32 v28, v28
	v_exp_f32_e32 v26, v26
	v_sub_f32_e32 v25, 1.0, v25
	v_sub_f32_e32 v29, 2.0, v25
	v_add_f32_e32 v28, 1.0, v28
	v_mul_f32_e32 v29, v25, v29
	v_add_f32_e32 v26, 1.0, v26
	v_rcp_f32_e32 v28, v28
	v_max_f32_e32 v29, 0, v29
	v_rcp_f32_e32 v26, v26
	v_sqrt_f32_e32 v29, v29
	v_and_b32_e32 v33, 0xffff0000, v86
	v_mul_f32_e32 v28, v28, v33
	v_mul_f32_e32 v26, v26, v74
	v_mul_f32_e32 v28, v28, v29
	v_mul_f32_e32 v26, 0x3fb8aa3b, v26
	v_cvt_pk_bf16_f32 v25, v25, v28
	v_add_f32_e32 v28, v30, v66
	v_exp_f32_e32 v26, v26
	v_add_f32_e32 v27, v27, v71
	v_mul_f32_e32 v28, 0xbfb8aa3b, v28
	v_mul_f32_e32 v27, 0xbfb8aa3b, v27
	v_exp_f32_e32 v28, v28
	v_exp_f32_e32 v27, v27
	v_sub_f32_e32 v26, 1.0, v26
	v_sub_f32_e32 v29, 2.0, v26
	v_add_f32_e32 v28, 1.0, v28
	v_mul_f32_e32 v29, v26, v29
	v_add_f32_e32 v27, 1.0, v27
	v_rcp_f32_e32 v28, v28
	v_max_f32_e32 v29, 0, v29
	v_rcp_f32_e32 v27, v27
	v_sqrt_f32_e32 v29, v29
	v_add_f32_e32 v16, v16, v68
	v_mul_f32_e32 v16, 0xbfb8aa3b, v16
	v_lshlrev_b32_e32 v34, 16, v87
	v_exp_f32_e32 v16, v16
	v_mul_f32_e32 v28, v28, v34
	v_mul_f32_e32 v27, v27, v75
	v_mul_f32_e32 v28, v28, v29
	v_mul_f32_e32 v27, 0x3fb8aa3b, v27
	v_cvt_pk_bf16_f32 v26, v26, v28
	v_add_f32_e32 v28, v31, v67
	v_exp_f32_e32 v27, v27
	v_mul_f32_e32 v28, 0xbfb8aa3b, v28
	v_add_f32_e32 v16, 1.0, v16
	v_exp_f32_e32 v28, v28
	v_rcp_f32_e32 v16, v16
	v_sub_f32_e32 v27, 1.0, v27
	v_sub_f32_e32 v29, 2.0, v27
	v_add_f32_e32 v28, 1.0, v28
	v_mul_f32_e32 v29, v27, v29
	v_mul_f32_e32 v16, v16, v72
	v_rcp_f32_e32 v28, v28
	v_max_f32_e32 v29, 0, v29
	v_mul_f32_e32 v16, 0x3fb8aa3b, v16
	v_sqrt_f32_e32 v29, v29
	v_add_f32_e32 v20, v20, v64
	v_exp_f32_e32 v16, v16
	v_add_f32_e32 v17, v17, v69
	v_mul_f32_e32 v20, 0xbfb8aa3b, v20
	v_mul_f32_e32 v17, 0xbfb8aa3b, v17
	v_and_b32_e32 v35, 0xffff0000, v87
	v_exp_f32_e32 v20, v20
	v_exp_f32_e32 v17, v17
	v_mul_f32_e32 v28, v28, v35
	v_mul_f32_e32 v28, v28, v29
	v_sub_f32_e32 v16, 1.0, v16
	v_cvt_pk_bf16_f32 v27, v27, v28
	v_sub_f32_e32 v28, 2.0, v16
	v_add_f32_e32 v20, 1.0, v20
	v_mul_f32_e32 v28, v16, v28
	v_add_f32_e32 v17, 1.0, v17
	v_rcp_f32_e32 v20, v20
	v_max_f32_e32 v28, 0, v28
	v_rcp_f32_e32 v17, v17
	v_sqrt_f32_e32 v28, v28
	global_store_dwordx4 v[96:97], v[24:27], off offset:64
	v_add_f32_e32 v18, v18, v70
	v_mul_f32_e32 v17, v17, v73
	v_lshlrev_b32_e32 v24, 16, v84
	v_mul_f32_e32 v20, v20, v24
	v_mul_f32_e32 v20, v20, v28
	v_mul_f32_e32 v17, 0x3fb8aa3b, v17
	v_cvt_pk_bf16_f32 v16, v16, v20
	v_add_f32_e32 v20, v21, v65
	v_exp_f32_e32 v17, v17
	v_mul_f32_e32 v20, 0xbfb8aa3b, v20
	v_mul_f32_e32 v18, 0xbfb8aa3b, v18
	v_exp_f32_e32 v20, v20
	v_exp_f32_e32 v18, v18
	v_sub_f32_e32 v17, 1.0, v17
	v_sub_f32_e32 v21, 2.0, v17
	v_add_f32_e32 v20, 1.0, v20
	v_mul_f32_e32 v21, v17, v21
	v_add_f32_e32 v18, 1.0, v18
	v_rcp_f32_e32 v20, v20
	v_max_f32_e32 v21, 0, v21
	v_rcp_f32_e32 v18, v18
	v_sqrt_f32_e32 v21, v21
	v_and_b32_e32 v25, 0xffff0000, v84
	v_mul_f32_e32 v20, v20, v25
	v_mul_f32_e32 v18, v18, v74
	v_mul_f32_e32 v20, v20, v21
	v_mul_f32_e32 v18, 0x3fb8aa3b, v18
	v_cvt_pk_bf16_f32 v17, v17, v20
	v_add_f32_e32 v20, v22, v66
	v_exp_f32_e32 v18, v18
	v_add_f32_e32 v19, v19, v71
	v_mul_f32_e32 v20, 0xbfb8aa3b, v20
	v_mul_f32_e32 v19, 0xbfb8aa3b, v19
	v_exp_f32_e32 v20, v20
	v_exp_f32_e32 v19, v19
	v_sub_f32_e32 v18, 1.0, v18
	v_sub_f32_e32 v21, 2.0, v18
	v_add_f32_e32 v20, 1.0, v20
	v_mul_f32_e32 v21, v18, v21
	v_add_f32_e32 v19, 1.0, v19
	v_rcp_f32_e32 v20, v20
	v_max_f32_e32 v21, 0, v21
	v_rcp_f32_e32 v19, v19
	v_sqrt_f32_e32 v21, v21
; __device__ __forceinline__ unsigned cvt_pk_bf16(float lo, float hi) { const bf16x2_t r = __builtin_convertvector((f32x2){lo, hi}, bf16x2_t); return __builtin_bit_cast(unsigned, r); }
; __device__ __forceinline__ float bf_lo(unsigned w) { return __uint_as_float(w << 16); }
; __device__ __forceinline__ float bf_hi(unsigned w) { return __uint_as_float(w & 0xffff0000u); }
; template <class Epi>
; __device__ __forceinline__ void gemm_phase(LAS unsigned char* lds, const bf16_t* A, int lda, const bf16_t* Bt, int ldb, int M, int N, int K, int asel, const Epi& E, const int fixed_round = -1) {
;     ...
;         if constexpr (!Epi::AFTER_DRAIN) E(acc, cur, wr, wc, fr, fq);
;         if (!has_next) break;
;     __device__ __forceinline__ void operator()(const AccT& acc, const Unit& u, int wr, int wc, int fr, int fq) const {
;     ...
;             for (int ai = 0; ai < 2; ++ai)
; #pragma unroll
;                 for (int m = 0; m < 4; ++m) { const size_t off = (size_t)(row0 + ai * HALF + m * 16) * DM + ch0 + 16 * n;
;                     const f32x4 rp = acc[ai][0][m][n] + bra, ip = acc[ai][1][m][n] + bri;
;                     const u32x2 w = xw[ai][m]; const float xv[4] = {bf_lo(w.x), bf_hi(w.x), bf_lo(w.y), bf_hi(w.y)};
;                     u32x4 o;
; #pragma unroll
;                     for (int j = 0; j < 4; ++j) { const float r = __builtin_amdgcn_rcpf(1.0f + __expf(-rp[j])), ig = __builtin_amdgcn_rcpf(1.0f + __expf(-ip[j])); const float la = sp[j] * r; const float d = 1.0f - __expf(la);
;                         o[j] = cvt_pk_bf16(d, __builtin_amdgcn_sqrtf(fmaxf(d * (2.0f - d), 0.f)) * (ig * xv[j])); }
;                     *(u32x4*)(AU + off) = o; }
	v_add_f32_e32 v8, v8, v68
	v_mul_f32_e32 v8, 0xbfb8aa3b, v8
	v_lshlrev_b32_e32 v26, 16, v85
	v_exp_f32_e32 v8, v8
	v_mul_f32_e32 v20, v20, v26
	v_mul_f32_e32 v19, v19, v75
	v_mul_f32_e32 v20, v20, v21
	v_mul_f32_e32 v19, 0x3fb8aa3b, v19
	v_cvt_pk_bf16_f32 v18, v18, v20
	v_add_f32_e32 v20, v23, v67
	v_exp_f32_e32 v19, v19
	v_mul_f32_e32 v20, 0xbfb8aa3b, v20
	v_add_f32_e32 v8, 1.0, v8
	v_exp_f32_e32 v20, v20
	v_rcp_f32_e32 v8, v8
	v_sub_f32_e32 v19, 1.0, v19
	v_sub_f32_e32 v21, 2.0, v19
	v_add_f32_e32 v20, 1.0, v20
	v_mul_f32_e32 v21, v19, v21
	v_mul_f32_e32 v8, v8, v72
	v_rcp_f32_e32 v20, v20
	v_max_f32_e32 v21, 0, v21
	v_mul_f32_e32 v8, 0x3fb8aa3b, v8
	v_sqrt_f32_e32 v21, v21
	v_add_f32_e32 v12, v12, v64
	v_exp_f32_e32 v8, v8
	v_add_f32_e32 v9, v9, v69
	v_mul_f32_e32 v12, 0xbfb8aa3b, v12
	v_mul_f32_e32 v9, 0xbfb8aa3b, v9
	v_and_b32_e32 v27, 0xffff0000, v85
	v_exp_f32_e32 v12, v12
	v_exp_f32_e32 v9, v9
	v_mul_f32_e32 v20, v20, v27
	v_mul_f32_e32 v20, v20, v21
	v_sub_f32_e32 v8, 1.0, v8
	v_cvt_pk_bf16_f32 v19, v19, v20
	v_sub_f32_e32 v20, 2.0, v8
	v_add_f32_e32 v12, 1.0, v12
	v_mul_f32_e32 v20, v8, v20
	v_add_f32_e32 v9, 1.0, v9
	v_rcp_f32_e32 v12, v12
	v_max_f32_e32 v20, 0, v20
	v_rcp_f32_e32 v9, v9
	v_sqrt_f32_e32 v20, v20
	global_store_dwordx4 v[88:89], v[16:19], off offset:64
	v_add_f32_e32 v10, v10, v70
	v_mul_f32_e32 v9, v9, v73
	v_lshlrev_b32_e32 v16, 16, v82
	v_mul_f32_e32 v12, v12, v16
	v_mul_f32_e32 v12, v12, v20
	v_mul_f32_e32 v9, 0x3fb8aa3b, v9
	v_cvt_pk_bf16_f32 v8, v8, v12
	v_add_f32_e32 v12, v13, v65
	v_exp_f32_e32 v9, v9
	v_mul_f32_e32 v12, 0xbfb8aa3b, v12
	v_mul_f32_e32 v10, 0xbfb8aa3b, v10
	v_exp_f32_e32 v12, v12
	v_exp_f32_e32 v10, v10
	v_sub_f32_e32 v9, 1.0, v9
	v_sub_f32_e32 v13, 2.0, v9
	v_add_f32_e32 v12, 1.0, v12
	v_mul_f32_e32 v13, v9, v13
	v_add_f32_e32 v10, 1.0, v10
	v_rcp_f32_e32 v12, v12
	v_max_f32_e32 v13, 0, v13
	v_rcp_f32_e32 v10, v10
	v_sqrt_f32_e32 v13, v13
	v_and_b32_e32 v17, 0xffff0000, v82
	v_mul_f32_e32 v12, v12, v17
	v_mul_f32_e32 v10, v10, v74
	v_mul_f32_e32 v12, v12, v13
	v_mul_f32_e32 v10, 0x3fb8aa3b, v10
	v_cvt_pk_bf16_f32 v9, v9, v12
	v_add_f32_e32 v12, v14, v66
	v_exp_f32_e32 v10, v10
	v_add_f32_e32 v11, v11, v71
	v_mul_f32_e32 v12, 0xbfb8aa3b, v12
	v_mul_f32_e32 v11, 0xbfb8aa3b, v11
	v_exp_f32_e32 v12, v12
	v_exp_f32_e32 v11, v11
	v_sub_f32_e32 v10, 1.0, v10
	v_sub_f32_e32 v13, 2.0, v10
	v_add_f32_e32 v12, 1.0, v12
	v_mul_f32_e32 v13, v10, v13
	v_add_f32_e32 v11, 1.0, v11
	v_rcp_f32_e32 v12, v12
	v_max_f32_e32 v13, 0, v13
	v_rcp_f32_e32 v11, v11
	v_sqrt_f32_e32 v13, v13
	v_add_f32_e32 v0, v0, v68
	v_mul_f32_e32 v0, 0xbfb8aa3b, v0
	v_lshlrev_b32_e32 v18, 16, v83
	v_exp_f32_e32 v0, v0
	v_mul_f32_e32 v12, v12, v18
	v_mul_f32_e32 v11, v11, v75
	v_mul_f32_e32 v12, v12, v13
	v_mul_f32_e32 v11, 0x3fb8aa3b, v11
	v_cvt_pk_bf16_f32 v10, v10, v12
	v_add_f32_e32 v12, v15, v67
	v_exp_f32_e32 v11, v11
	v_mul_f32_e32 v12, 0xbfb8aa3b, v12
	v_add_f32_e32 v0, 1.0, v0
	v_exp_f32_e32 v12, v12
	v_rcp_f32_e32 v0, v0
	v_sub_f32_e32 v11, 1.0, v11
	v_sub_f32_e32 v13, 2.0, v11
	v_add_f32_e32 v12, 1.0, v12
	v_mul_f32_e32 v13, v11, v13
	v_mul_f32_e32 v0, v0, v72
	v_rcp_f32_e32 v12, v12
	v_max_f32_e32 v13, 0, v13
	v_mul_f32_e32 v0, 0x3fb8aa3b, v0
	v_sqrt_f32_e32 v13, v13
	v_add_f32_e32 v4, v4, v64
	v_exp_f32_e32 v0, v0
	v_add_f32_e32 v1, v1, v69
	v_mul_f32_e32 v4, 0xbfb8aa3b, v4
	v_mul_f32_e32 v1, 0xbfb8aa3b, v1
	v_and_b32_e32 v19, 0xffff0000, v83
	v_exp_f32_e32 v4, v4
	v_exp_f32_e32 v1, v1
	v_mul_f32_e32 v12, v12, v19
	v_mul_f32_e32 v12, v12, v13
	v_sub_f32_e32 v0, 1.0, v0
	v_cvt_pk_bf16_f32 v11, v11, v12
	v_sub_f32_e32 v12, 2.0, v0
	v_add_f32_e32 v4, 1.0, v4
	v_mul_f32_e32 v12, v0, v12
	v_add_f32_e32 v1, 1.0, v1
	v_rcp_f32_e32 v4, v4
	v_max_f32_e32 v12, 0, v12
	v_rcp_f32_e32 v1, v1
	v_sqrt_f32_e32 v12, v12
	global_store_dwordx4 v[80:81], v[8:11], off offset:64
	v_add_f32_e32 v2, v2, v70
	v_mul_f32_e32 v1, v1, v73
	v_lshlrev_b32_e32 v8, 16, v78
	v_mul_f32_e32 v4, v4, v8
	v_mul_f32_e32 v4, v4, v12
	v_mul_f32_e32 v1, 0x3fb8aa3b, v1
	v_cvt_pk_bf16_f32 v0, v0, v4
	v_add_f32_e32 v4, v5, v65
	v_exp_f32_e32 v1, v1
	v_mul_f32_e32 v4, 0xbfb8aa3b, v4
	v_mul_f32_e32 v2, 0xbfb8aa3b, v2
	v_exp_f32_e32 v4, v4
	v_exp_f32_e32 v2, v2
	v_sub_f32_e32 v1, 1.0, v1
	v_sub_f32_e32 v5, 2.0, v1
	v_add_f32_e32 v4, 1.0, v4
	v_mul_f32_e32 v5, v1, v5
	v_add_f32_e32 v2, 1.0, v2
	v_rcp_f32_e32 v4, v4
	v_max_f32_e32 v5, 0, v5
	v_rcp_f32_e32 v2, v2
	v_sqrt_f32_e32 v5, v5
	v_and_b32_e32 v9, 0xffff0000, v78
	v_mul_f32_e32 v4, v4, v9
	v_mul_f32_e32 v2, v2, v74
	v_mul_f32_e32 v4, v4, v5
	v_mul_f32_e32 v2, 0x3fb8aa3b, v2
	v_cvt_pk_bf16_f32 v1, v1, v4
	v_add_f32_e32 v4, v6, v66
	v_exp_f32_e32 v2, v2
	v_add_f32_e32 v3, v3, v71
	v_mul_f32_e32 v4, 0xbfb8aa3b, v4
	v_mul_f32_e32 v3, 0xbfb8aa3b, v3
	v_exp_f32_e32 v4, v4
	v_exp_f32_e32 v3, v3
	v_sub_f32_e32 v2, 1.0, v2
	v_sub_f32_e32 v5, 2.0, v2
	v_add_f32_e32 v4, 1.0, v4
	v_mul_f32_e32 v5, v2, v5
	v_add_f32_e32 v3, 1.0, v3
	v_rcp_f32_e32 v4, v4
	v_max_f32_e32 v5, 0, v5
	v_rcp_f32_e32 v3, v3
	v_sqrt_f32_e32 v5, v5
	v_lshlrev_b32_e32 v10, 16, v79
	v_mul_f32_e32 v4, v4, v10
	v_mul_f32_e32 v3, v3, v75
	v_mul_f32_e32 v4, v4, v5
	v_mul_f32_e32 v3, 0x3fb8aa3b, v3
	v_cvt_pk_bf16_f32 v2, v2, v4
	v_add_f32_e32 v4, v7, v67
	v_exp_f32_e32 v3, v3
	v_mul_f32_e32 v4, 0xbfb8aa3b, v4
	v_exp_f32_e32 v4, v4
	v_and_b32_e32 v11, 0xffff0000, v79
	v_sub_f32_e32 v3, 1.0, v3
	v_sub_f32_e32 v5, 2.0, v3
	v_add_f32_e32 v4, 1.0, v4
	v_mul_f32_e32 v5, v3, v5
	v_rcp_f32_e32 v4, v4
	v_max_f32_e32 v5, 0, v5
	v_sqrt_f32_e32 v5, v5
	s_andn2_b64 vcc, exec, s[4:5]
	v_mul_f32_e32 v4, v4, v11
	v_mul_f32_e32 v4, v4, v5
	v_cvt_pk_bf16_f32 v3, v3, v4
	global_store_dwordx4 v[76:77], v[0:3], off offset:64
	s_cbranch_vccz .LBB0_946
